# 8-phase GEMM K-loops: per-phase counted vmcnt(10) waits (each LDS-DMA stage waited one phase before its first reader: 5 phases of flight instead of 3)
# baseline (speedup 1.0000x reference)
; #define LDA8(dst, b, h) _Pragma("unroll") for (int m = 0; m < 4; ++m) _Pragma("unroll") for (int k = 0; k < 2; ++k) \
;     dst[m][k] = *(const bf16x8*)((const char*)SA8(b, h) + lds_byte8(wr * 64 + m * 16 + fr, k * 32 + fq * 8))
; #define LDB8(dst, b, h) _Pragma("unroll") for (int n = 0; n < 2; ++n) _Pragma("unroll") for (int k = 0; k < 2; ++k) \
;     dst[n][k] = *(const bf16x8*)((const char*)SB8(b, h) + lds_byte8(wc * 32 + n * 16 + fr, k * 32 + fq * 8))
; #define WAIT_L8(n) asm volatile("s_waitcnt lgkmcnt(" #n ")" ::: "memory")
; #define BAR8 __builtin_amdgcn_s_barrier()
; #define SCHED8 __builtin_amdgcn_sched_barrier(0)
;     ...
;     LDB8(B0, 0, 0); SCHED8; LDA8(At, 0, 0); STAGE8(SA8(1, 1), A, lda, brow + 128, tt + 1);
;     WAIT_L8(8); BAR8; WAIT_L8(0); MMA8(0, 0, At, B0); BAR8; SCHED8;
;     LDB8(B1, 0, 1); STAGE8(SB8(0, 0), Bt, K, bcol, tt + 2);
;     BAR8; WAIT_L8(0); MMA8(0, 1, At, B1); BAR8;
;     LDA8(At, 0, 1); STAGE8(SA8(0, 0), A, lda, brow, tt + 2);
;     BAR8; WAIT_L8(0); MMA8(1, 0, At, B0); BAR8; SCHED8;
.LBB0_192:
	ds_read_b128 v[174:177], v173
	ds_read_b128 v[178:181], v173 offset:1024
	ds_read_b128 v[182:185], v173 offset:2048
	ds_read_b128 v[186:189], v173 offset:3072
	v_lshl_add_u64 v[222:223], v[140:141], 0, s[12:13]
	v_readfirstlane_b32 s15, v172
	v_lshl_add_u64 v[226:227], v[222:223], 0, s[34:35]
	s_mov_b32 m0, s15
	ds_read_b128 v[190:193], v156
	ds_read_b128 v[194:197], v156 offset:1024
	ds_read_b128 v[198:201], v154
	ds_read_b128 v[202:205], v154 offset:1024
	ds_read_b128 v[206:209], v153
	ds_read_b128 v[210:213], v153 offset:1024
	ds_read_b128 v[214:217], v152
	ds_read_b128 v[218:221], v152 offset:1024
	global_load_lds_dwordx4 v[226:227], off
	v_lshl_add_u64 v[226:227], v[138:139], 0, s[12:13]
	v_readfirstlane_b32 s15, v171
	v_lshl_add_u64 v[228:229], v[226:227], 0, s[34:35]
	s_mov_b32 m0, s15
	s_nop 0
	global_load_lds_dwordx4 v[228:229], off
	s_waitcnt lgkmcnt(8)
	s_waitcnt vmcnt(10)
	s_barrier
	s_waitcnt lgkmcnt(0)
	s_setprio 1
	s_waitcnt lgkmcnt(0)
	v_mfma_f32_16x16x32_f16 v[128:131], v[190:193], v[174:177], v[128:131]
	v_mfma_f32_16x16x32_f16 v[124:127], v[190:193], v[182:185], v[124:127]
	v_mfma_f32_16x16x32_f16 v[120:123], v[198:201], v[174:177], v[120:123]
	v_mfma_f32_16x16x32_f16 v[116:119], v[198:201], v[182:185], v[116:119]
	v_mfma_f32_16x16x32_f16 v[112:115], v[206:209], v[174:177], v[112:115]
	v_mfma_f32_16x16x32_f16 v[108:111], v[206:209], v[182:185], v[108:111]
	v_mfma_f32_16x16x32_f16 v[104:107], v[214:217], v[174:177], v[104:107]
	v_mfma_f32_16x16x32_f16 v[100:103], v[214:217], v[182:185], v[100:103]
	v_mfma_f32_16x16x32_f16 v[128:131], v[194:197], v[178:181], v[128:131]
	v_mfma_f32_16x16x32_f16 v[124:127], v[194:197], v[186:189], v[124:127]
	v_mfma_f32_16x16x32_f16 v[120:123], v[202:205], v[178:181], v[120:123]
	v_mfma_f32_16x16x32_f16 v[116:119], v[202:205], v[186:189], v[116:119]
	v_mfma_f32_16x16x32_f16 v[112:115], v[210:213], v[178:181], v[112:115]
	v_mfma_f32_16x16x32_f16 v[108:111], v[210:213], v[186:189], v[108:111]
	v_mfma_f32_16x16x32_f16 v[104:107], v[218:221], v[178:181], v[104:107]
	v_mfma_f32_16x16x32_f16 v[100:103], v[218:221], v[186:189], v[100:103]
	s_setprio 0
	s_barrier
	v_lshl_add_u64 v[228:229], v[142:143], 0, s[12:13]
	v_readfirstlane_b32 s15, v151
	v_lshl_add_u64 v[236:237], v[228:229], 0, s[60:61]
	s_mov_b32 m0, s15
	ds_read_b128 v[238:241], v169
	ds_read_b128 v[242:245], v169 offset:1024
	ds_read_b128 v[246:249], v169 offset:2048
	ds_read_b128 v[230:233], v169 offset:3072
	global_load_lds_dwordx4 v[236:237], off
	v_lshl_add_u64 v[236:237], v[144:145], 0, s[12:13]
	v_readfirstlane_b32 s15, v157
	v_lshl_add_u64 v[250:251], v[236:237], 0, s[60:61]
	s_mov_b32 m0, s15
	s_nop 0
	global_load_lds_dwordx4 v[250:251], off
	s_waitcnt vmcnt(10)
	s_barrier
	s_waitcnt lgkmcnt(0)
	s_setprio 1
	s_waitcnt lgkmcnt(0)
	v_mfma_f32_16x16x32_f16 v[96:99], v[190:193], v[238:241], v[96:99]
	v_mfma_f32_16x16x32_f16 v[92:95], v[190:193], v[246:249], v[92:95]
	v_mfma_f32_16x16x32_f16 v[88:91], v[198:201], v[238:241], v[88:91]
	v_mfma_f32_16x16x32_f16 v[84:87], v[198:201], v[246:249], v[84:87]
	v_mfma_f32_16x16x32_f16 v[80:83], v[206:209], v[238:241], v[80:83]
	v_mfma_f32_16x16x32_f16 v[76:79], v[206:209], v[246:249], v[76:79]
	v_mfma_f32_16x16x32_f16 v[72:75], v[214:217], v[238:241], v[72:75]
	v_mfma_f32_16x16x32_f16 v[68:71], v[214:217], v[246:249], v[68:71]
	v_mfma_f32_16x16x32_f16 v[96:99], v[194:197], v[242:245], v[96:99]
	v_mfma_f32_16x16x32_f16 v[92:95], v[194:197], v[230:233], v[92:95]
	v_mfma_f32_16x16x32_f16 v[88:91], v[202:205], v[242:245], v[88:91]
	v_mfma_f32_16x16x32_f16 v[84:87], v[202:205], v[230:233], v[84:87]
	v_mfma_f32_16x16x32_f16 v[80:83], v[210:213], v[242:245], v[80:83]
	v_mfma_f32_16x16x32_f16 v[76:79], v[210:213], v[230:233], v[76:79]
	v_mfma_f32_16x16x32_f16 v[72:75], v[218:221], v[242:245], v[72:75]
	v_mfma_f32_16x16x32_f16 v[68:71], v[218:221], v[230:233], v[68:71]
	s_setprio 0
	v_readfirstlane_b32 s15, v150
	v_lshl_add_u64 v[250:251], v[222:223], 0, s[10:11]
	s_mov_b32 m0, s15
	v_readfirstlane_b32 s15, v155
	s_barrier
	ds_read_b128 v[190:193], v156 offset:16384
	ds_read_b128 v[194:197], v156 offset:17408
	ds_read_b128 v[198:201], v154 offset:16384
	ds_read_b128 v[202:205], v154 offset:17408
	ds_read_b128 v[206:209], v153 offset:16384
	ds_read_b128 v[210:213], v153 offset:17408
	ds_read_b128 v[214:217], v152 offset:16384
	ds_read_b128 v[218:221], v152 offset:17408
	global_load_lds_dwordx4 v[250:251], off
	v_lshl_add_u64 v[250:251], v[226:227], 0, s[10:11]
	s_mov_b32 m0, s15
	s_nop 0
	global_load_lds_dwordx4 v[250:251], off
	s_barrier
	s_waitcnt lgkmcnt(0)
	s_setprio 1
	s_waitcnt lgkmcnt(0)
	v_mfma_f32_16x16x32_f16 v[64:67], v[190:193], v[174:177], v[64:67]
	v_mfma_f32_16x16x32_f16 v[60:63], v[190:193], v[182:185], v[60:63]
	v_mfma_f32_16x16x32_f16 v[56:59], v[198:201], v[174:177], v[56:59]
	v_mfma_f32_16x16x32_f16 v[52:55], v[198:201], v[182:185], v[52:55]
	v_mfma_f32_16x16x32_f16 v[48:51], v[206:209], v[174:177], v[48:51]
	v_mfma_f32_16x16x32_f16 v[44:47], v[206:209], v[182:185], v[44:47]
	v_mfma_f32_16x16x32_f16 v[40:43], v[214:217], v[174:177], v[40:43]
	v_mfma_f32_16x16x32_f16 v[36:39], v[214:217], v[182:185], v[36:39]
	v_mfma_f32_16x16x32_f16 v[64:67], v[194:197], v[178:181], v[64:67]
	v_mfma_f32_16x16x32_f16 v[60:63], v[194:197], v[186:189], v[60:63]
	v_mfma_f32_16x16x32_f16 v[56:59], v[202:205], v[178:181], v[56:59]
	v_mfma_f32_16x16x32_f16 v[52:55], v[202:205], v[186:189], v[52:55]
	v_mfma_f32_16x16x32_f16 v[48:51], v[210:213], v[178:181], v[48:51]
	v_mfma_f32_16x16x32_f16 v[44:47], v[210:213], v[186:189], v[44:47]
	v_mfma_f32_16x16x32_f16 v[40:43], v[218:221], v[178:181], v[40:43]
	v_mfma_f32_16x16x32_f16 v[36:39], v[218:221], v[186:189], v[36:39]
	s_setprio 0
	s_barrier
; #define LDA8(dst, b, h) _Pragma("unroll") for (int m = 0; m < 4; ++m) _Pragma("unroll") for (int k = 0; k < 2; ++k) \
;     dst[m][k] = *(const bf16x8*)((const char*)SA8(b, h) + lds_byte8(wr * 64 + m * 16 + fr, k * 32 + fq * 8))
; #define LDB8(dst, b, h) _Pragma("unroll") for (int n = 0; n < 2; ++n) _Pragma("unroll") for (int k = 0; k < 2; ++k) \
;     dst[n][k] = *(const bf16x8*)((const char*)SB8(b, h) + lds_byte8(wc * 32 + n * 16 + fr, k * 32 + fq * 8))
; #define WAIT_V8(n) asm volatile("s_waitcnt vmcnt(" #n ")" ::: "memory")
; #define WAIT_L8(n) asm volatile("s_waitcnt lgkmcnt(" #n ")" ::: "memory")
; #define BAR8 __builtin_amdgcn_s_barrier()
; #define SCHED8 __builtin_amdgcn_sched_barrier(0)
;     ...
;     STAGE8(SB8(0, 1), Bt, K, bcol + 128, tt + 2);
;     WAIT_V8(6); BAR8; MMA8(1, 1, At, B1); BAR8;
;     LDB8(B0, 1, 0); SCHED8; LDA8(At, 1, 0); STAGE8(SA8(0, 1), A, lda, brow + 128, tt + 2);
;     WAIT_L8(8); BAR8; WAIT_L8(0); MMA8(0, 0, At, B0); BAR8; SCHED8;
;     LDB8(B1, 1, 1); STAGE8(SB8(1, 0), Bt, K, bcol, tt + 3);
;     BAR8; WAIT_L8(0); MMA8(0, 1, At, B1); BAR8;
;     LDA8(At, 1, 1); STAGE8(SA8(1, 0), A, lda, brow, tt + 3);
;     BAR8; WAIT_L8(0); MMA8(1, 0, At, B0); BAR8; SCHED8;
	v_readfirstlane_b32 s15, v160
	v_lshl_add_u64 v[174:175], v[228:229], 0, s[62:63]
	s_mov_b32 m0, s15
	v_readfirstlane_b32 s15, v161
	global_load_lds_dwordx4 v[174:175], off
	v_lshl_add_u64 v[174:175], v[236:237], 0, s[62:63]
	s_mov_b32 m0, s15
	s_nop 0
	global_load_lds_dwordx4 v[174:175], off
	s_waitcnt vmcnt(10)
	s_barrier
	s_setprio 1
	v_mfma_f32_16x16x32_f16 v[32:35], v[190:193], v[238:241], v[32:35]
	v_mfma_f32_16x16x32_f16 v[28:31], v[190:193], v[246:249], v[28:31]
	v_mfma_f32_16x16x32_f16 v[24:27], v[198:201], v[238:241], v[24:27]
	v_mfma_f32_16x16x32_f16 v[20:23], v[198:201], v[246:249], v[20:23]
	v_mfma_f32_16x16x32_f16 v[16:19], v[206:209], v[238:241], v[16:19]
	v_mfma_f32_16x16x32_f16 v[12:15], v[206:209], v[246:249], v[12:15]
	v_mfma_f32_16x16x32_f16 v[8:11], v[214:217], v[238:241], v[8:11]
	v_mfma_f32_16x16x32_f16 v[4:7], v[214:217], v[246:249], v[4:7]
	v_mfma_f32_16x16x32_f16 v[32:35], v[194:197], v[242:245], v[32:35]
	v_mfma_f32_16x16x32_f16 v[28:31], v[194:197], v[230:233], v[28:31]
	v_mfma_f32_16x16x32_f16 v[24:27], v[202:205], v[242:245], v[24:27]
	v_mfma_f32_16x16x32_f16 v[20:23], v[202:205], v[230:233], v[20:23]
	v_mfma_f32_16x16x32_f16 v[16:19], v[210:213], v[242:245], v[16:19]
	v_mfma_f32_16x16x32_f16 v[12:15], v[210:213], v[230:233], v[12:15]
	v_mfma_f32_16x16x32_f16 v[8:11], v[218:221], v[242:245], v[8:11]
	v_mfma_f32_16x16x32_f16 v[4:7], v[218:221], v[230:233], v[4:7]
	s_setprio 0
	s_barrier
	ds_read_b128 v[174:177], v159
	ds_read_b128 v[178:181], v159 offset:1024
	ds_read_b128 v[182:185], v159 offset:2048
	ds_read_b128 v[186:189], v159 offset:3072
	v_readfirstlane_b32 s15, v162
	v_lshl_add_u64 v[230:231], v[222:223], 0, s[18:19]
	s_mov_b32 m0, s15
	v_readfirstlane_b32 s15, v163
	ds_read_b128 v[190:193], v156 offset:32768
	ds_read_b128 v[194:197], v156 offset:33792
	ds_read_b128 v[198:201], v154 offset:32768
	ds_read_b128 v[202:205], v154 offset:33792
	ds_read_b128 v[206:209], v153 offset:32768
	ds_read_b128 v[210:213], v153 offset:33792
	ds_read_b128 v[214:217], v152 offset:32768
	ds_read_b128 v[218:221], v152 offset:33792
	global_load_lds_dwordx4 v[230:231], off
	v_lshl_add_u64 v[230:231], v[226:227], 0, s[18:19]
	s_mov_b32 m0, s15
	s_nop 0
	global_load_lds_dwordx4 v[230:231], off
	s_waitcnt lgkmcnt(8)
	s_waitcnt vmcnt(10)
	s_barrier
	s_waitcnt lgkmcnt(0)
	s_setprio 1
	s_waitcnt lgkmcnt(0)
	v_mfma_f32_16x16x32_f16 v[128:131], v[190:193], v[174:177], v[128:131]
	v_mfma_f32_16x16x32_f16 v[124:127], v[190:193], v[182:185], v[124:127]
	v_mfma_f32_16x16x32_f16 v[120:123], v[198:201], v[174:177], v[120:123]
	v_mfma_f32_16x16x32_f16 v[116:119], v[198:201], v[182:185], v[116:119]
	v_mfma_f32_16x16x32_f16 v[112:115], v[206:209], v[174:177], v[112:115]
	v_mfma_f32_16x16x32_f16 v[108:111], v[206:209], v[182:185], v[108:111]
	v_mfma_f32_16x16x32_f16 v[104:107], v[214:217], v[174:177], v[104:107]
	v_mfma_f32_16x16x32_f16 v[100:103], v[214:217], v[182:185], v[100:103]
	v_mfma_f32_16x16x32_f16 v[128:131], v[194:197], v[178:181], v[128:131]
	v_mfma_f32_16x16x32_f16 v[124:127], v[194:197], v[186:189], v[124:127]
	v_mfma_f32_16x16x32_f16 v[120:123], v[202:205], v[178:181], v[120:123]
	v_mfma_f32_16x16x32_f16 v[116:119], v[202:205], v[186:189], v[116:119]
	v_mfma_f32_16x16x32_f16 v[112:115], v[210:213], v[178:181], v[112:115]
	v_mfma_f32_16x16x32_f16 v[108:111], v[210:213], v[186:189], v[108:111]
	v_mfma_f32_16x16x32_f16 v[104:107], v[218:221], v[178:181], v[104:107]
	v_mfma_f32_16x16x32_f16 v[100:103], v[218:221], v[186:189], v[100:103]
	s_setprio 0
	s_barrier
	v_readfirstlane_b32 s15, v164
	v_lshl_add_u64 v[250:251], v[228:229], 0, s[64:65]
	s_mov_b32 m0, s15
	v_readfirstlane_b32 s15, v165
	ds_read_b128 v[230:233], v158
	ds_read_b128 v[238:241], v158 offset:1024
	ds_read_b128 v[242:245], v158 offset:2048
	ds_read_b128 v[246:249], v158 offset:3072
	global_load_lds_dwordx4 v[250:251], off
	v_lshl_add_u64 v[250:251], v[236:237], 0, s[64:65]
	s_mov_b32 m0, s15
	s_nop 0
	global_load_lds_dwordx4 v[250:251], off
	s_waitcnt vmcnt(10)
	s_barrier
	s_waitcnt lgkmcnt(0)
	s_setprio 1
	s_waitcnt lgkmcnt(0)
	v_mfma_f32_16x16x32_f16 v[96:99], v[190:193], v[230:233], v[96:99]
	v_mfma_f32_16x16x32_f16 v[92:95], v[190:193], v[242:245], v[92:95]
	v_mfma_f32_16x16x32_f16 v[88:91], v[198:201], v[230:233], v[88:91]
	v_mfma_f32_16x16x32_f16 v[84:87], v[198:201], v[242:245], v[84:87]
	v_mfma_f32_16x16x32_f16 v[80:83], v[206:209], v[230:233], v[80:83]
	v_mfma_f32_16x16x32_f16 v[76:79], v[206:209], v[242:245], v[76:79]
	v_mfma_f32_16x16x32_f16 v[72:75], v[214:217], v[230:233], v[72:75]
	v_mfma_f32_16x16x32_f16 v[68:71], v[214:217], v[242:245], v[68:71]
	v_mfma_f32_16x16x32_f16 v[96:99], v[194:197], v[238:241], v[96:99]
	v_mfma_f32_16x16x32_f16 v[92:95], v[194:197], v[246:249], v[92:95]
	v_mfma_f32_16x16x32_f16 v[88:91], v[202:205], v[238:241], v[88:91]
	v_mfma_f32_16x16x32_f16 v[84:87], v[202:205], v[246:249], v[84:87]
	v_mfma_f32_16x16x32_f16 v[80:83], v[210:213], v[238:241], v[80:83]
	v_mfma_f32_16x16x32_f16 v[76:79], v[210:213], v[246:249], v[76:79]
	v_mfma_f32_16x16x32_f16 v[72:75], v[218:221], v[238:241], v[72:75]
	v_mfma_f32_16x16x32_f16 v[68:71], v[218:221], v[246:249], v[68:71]
	s_setprio 0
	v_readfirstlane_b32 s15, v166
	v_lshl_add_u64 v[222:223], v[222:223], 0, s[22:23]
	s_mov_b32 m0, s15
	v_readfirstlane_b32 s15, v167
	s_barrier
	ds_read_b128 v[190:193], v156 offset:49152
	ds_read_b128 v[194:197], v156 offset:50176
	ds_read_b128 v[198:201], v154 offset:49152
	ds_read_b128 v[202:205], v154 offset:50176
	ds_read_b128 v[206:209], v153 offset:49152
	ds_read_b128 v[210:213], v153 offset:50176
	ds_read_b128 v[214:217], v152 offset:49152
	ds_read_b128 v[218:221], v152 offset:50176
	global_load_lds_dwordx4 v[222:223], off
	v_lshl_add_u64 v[222:223], v[226:227], 0, s[22:23]
	s_mov_b32 m0, s15
	s_nop 0
	global_load_lds_dwordx4 v[222:223], off
	s_barrier
; #define LDA8(dst, b, h) _Pragma("unroll") for (int m = 0; m < 4; ++m) _Pragma("unroll") for (int k = 0; k < 2; ++k) \
;     dst[m][k] = *(const bf16x8*)((const char*)SA8(b, h) + lds_byte8(wr * 64 + m * 16 + fr, k * 32 + fq * 8))
; #define LDB8(dst, b, h) _Pragma("unroll") for (int n = 0; n < 2; ++n) _Pragma("unroll") for (int k = 0; k < 2; ++k) \
;     dst[n][k] = *(const bf16x8*)((const char*)SB8(b, h) + lds_byte8(wc * 32 + n * 16 + fr, k * 32 + fq * 8))
; #define WAIT_V8(n) asm volatile("s_waitcnt vmcnt(" #n ")" ::: "memory")
; #define WAIT_L8(n) asm volatile("s_waitcnt lgkmcnt(" #n ")" ::: "memory")
; #define BAR8 __builtin_amdgcn_s_barrier()
; #define SCHED8 __builtin_amdgcn_sched_barrier(0)
;     ...
;     BAR8; WAIT_L8(0); MMA8(1, 0, At, B0); BAR8; SCHED8;
;     STAGE8(SB8(1, 1), Bt, K, bcol + 128, tt + 3);
;     WAIT_V8(6); BAR8; MMA8(1, 1, At, B1); BAR8;
;   }
;   { LDB8(B0, 0, 0); LDA8(At, 0, 0); STAGE8(SA8(1, 1), A, lda, brow + 128, nt - 1);
;     BAR8; WAIT_L8(0); MMA8(0, 0, At, B0); BAR8;
;     LDB8(B1, 0, 1); BAR8; WAIT_L8(0); MMA8(0, 1, At, B1); BAR8;
	s_waitcnt lgkmcnt(0)
	s_setprio 1
	s_waitcnt lgkmcnt(0)
	v_mfma_f32_16x16x32_f16 v[64:67], v[190:193], v[174:177], v[64:67]
	v_mfma_f32_16x16x32_f16 v[60:63], v[190:193], v[182:185], v[60:63]
	v_mfma_f32_16x16x32_f16 v[56:59], v[198:201], v[174:177], v[56:59]
	v_mfma_f32_16x16x32_f16 v[52:55], v[198:201], v[182:185], v[52:55]
	v_mfma_f32_16x16x32_f16 v[48:51], v[206:209], v[174:177], v[48:51]
	v_mfma_f32_16x16x32_f16 v[44:47], v[206:209], v[182:185], v[44:47]
	v_mfma_f32_16x16x32_f16 v[40:43], v[214:217], v[174:177], v[40:43]
	v_mfma_f32_16x16x32_f16 v[36:39], v[214:217], v[182:185], v[36:39]
	v_mfma_f32_16x16x32_f16 v[64:67], v[194:197], v[178:181], v[64:67]
	v_mfma_f32_16x16x32_f16 v[60:63], v[194:197], v[186:189], v[60:63]
	v_mfma_f32_16x16x32_f16 v[56:59], v[202:205], v[178:181], v[56:59]
	v_mfma_f32_16x16x32_f16 v[52:55], v[202:205], v[186:189], v[52:55]
	v_mfma_f32_16x16x32_f16 v[48:51], v[210:213], v[178:181], v[48:51]
	v_mfma_f32_16x16x32_f16 v[44:47], v[210:213], v[186:189], v[44:47]
	v_mfma_f32_16x16x32_f16 v[40:43], v[218:221], v[178:181], v[40:43]
	v_mfma_f32_16x16x32_f16 v[36:39], v[218:221], v[186:189], v[36:39]
	s_setprio 0
	s_barrier
	v_readfirstlane_b32 s15, v168
	v_lshl_add_u64 v[174:175], v[228:229], 0, s[66:67]
	s_mov_b32 m0, s15
	v_readfirstlane_b32 s15, v170
	global_load_lds_dwordx4 v[174:175], off
	v_lshl_add_u64 v[174:175], v[236:237], 0, s[66:67]
	s_mov_b32 m0, s15
	s_nop 0
	global_load_lds_dwordx4 v[174:175], off
	s_waitcnt vmcnt(10)
	s_barrier
	s_setprio 1
	v_mfma_f32_16x16x32_f16 v[32:35], v[190:193], v[230:233], v[32:35]
	v_mfma_f32_16x16x32_f16 v[28:31], v[190:193], v[242:245], v[28:31]
	v_mfma_f32_16x16x32_f16 v[24:27], v[198:201], v[230:233], v[24:27]
	v_mfma_f32_16x16x32_f16 v[20:23], v[198:201], v[242:245], v[20:23]
	v_mfma_f32_16x16x32_f16 v[16:19], v[206:209], v[230:233], v[16:19]
	v_mfma_f32_16x16x32_f16 v[12:15], v[206:209], v[242:245], v[12:15]
	v_mfma_f32_16x16x32_f16 v[8:11], v[214:217], v[230:233], v[8:11]
	v_mfma_f32_16x16x32_f16 v[4:7], v[214:217], v[242:245], v[4:7]
	v_mfma_f32_16x16x32_f16 v[32:35], v[194:197], v[238:241], v[32:35]
	v_mfma_f32_16x16x32_f16 v[28:31], v[194:197], v[246:249], v[28:31]
	v_mfma_f32_16x16x32_f16 v[24:27], v[202:205], v[238:241], v[24:27]
	v_mfma_f32_16x16x32_f16 v[20:23], v[202:205], v[246:249], v[20:23]
	v_mfma_f32_16x16x32_f16 v[16:19], v[210:213], v[238:241], v[16:19]
	v_mfma_f32_16x16x32_f16 v[12:15], v[210:213], v[246:249], v[12:15]
	v_mfma_f32_16x16x32_f16 v[8:11], v[218:221], v[238:241], v[8:11]
	v_mfma_f32_16x16x32_f16 v[4:7], v[218:221], v[246:249], v[4:7]
	s_setprio 0
	s_add_i32 s14, s14, 2
	s_add_u32 s12, s12, 0x100
	s_addc_u32 s13, s13, 0
	s_cmp_lt_u32 s14, 12
	s_barrier
	s_cbranch_scc1 .LBB0_192
	s_add_u32 s4, s4, 0x40780
	s_addc_u32 s5, s5, 0
	v_lshl_add_u64 v[132:133], s[4:5], 0, v[132:133]
	v_readfirstlane_b32 s12, v172
	v_lshl_add_u64 v[0:1], v[0:1], 1, v[132:133]
	s_mov_b32 m0, s12
	ds_read_b128 v[138:141], v173
	ds_read_b128 v[142:145], v173 offset:1024
	ds_read_b128 v[160:163], v173 offset:2048
	ds_read_b128 v[164:167], v173 offset:3072
	ds_read_b128 v[174:177], v156
	ds_read_b128 v[178:181], v156 offset:1024
	ds_read_b128 v[182:185], v154
	ds_read_b128 v[186:189], v154 offset:1024
	ds_read_b128 v[190:193], v153
	ds_read_b128 v[194:197], v153 offset:1024
	ds_read_b128 v[198:201], v152
	ds_read_b128 v[202:205], v152 offset:1024
	global_load_lds_dwordx4 v[0:1], off
	v_lshl_add_u64 v[0:1], s[4:5], 0, v[136:137]
	v_readfirstlane_b32 s4, v171
	v_lshl_add_u64 v[0:1], v[134:135], 1, v[0:1]
	s_mov_b32 m0, s4
	s_nop 0
	global_load_lds_dwordx4 v[0:1], off
	s_waitcnt vmcnt(10)
	s_barrier
	s_waitcnt lgkmcnt(0)
	s_setprio 1
	s_waitcnt lgkmcnt(0)
	v_mfma_f32_16x16x32_f16 v[128:131], v[174:177], v[138:141], v[128:131]
	v_mfma_f32_16x16x32_f16 v[124:127], v[174:177], v[160:163], v[124:127]
	v_mfma_f32_16x16x32_f16 v[120:123], v[182:185], v[138:141], v[120:123]
	v_mfma_f32_16x16x32_f16 v[112:115], v[190:193], v[138:141], v[112:115]
	v_mfma_f32_16x16x32_f16 v[128:131], v[178:181], v[142:145], v[128:131]
	v_mfma_f32_16x16x32_f16 v[124:127], v[178:181], v[164:167], v[124:127]
	v_mfma_f32_16x16x32_f16 v[120:123], v[186:189], v[142:145], v[120:123]
	v_mfma_f32_16x16x32_f16 v[116:119], v[182:185], v[160:163], v[116:119]
	v_mfma_f32_16x16x32_f16 v[112:115], v[194:197], v[142:145], v[112:115]
	v_mfma_f32_16x16x32_f16 v[108:111], v[190:193], v[160:163], v[108:111]
	v_mfma_f32_16x16x32_f16 v[104:107], v[198:201], v[138:141], v[104:107]
	v_mfma_f32_16x16x32_f16 v[100:103], v[198:201], v[160:163], v[100:103]
	v_mfma_f32_16x16x32_f16 v[132:135], v[186:189], v[164:167], v[116:119]
	v_mfma_f32_16x16x32_f16 v[170:173], v[194:197], v[164:167], v[108:111]
	v_mfma_f32_16x16x32_f16 v[206:209], v[202:205], v[142:145], v[104:107]
	v_mfma_f32_16x16x32_f16 v[210:213], v[202:205], v[164:167], v[100:103]
	s_setprio 0
	s_barrier
	s_nop 1
	ds_read_b128 v[100:103], v169
	ds_read_b128 v[104:107], v169 offset:1024
	ds_read_b128 v[108:111], v169 offset:2048
	ds_read_b128 v[116:119], v169 offset:3072
	s_waitcnt vmcnt(8)
	s_barrier
; #define LDA8(dst, b, h) _Pragma("unroll") for (int m = 0; m < 4; ++m) _Pragma("unroll") for (int k = 0; k < 2; ++k) \
;     dst[m][k] = *(const bf16x8*)((const char*)SA8(b, h) + lds_byte8(wr * 64 + m * 16 + fr, k * 32 + fq * 8))
; #define LDB8(dst, b, h) _Pragma("unroll") for (int n = 0; n < 2; ++n) _Pragma("unroll") for (int k = 0; k < 2; ++k) \
;     dst[n][k] = *(const bf16x8*)((const char*)SB8(b, h) + lds_byte8(wc * 32 + n * 16 + fr, k * 32 + fq * 8))
; #define WAIT_V8(n) asm volatile("s_waitcnt vmcnt(" #n ")" ::: "memory")
; #define WAIT_L8(n) asm volatile("s_waitcnt lgkmcnt(" #n ")" ::: "memory")
; #define BAR8 __builtin_amdgcn_s_barrier()
;     ...
;     LDB8(B1, 0, 1); BAR8; WAIT_L8(0); MMA8(0, 1, At, B1); BAR8;
;     LDA8(At, 0, 1); WAIT_V8(4); BAR8; WAIT_L8(0); MMA8(1, 0, At, B0); MMA8(1, 1, At, B1); BAR8; }
;   { LDB8(B0, 1, 0); LDA8(At, 1, 0); WAIT_V8(2); BAR8; WAIT_L8(0); MMA8(0, 0, At, B0); BAR8;
	s_waitcnt lgkmcnt(0)
	s_setprio 1
	s_waitcnt lgkmcnt(0)
	v_mfma_f32_16x16x32_f16 v[80:83], v[190:193], v[100:103], v[80:83]
	v_mfma_f32_16x16x32_f16 v[76:79], v[190:193], v[108:111], v[76:79]
	v_mfma_f32_16x16x32_f16 v[72:75], v[198:201], v[100:103], v[72:75]
	v_mfma_f32_16x16x32_f16 v[68:71], v[198:201], v[108:111], v[68:71]
	v_mfma_f32_16x16x32_f16 v[96:99], v[174:177], v[100:103], v[96:99]
	v_mfma_f32_16x16x32_f16 v[92:95], v[174:177], v[108:111], v[92:95]
	v_mfma_f32_16x16x32_f16 v[88:91], v[182:185], v[100:103], v[88:91]
	v_mfma_f32_16x16x32_f16 v[84:87], v[182:185], v[108:111], v[84:87]
	v_mfma_f32_16x16x32_f16 v[80:83], v[194:197], v[104:107], v[80:83]
	v_mfma_f32_16x16x32_f16 v[76:79], v[194:197], v[116:119], v[76:79]
	v_mfma_f32_16x16x32_f16 v[72:75], v[202:205], v[104:107], v[72:75]
	v_mfma_f32_16x16x32_f16 v[68:71], v[202:205], v[116:119], v[68:71]
	v_mfma_f32_16x16x32_f16 v[214:217], v[178:181], v[104:107], v[96:99]
	v_mfma_f32_16x16x32_f16 v[174:177], v[178:181], v[116:119], v[92:95]
	v_mfma_f32_16x16x32_f16 v[178:181], v[186:189], v[104:107], v[88:91]
	v_mfma_f32_16x16x32_f16 v[182:185], v[186:189], v[116:119], v[84:87]
	s_setprio 0
	s_barrier
	s_nop 0
	ds_read_b128 v[84:87], v156 offset:16384
	ds_read_b128 v[88:91], v156 offset:17408
	ds_read_b128 v[92:95], v154 offset:16384
	ds_read_b128 v[96:99], v154 offset:17408
	ds_read_b128 v[186:189], v153 offset:16384
	ds_read_b128 v[190:193], v153 offset:17408
	ds_read_b128 v[194:197], v152 offset:16384
	ds_read_b128 v[198:201], v152 offset:17408
	s_waitcnt vmcnt(4)
	s_barrier
	s_waitcnt lgkmcnt(0)
	s_setprio 1
	s_waitcnt lgkmcnt(0)
	v_mfma_f32_16x16x32_f16 v[64:67], v[84:87], v[138:141], v[64:67]
	v_mfma_f32_16x16x32_f16 v[60:63], v[84:87], v[160:163], v[60:63]
	v_mfma_f32_16x16x32_f16 v[56:59], v[92:95], v[138:141], v[56:59]
	v_mfma_f32_16x16x32_f16 v[52:55], v[92:95], v[160:163], v[52:55]
	v_mfma_f32_16x16x32_f16 v[48:51], v[186:189], v[138:141], v[48:51]
	v_mfma_f32_16x16x32_f16 v[44:47], v[186:189], v[160:163], v[44:47]
	v_mfma_f32_16x16x32_f16 v[64:67], v[88:91], v[142:145], v[64:67]
	v_mfma_f32_16x16x32_f16 v[60:63], v[88:91], v[164:167], v[60:63]
	v_mfma_f32_16x16x32_f16 v[56:59], v[96:99], v[142:145], v[56:59]
	v_mfma_f32_16x16x32_f16 v[52:55], v[96:99], v[164:167], v[52:55]
	v_mfma_f32_16x16x32_f16 v[48:51], v[190:193], v[142:145], v[48:51]
	v_mfma_f32_16x16x32_f16 v[44:47], v[190:193], v[164:167], v[44:47]
	v_mfma_f32_16x16x32_f16 v[40:43], v[194:197], v[138:141], v[40:43]
	v_mfma_f32_16x16x32_f16 v[36:39], v[194:197], v[160:163], v[36:39]
	v_mfma_f32_16x16x32_f16 v[136:139], v[198:201], v[142:145], v[40:43]
	v_mfma_f32_16x16x32_f16 v[140:143], v[198:201], v[164:167], v[36:39]
	s_setprio 0
	s_setprio 1
	v_mfma_f32_16x16x32_f16 v[32:35], v[84:87], v[100:103], v[32:35]
	v_mfma_f32_16x16x32_f16 v[28:31], v[84:87], v[108:111], v[28:31]
	v_mfma_f32_16x16x32_f16 v[24:27], v[92:95], v[100:103], v[24:27]
	v_mfma_f32_16x16x32_f16 v[20:23], v[92:95], v[108:111], v[20:23]
	v_mfma_f32_16x16x32_f16 v[16:19], v[186:189], v[100:103], v[16:19]
	v_mfma_f32_16x16x32_f16 v[12:15], v[186:189], v[108:111], v[12:15]
	v_mfma_f32_16x16x32_f16 v[8:11], v[194:197], v[100:103], v[8:11]
	v_mfma_f32_16x16x32_f16 v[4:7], v[194:197], v[108:111], v[4:7]
	v_mfma_f32_16x16x32_f16 v[160:163], v[88:91], v[104:107], v[32:35]
	v_mfma_f32_16x16x32_f16 v[164:167], v[88:91], v[116:119], v[28:31]
	v_mfma_f32_16x16x32_f16 v[202:205], v[96:99], v[104:107], v[24:27]
	v_mfma_f32_16x16x32_f16 v[218:221], v[96:99], v[116:119], v[20:23]
	v_mfma_f32_16x16x32_f16 v[230:233], v[190:193], v[104:107], v[16:19]
	v_mfma_f32_16x16x32_f16 v[186:189], v[190:193], v[116:119], v[12:15]
	v_mfma_f32_16x16x32_f16 v[190:193], v[198:201], v[104:107], v[8:11]
	v_mfma_f32_16x16x32_f16 v[194:197], v[198:201], v[116:119], v[4:7]
	s_setprio 0
	s_barrier
	s_nop 0
	ds_read_b128 v[4:7], v159
	ds_read_b128 v[8:11], v159 offset:1024
	ds_read_b128 v[198:201], v159 offset:2048
	ds_read_b128 v[238:241], v159 offset:3072
	ds_read_b128 v[16:19], v156 offset:32768
	ds_read_b128 v[20:23], v156 offset:33792
	ds_read_b128 v[24:27], v154 offset:32768
	ds_read_b128 v[32:35], v154 offset:33792
	ds_read_b128 v[36:39], v153 offset:32768
	ds_read_b128 v[40:43], v153 offset:33792
	ds_read_b128 v[242:245], v152 offset:32768
	ds_read_b128 v[246:249], v152 offset:33792
	s_waitcnt vmcnt(2)
	s_barrier
; #define LDA8(dst, b, h) _Pragma("unroll") for (int m = 0; m < 4; ++m) _Pragma("unroll") for (int k = 0; k < 2; ++k) \
;     dst[m][k] = *(const bf16x8*)((const char*)SA8(b, h) + lds_byte8(wr * 64 + m * 16 + fr, k * 32 + fq * 8))
; #define LDB8(dst, b, h) _Pragma("unroll") for (int n = 0; n < 2; ++n) _Pragma("unroll") for (int k = 0; k < 2; ++k) \
;     dst[n][k] = *(const bf16x8*)((const char*)SB8(b, h) + lds_byte8(wc * 32 + n * 16 + fr, k * 32 + fq * 8))
; #define WAIT_V8(n) asm volatile("s_waitcnt vmcnt(" #n ")" ::: "memory")
; #define WAIT_L8(n) asm volatile("s_waitcnt lgkmcnt(" #n ")" ::: "memory")
; #define BAR8 __builtin_amdgcn_s_barrier()
;     ...
;   { LDB8(B0, 1, 0); LDA8(At, 1, 0); WAIT_V8(2); BAR8; WAIT_L8(0); MMA8(0, 0, At, B0); BAR8;
;     LDB8(B1, 1, 1); WAIT_V8(0); BAR8; WAIT_L8(0); MMA8(0, 1, At, B1); BAR8;
;     LDA8(At, 1, 1); BAR8; WAIT_L8(0); MMA8(1, 0, At, B0); MMA8(1, 1, At, B1); BAR8; }
;   if (wr == 0) BAR8;
	s_waitcnt lgkmcnt(0)
	s_setprio 1
	s_waitcnt lgkmcnt(0)
	v_mfma_f32_16x16x32_f16 v[12:15], v[16:19], v[4:7], v[128:131]
	v_mfma_f32_16x16x32_f16 v[104:107], v[20:23], v[8:11], v[12:15]
	v_mfma_f32_16x16x32_f16 v[12:15], v[16:19], v[198:201], v[124:127]
	v_mfma_f32_16x16x32_f16 v[116:119], v[20:23], v[238:241], v[12:15]
	v_mfma_f32_16x16x32_f16 v[12:15], v[24:27], v[4:7], v[120:123]
	v_mfma_f32_16x16x32_f16 v[100:103], v[32:35], v[8:11], v[12:15]
	v_mfma_f32_16x16x32_f16 v[12:15], v[24:27], v[198:201], v[132:135]
	v_mfma_f32_16x16x32_f16 v[108:111], v[32:35], v[238:241], v[12:15]
	v_mfma_f32_16x16x32_f16 v[12:15], v[36:39], v[4:7], v[112:115]
	v_mfma_f32_16x16x32_f16 v[92:95], v[40:43], v[8:11], v[12:15]
	v_mfma_f32_16x16x32_f16 v[12:15], v[36:39], v[198:201], v[170:173]
	v_mfma_f32_16x16x32_f16 v[96:99], v[40:43], v[238:241], v[12:15]
	v_mfma_f32_16x16x32_f16 v[12:15], v[242:245], v[4:7], v[206:209]
	v_mfma_f32_16x16x32_f16 v[84:87], v[246:249], v[8:11], v[12:15]
	v_mfma_f32_16x16x32_f16 v[12:15], v[242:245], v[198:201], v[210:213]
	v_mfma_f32_16x16x32_f16 v[88:91], v[246:249], v[238:241], v[12:15]
	s_setprio 0
	s_barrier
	ds_read_b128 v[132:135], v158
	ds_read_b128 v[168:171], v158 offset:1024
	ds_read_b128 v[206:209], v158 offset:2048
	ds_read_b128 v[210:213], v158 offset:3072
	s_waitcnt vmcnt(0)
	s_barrier
	s_waitcnt lgkmcnt(0)
	s_setprio 1
	s_waitcnt lgkmcnt(0)
	v_mfma_f32_16x16x32_f16 v[12:15], v[16:19], v[132:135], v[214:217]
	v_mfma_f32_16x16x32_f16 v[16:19], v[16:19], v[206:209], v[174:177]
	v_mfma_f32_16x16x32_f16 v[12:15], v[20:23], v[168:171], v[12:15]
	v_mfma_f32_16x16x32_f16 v[28:31], v[20:23], v[210:213], v[16:19]
	v_mfma_f32_16x16x32_f16 v[16:19], v[24:27], v[132:135], v[178:181]
	v_mfma_f32_16x16x32_f16 v[20:23], v[24:27], v[206:209], v[182:185]
	v_mfma_f32_16x16x32_f16 v[16:19], v[32:35], v[168:171], v[16:19]
	v_mfma_f32_16x16x32_f16 v[32:35], v[32:35], v[210:213], v[20:23]
	v_mfma_f32_16x16x32_f16 v[20:23], v[36:39], v[132:135], v[80:83]
	v_mfma_f32_16x16x32_f16 v[24:27], v[36:39], v[206:209], v[76:79]
	v_mfma_f32_16x16x32_f16 v[20:23], v[40:43], v[168:171], v[20:23]
	v_mfma_f32_16x16x32_f16 v[36:39], v[40:43], v[210:213], v[24:27]
	v_mfma_f32_16x16x32_f16 v[24:27], v[242:245], v[132:135], v[72:75]
	v_mfma_f32_16x16x32_f16 v[40:43], v[242:245], v[206:209], v[68:71]
	v_mfma_f32_16x16x32_f16 v[24:27], v[246:249], v[168:171], v[24:27]
	v_mfma_f32_16x16x32_f16 v[40:43], v[246:249], v[210:213], v[40:43]
	s_setprio 0
	s_barrier
	ds_read_b128 v[68:71], v156 offset:49152
	ds_read_b128 v[72:75], v156 offset:50176
	ds_read_b128 v[156:159], v154 offset:49152
	ds_read_b128 v[172:175], v154 offset:50176
	ds_read_b128 v[176:179], v153 offset:49152
	ds_read_b128 v[180:183], v153 offset:50176
	ds_read_b128 v[214:217], v152 offset:49152
	ds_read_b128 v[150:153], v152 offset:50176
	s_barrier
	s_waitcnt lgkmcnt(0)
	s_setprio 1
	s_waitcnt lgkmcnt(0)
	v_mfma_f32_16x16x32_f16 v[64:67], v[68:71], v[4:7], v[64:67]
	v_mfma_f32_16x16x32_f16 v[56:59], v[156:159], v[4:7], v[56:59]
	v_mfma_f32_16x16x32_f16 v[48:51], v[176:179], v[4:7], v[48:51]
	v_mfma_f32_16x16x32_f16 v[4:7], v[214:217], v[4:7], v[136:139]
	v_mfma_f32_16x16x32_f16 v[128:131], v[72:75], v[8:11], v[64:67]
	v_mfma_f32_16x16x32_f16 v[60:63], v[68:71], v[198:201], v[60:63]
	v_mfma_f32_16x16x32_f16 v[120:123], v[172:175], v[8:11], v[56:59]
	v_mfma_f32_16x16x32_f16 v[52:55], v[156:159], v[198:201], v[52:55]
	v_mfma_f32_16x16x32_f16 v[80:83], v[180:183], v[8:11], v[48:51]
	v_mfma_f32_16x16x32_f16 v[44:47], v[176:179], v[198:201], v[44:47]
	v_mfma_f32_16x16x32_f16 v[8:11], v[150:153], v[8:11], v[4:7]
	v_mfma_f32_16x16x32_f16 v[4:7], v[214:217], v[198:201], v[140:143]
	v_mfma_f32_16x16x32_f16 v[124:127], v[72:75], v[238:241], v[60:63]
	v_mfma_f32_16x16x32_f16 v[112:115], v[172:175], v[238:241], v[52:55]
	v_mfma_f32_16x16x32_f16 v[76:79], v[180:183], v[238:241], v[44:47]
	v_mfma_f32_16x16x32_f16 v[4:7], v[150:153], v[238:241], v[4:7]
	s_setprio 0
	s_setprio 1
	v_mfma_f32_16x16x32_f16 v[44:47], v[68:71], v[132:135], v[160:163]
	v_mfma_f32_16x16x32_f16 v[48:51], v[68:71], v[206:209], v[164:167]
	v_mfma_f32_16x16x32_f16 v[52:55], v[156:159], v[206:209], v[218:221]
	v_mfma_f32_16x16x32_f16 v[56:59], v[176:179], v[206:209], v[186:189]
	v_mfma_f32_16x16x32_f16 v[44:47], v[72:75], v[168:171], v[44:47]
	v_mfma_f32_16x16x32_f16 v[60:63], v[72:75], v[210:213], v[48:51]
	v_mfma_f32_16x16x32_f16 v[48:51], v[156:159], v[132:135], v[202:205]
	v_mfma_f32_16x16x32_f16 v[64:67], v[172:175], v[210:213], v[52:55]
	v_mfma_f32_16x16x32_f16 v[52:55], v[176:179], v[132:135], v[230:233]
	v_mfma_f32_16x16x32_f16 v[68:71], v[180:183], v[210:213], v[56:59]
	v_mfma_f32_16x16x32_f16 v[56:59], v[214:217], v[132:135], v[190:193]
	v_mfma_f32_16x16x32_f16 v[72:75], v[214:217], v[206:209], v[194:197]
	v_mfma_f32_16x16x32_f16 v[48:51], v[172:175], v[168:171], v[48:51]
	v_mfma_f32_16x16x32_f16 v[52:55], v[180:183], v[168:171], v[52:55]
	v_mfma_f32_16x16x32_f16 v[56:59], v[150:153], v[168:171], v[56:59]
	v_mfma_f32_16x16x32_f16 v[72:75], v[150:153], v[210:213], v[72:75]
	s_setprio 0
	s_movk_i32 s4, 0x100
	v_cmp_gt_u32_e32 vcc, s4, v3
	s_barrier
	s_and_saveexec_b64 s[4:5], vcc
	s_cbranch_execz .LBB0_195
	s_barrier

; #define LDA8(dst, b, h) _Pragma("unroll") for (int m = 0; m < 4; ++m) _Pragma("unroll") for (int k = 0; k < 2; ++k) \
;     dst[m][k] = *(const bf16x8*)((const char*)SA8(b, h) + lds_byte8(wr * 64 + m * 16 + fr, k * 32 + fq * 8))
; #define LDB8(dst, b, h) _Pragma("unroll") for (int n = 0; n < 2; ++n) _Pragma("unroll") for (int k = 0; k < 2; ++k) \
;     dst[n][k] = *(const bf16x8*)((const char*)SB8(b, h) + lds_byte8(wc * 32 + n * 16 + fr, k * 32 + fq * 8))
; #define WAIT_L8(n) asm volatile("s_waitcnt lgkmcnt(" #n ")" ::: "memory")
; #define BAR8 __builtin_amdgcn_s_barrier()
; #define SCHED8 __builtin_amdgcn_sched_barrier(0)
;     ...
;     LDB8(B0, 0, 0); SCHED8; LDA8(At, 0, 0); STAGE8(SA8(1, 1), A, lda, brow + 128, tt + 1);
;     WAIT_L8(8); BAR8; WAIT_L8(0); MMA8(0, 0, At, B0); BAR8; SCHED8;
;     LDB8(B1, 0, 1); STAGE8(SB8(0, 0), Bt, K, bcol, tt + 2);
;     BAR8; WAIT_L8(0); MMA8(0, 1, At, B1); BAR8;
;     LDA8(At, 0, 1); STAGE8(SA8(0, 0), A, lda, brow, tt + 2);
;     BAR8; WAIT_L8(0); MMA8(1, 0, At, B0); BAR8; SCHED8;
.LBB0_242:
	ds_read_b128 v[174:177], v171
	ds_read_b128 v[178:181], v171 offset:1024
	ds_read_b128 v[182:185], v171 offset:2048
	ds_read_b128 v[186:189], v171 offset:3072
	v_add_u32_e32 v172, 0xc000, v150
	v_lshl_add_u64 v[222:223], v[140:141], 0, s[14:15]
	v_readfirstlane_b32 s20, v172
	v_lshl_add_u64 v[226:227], v[222:223], 0, s[34:35]
	s_mov_b32 m0, s20
	v_add_u32_e32 v173, 0xe000, v150
	ds_read_b128 v[190:193], v156
	ds_read_b128 v[194:197], v156 offset:1024
	ds_read_b128 v[198:201], v154
	ds_read_b128 v[202:205], v154 offset:1024
	ds_read_b128 v[206:209], v153
	ds_read_b128 v[210:213], v153 offset:1024
	ds_read_b128 v[214:217], v152
	ds_read_b128 v[218:221], v152 offset:1024
	global_load_lds_dwordx4 v[226:227], off
	v_lshl_add_u64 v[226:227], v[138:139], 0, s[14:15]
	v_readfirstlane_b32 s20, v173
	v_lshl_add_u64 v[228:229], v[226:227], 0, s[34:35]
	s_mov_b32 m0, s20
	s_nop 0
	global_load_lds_dwordx4 v[228:229], off
	s_waitcnt lgkmcnt(8)
	s_waitcnt vmcnt(10)
	s_barrier
	s_waitcnt lgkmcnt(0)
	s_setprio 1
	s_waitcnt lgkmcnt(0)
	v_mfma_f32_16x16x32_f16 v[128:131], v[190:193], v[174:177], v[128:131]
	v_mfma_f32_16x16x32_f16 v[124:127], v[190:193], v[182:185], v[124:127]
	v_mfma_f32_16x16x32_f16 v[120:123], v[198:201], v[174:177], v[120:123]
	v_mfma_f32_16x16x32_f16 v[116:119], v[198:201], v[182:185], v[116:119]
	v_mfma_f32_16x16x32_f16 v[112:115], v[206:209], v[174:177], v[112:115]
	v_mfma_f32_16x16x32_f16 v[108:111], v[206:209], v[182:185], v[108:111]
	v_mfma_f32_16x16x32_f16 v[104:107], v[214:217], v[174:177], v[104:107]
	v_mfma_f32_16x16x32_f16 v[100:103], v[214:217], v[182:185], v[100:103]
	v_mfma_f32_16x16x32_f16 v[128:131], v[194:197], v[178:181], v[128:131]
	v_mfma_f32_16x16x32_f16 v[124:127], v[194:197], v[186:189], v[124:127]
	v_mfma_f32_16x16x32_f16 v[120:123], v[202:205], v[178:181], v[120:123]
	v_mfma_f32_16x16x32_f16 v[116:119], v[202:205], v[186:189], v[116:119]
	v_mfma_f32_16x16x32_f16 v[112:115], v[210:213], v[178:181], v[112:115]
	v_mfma_f32_16x16x32_f16 v[108:111], v[210:213], v[186:189], v[108:111]
	v_mfma_f32_16x16x32_f16 v[104:107], v[218:221], v[178:181], v[104:107]
	v_mfma_f32_16x16x32_f16 v[100:103], v[218:221], v[186:189], v[100:103]
	s_setprio 0
	s_barrier
	v_lshl_add_u64 v[228:229], v[142:143], 0, s[14:15]
	v_readfirstlane_b32 s20, v151
	v_lshl_add_u64 v[236:237], v[228:229], 0, s[30:31]
	s_mov_b32 m0, s20
	ds_read_b128 v[230:233], v168
	ds_read_b128 v[238:241], v168 offset:1024
	ds_read_b128 v[242:245], v168 offset:2048
	ds_read_b128 v[246:249], v168 offset:3072
	global_load_lds_dwordx4 v[236:237], off
	v_lshl_add_u64 v[236:237], v[144:145], 0, s[14:15]
	v_readfirstlane_b32 s20, v158
	v_lshl_add_u64 v[250:251], v[236:237], 0, s[30:31]
	s_mov_b32 m0, s20
	s_nop 0
	global_load_lds_dwordx4 v[250:251], off
	s_waitcnt vmcnt(10)
	s_barrier
	s_waitcnt lgkmcnt(0)
	s_setprio 1
	s_waitcnt lgkmcnt(0)
	v_mfma_f32_16x16x32_f16 v[96:99], v[190:193], v[230:233], v[96:99]
	v_mfma_f32_16x16x32_f16 v[92:95], v[190:193], v[242:245], v[92:95]
	v_mfma_f32_16x16x32_f16 v[88:91], v[198:201], v[230:233], v[88:91]
	v_mfma_f32_16x16x32_f16 v[84:87], v[198:201], v[242:245], v[84:87]
	v_mfma_f32_16x16x32_f16 v[80:83], v[206:209], v[230:233], v[80:83]
	v_mfma_f32_16x16x32_f16 v[76:79], v[206:209], v[242:245], v[76:79]
	v_mfma_f32_16x16x32_f16 v[72:75], v[214:217], v[230:233], v[72:75]
	v_mfma_f32_16x16x32_f16 v[68:71], v[214:217], v[242:245], v[68:71]
	v_mfma_f32_16x16x32_f16 v[96:99], v[194:197], v[238:241], v[96:99]
	v_mfma_f32_16x16x32_f16 v[92:95], v[194:197], v[246:249], v[92:95]
	v_mfma_f32_16x16x32_f16 v[88:91], v[202:205], v[238:241], v[88:91]
	v_mfma_f32_16x16x32_f16 v[84:87], v[202:205], v[246:249], v[84:87]
	v_mfma_f32_16x16x32_f16 v[80:83], v[210:213], v[238:241], v[80:83]
	v_mfma_f32_16x16x32_f16 v[76:79], v[210:213], v[246:249], v[76:79]
	v_mfma_f32_16x16x32_f16 v[72:75], v[218:221], v[238:241], v[72:75]
	v_mfma_f32_16x16x32_f16 v[68:71], v[218:221], v[246:249], v[68:71]
	s_setprio 0
	v_readfirstlane_b32 s20, v150
	v_lshl_add_u64 v[250:251], v[222:223], 0, s[10:11]
	s_mov_b32 m0, s20
	v_readfirstlane_b32 s20, v155
	s_barrier
	ds_read_b128 v[190:193], v156 offset:16384
	ds_read_b128 v[194:197], v156 offset:17408
	ds_read_b128 v[198:201], v154 offset:16384
	ds_read_b128 v[202:205], v154 offset:17408
	ds_read_b128 v[206:209], v153 offset:16384
	ds_read_b128 v[210:213], v153 offset:17408
	ds_read_b128 v[214:217], v152 offset:16384
	ds_read_b128 v[218:221], v152 offset:17408
	global_load_lds_dwordx4 v[250:251], off
	v_lshl_add_u64 v[250:251], v[226:227], 0, s[10:11]
	s_mov_b32 m0, s20
	s_nop 0
	global_load_lds_dwordx4 v[250:251], off
	s_barrier
	s_waitcnt lgkmcnt(0)
	s_setprio 1
	s_waitcnt lgkmcnt(0)
	v_mfma_f32_16x16x32_f16 v[64:67], v[190:193], v[174:177], v[64:67]
	v_mfma_f32_16x16x32_f16 v[60:63], v[190:193], v[182:185], v[60:63]
	v_mfma_f32_16x16x32_f16 v[56:59], v[198:201], v[174:177], v[56:59]
	v_mfma_f32_16x16x32_f16 v[52:55], v[198:201], v[182:185], v[52:55]
	v_mfma_f32_16x16x32_f16 v[48:51], v[206:209], v[174:177], v[48:51]
	v_mfma_f32_16x16x32_f16 v[44:47], v[206:209], v[182:185], v[44:47]
	v_mfma_f32_16x16x32_f16 v[40:43], v[214:217], v[174:177], v[40:43]
	v_mfma_f32_16x16x32_f16 v[36:39], v[214:217], v[182:185], v[36:39]
	v_mfma_f32_16x16x32_f16 v[64:67], v[194:197], v[178:181], v[64:67]
	v_mfma_f32_16x16x32_f16 v[60:63], v[194:197], v[186:189], v[60:63]
	v_mfma_f32_16x16x32_f16 v[56:59], v[202:205], v[178:181], v[56:59]
	v_mfma_f32_16x16x32_f16 v[52:55], v[202:205], v[186:189], v[52:55]
	v_mfma_f32_16x16x32_f16 v[48:51], v[210:213], v[178:181], v[48:51]
	v_mfma_f32_16x16x32_f16 v[44:47], v[210:213], v[186:189], v[44:47]
	v_mfma_f32_16x16x32_f16 v[40:43], v[218:221], v[178:181], v[40:43]
	v_mfma_f32_16x16x32_f16 v[36:39], v[218:221], v[186:189], v[36:39]
	s_setprio 0
	s_barrier
; #define LDA8(dst, b, h) _Pragma("unroll") for (int m = 0; m < 4; ++m) _Pragma("unroll") for (int k = 0; k < 2; ++k) \
;     dst[m][k] = *(const bf16x8*)((const char*)SA8(b, h) + lds_byte8(wr * 64 + m * 16 + fr, k * 32 + fq * 8))
; #define LDB8(dst, b, h) _Pragma("unroll") for (int n = 0; n < 2; ++n) _Pragma("unroll") for (int k = 0; k < 2; ++k) \
;     dst[n][k] = *(const bf16x8*)((const char*)SB8(b, h) + lds_byte8(wc * 32 + n * 16 + fr, k * 32 + fq * 8))
; #define WAIT_V8(n) asm volatile("s_waitcnt vmcnt(" #n ")" ::: "memory")
; #define WAIT_L8(n) asm volatile("s_waitcnt lgkmcnt(" #n ")" ::: "memory")
; #define BAR8 __builtin_amdgcn_s_barrier()
; #define SCHED8 __builtin_amdgcn_sched_barrier(0)
;     ...
;     STAGE8(SB8(0, 1), Bt, K, bcol + 128, tt + 2);
;     WAIT_V8(6); BAR8; MMA8(1, 1, At, B1); BAR8;
;     LDB8(B0, 1, 0); SCHED8; LDA8(At, 1, 0); STAGE8(SA8(0, 1), A, lda, brow + 128, tt + 2);
;     WAIT_L8(8); BAR8; WAIT_L8(0); MMA8(0, 0, At, B0); BAR8; SCHED8;
;     LDB8(B1, 1, 1); STAGE8(SB8(1, 0), Bt, K, bcol, tt + 3);
;     BAR8; WAIT_L8(0); MMA8(0, 1, At, B1); BAR8;
;     LDA8(At, 1, 1); STAGE8(SA8(1, 0), A, lda, brow, tt + 3);
;     BAR8; WAIT_L8(0); MMA8(1, 0, At, B0); BAR8; SCHED8;
	v_readfirstlane_b32 s20, v160
	v_lshl_add_u64 v[174:175], v[228:229], 0, s[56:57]
	s_mov_b32 m0, s20
	v_readfirstlane_b32 s20, v161
	global_load_lds_dwordx4 v[174:175], off
	v_lshl_add_u64 v[174:175], v[236:237], 0, s[56:57]
	s_mov_b32 m0, s20
	s_nop 0
	global_load_lds_dwordx4 v[174:175], off
	s_waitcnt vmcnt(10)
	s_barrier
	s_setprio 1
	v_mfma_f32_16x16x32_f16 v[32:35], v[190:193], v[230:233], v[32:35]
	v_mfma_f32_16x16x32_f16 v[28:31], v[190:193], v[242:245], v[28:31]
	v_mfma_f32_16x16x32_f16 v[24:27], v[198:201], v[230:233], v[24:27]
	v_mfma_f32_16x16x32_f16 v[20:23], v[198:201], v[242:245], v[20:23]
	v_mfma_f32_16x16x32_f16 v[16:19], v[206:209], v[230:233], v[16:19]
	v_mfma_f32_16x16x32_f16 v[12:15], v[206:209], v[242:245], v[12:15]
	v_mfma_f32_16x16x32_f16 v[8:11], v[214:217], v[230:233], v[8:11]
	v_mfma_f32_16x16x32_f16 v[4:7], v[214:217], v[242:245], v[4:7]
	v_mfma_f32_16x16x32_f16 v[32:35], v[194:197], v[238:241], v[32:35]
	v_mfma_f32_16x16x32_f16 v[28:31], v[194:197], v[246:249], v[28:31]
	v_mfma_f32_16x16x32_f16 v[24:27], v[202:205], v[238:241], v[24:27]
	v_mfma_f32_16x16x32_f16 v[20:23], v[202:205], v[246:249], v[20:23]
	v_mfma_f32_16x16x32_f16 v[16:19], v[210:213], v[238:241], v[16:19]
	v_mfma_f32_16x16x32_f16 v[12:15], v[210:213], v[246:249], v[12:15]
	v_mfma_f32_16x16x32_f16 v[8:11], v[218:221], v[238:241], v[8:11]
	v_mfma_f32_16x16x32_f16 v[4:7], v[218:221], v[246:249], v[4:7]
	s_setprio 0
	s_barrier
	ds_read_b128 v[174:177], v159
	ds_read_b128 v[178:181], v159 offset:1024
	ds_read_b128 v[182:185], v159 offset:2048
	ds_read_b128 v[186:189], v159 offset:3072
	v_readfirstlane_b32 s20, v162
	v_lshl_add_u64 v[230:231], v[222:223], 0, s[18:19]
	s_mov_b32 m0, s20
	v_readfirstlane_b32 s20, v163
	ds_read_b128 v[190:193], v156 offset:32768
	ds_read_b128 v[194:197], v156 offset:33792
	ds_read_b128 v[198:201], v154 offset:32768
	ds_read_b128 v[202:205], v154 offset:33792
	ds_read_b128 v[206:209], v153 offset:32768
	ds_read_b128 v[210:213], v153 offset:33792
	ds_read_b128 v[214:217], v152 offset:32768
	ds_read_b128 v[218:221], v152 offset:33792
	global_load_lds_dwordx4 v[230:231], off
	v_lshl_add_u64 v[230:231], v[226:227], 0, s[18:19]
	s_mov_b32 m0, s20
	s_nop 0
	global_load_lds_dwordx4 v[230:231], off
	s_waitcnt lgkmcnt(8)
	s_waitcnt vmcnt(10)
	s_barrier
	s_waitcnt lgkmcnt(0)
	s_setprio 1
	s_waitcnt lgkmcnt(0)
	v_mfma_f32_16x16x32_f16 v[128:131], v[190:193], v[174:177], v[128:131]
	v_mfma_f32_16x16x32_f16 v[124:127], v[190:193], v[182:185], v[124:127]
	v_mfma_f32_16x16x32_f16 v[120:123], v[198:201], v[174:177], v[120:123]
	v_mfma_f32_16x16x32_f16 v[116:119], v[198:201], v[182:185], v[116:119]
	v_mfma_f32_16x16x32_f16 v[112:115], v[206:209], v[174:177], v[112:115]
	v_mfma_f32_16x16x32_f16 v[108:111], v[206:209], v[182:185], v[108:111]
	v_mfma_f32_16x16x32_f16 v[104:107], v[214:217], v[174:177], v[104:107]
	v_mfma_f32_16x16x32_f16 v[100:103], v[214:217], v[182:185], v[100:103]
	v_mfma_f32_16x16x32_f16 v[128:131], v[194:197], v[178:181], v[128:131]
	v_mfma_f32_16x16x32_f16 v[124:127], v[194:197], v[186:189], v[124:127]
	v_mfma_f32_16x16x32_f16 v[120:123], v[202:205], v[178:181], v[120:123]
	v_mfma_f32_16x16x32_f16 v[116:119], v[202:205], v[186:189], v[116:119]
	v_mfma_f32_16x16x32_f16 v[112:115], v[210:213], v[178:181], v[112:115]
	v_mfma_f32_16x16x32_f16 v[108:111], v[210:213], v[186:189], v[108:111]
	v_mfma_f32_16x16x32_f16 v[104:107], v[218:221], v[178:181], v[104:107]
	v_mfma_f32_16x16x32_f16 v[100:103], v[218:221], v[186:189], v[100:103]
	s_setprio 0
	s_barrier
	v_readfirstlane_b32 s20, v164
	v_lshl_add_u64 v[250:251], v[228:229], 0, s[58:59]
	s_mov_b32 m0, s20
	v_readfirstlane_b32 s20, v165
	ds_read_b128 v[230:233], v157
	ds_read_b128 v[238:241], v157 offset:1024
	ds_read_b128 v[242:245], v157 offset:2048
	ds_read_b128 v[246:249], v157 offset:3072
	global_load_lds_dwordx4 v[250:251], off
	v_lshl_add_u64 v[250:251], v[236:237], 0, s[58:59]
	s_mov_b32 m0, s20
	s_nop 0
	global_load_lds_dwordx4 v[250:251], off
	s_waitcnt vmcnt(10)
	s_barrier
	s_waitcnt lgkmcnt(0)
	s_setprio 1
	s_waitcnt lgkmcnt(0)
	v_mfma_f32_16x16x32_f16 v[96:99], v[190:193], v[230:233], v[96:99]
	v_mfma_f32_16x16x32_f16 v[92:95], v[190:193], v[242:245], v[92:95]
	v_mfma_f32_16x16x32_f16 v[88:91], v[198:201], v[230:233], v[88:91]
	v_mfma_f32_16x16x32_f16 v[84:87], v[198:201], v[242:245], v[84:87]
	v_mfma_f32_16x16x32_f16 v[80:83], v[206:209], v[230:233], v[80:83]
	v_mfma_f32_16x16x32_f16 v[76:79], v[206:209], v[242:245], v[76:79]
	v_mfma_f32_16x16x32_f16 v[72:75], v[214:217], v[230:233], v[72:75]
	v_mfma_f32_16x16x32_f16 v[68:71], v[214:217], v[242:245], v[68:71]
	v_mfma_f32_16x16x32_f16 v[96:99], v[194:197], v[238:241], v[96:99]
	v_mfma_f32_16x16x32_f16 v[92:95], v[194:197], v[246:249], v[92:95]
	v_mfma_f32_16x16x32_f16 v[88:91], v[202:205], v[238:241], v[88:91]
	v_mfma_f32_16x16x32_f16 v[84:87], v[202:205], v[246:249], v[84:87]
	v_mfma_f32_16x16x32_f16 v[80:83], v[210:213], v[238:241], v[80:83]
	v_mfma_f32_16x16x32_f16 v[76:79], v[210:213], v[246:249], v[76:79]
	v_mfma_f32_16x16x32_f16 v[72:75], v[218:221], v[238:241], v[72:75]
	v_mfma_f32_16x16x32_f16 v[68:71], v[218:221], v[246:249], v[68:71]
	s_setprio 0
	v_readfirstlane_b32 s20, v166
	v_lshl_add_u64 v[222:223], v[222:223], 0, s[22:23]
	s_mov_b32 m0, s20
	v_readfirstlane_b32 s20, v167
	s_barrier
	ds_read_b128 v[190:193], v156 offset:49152
	ds_read_b128 v[194:197], v156 offset:50176
	ds_read_b128 v[198:201], v154 offset:49152
	ds_read_b128 v[202:205], v154 offset:50176
	ds_read_b128 v[206:209], v153 offset:49152
	ds_read_b128 v[210:213], v153 offset:50176
	ds_read_b128 v[214:217], v152 offset:49152
	ds_read_b128 v[218:221], v152 offset:50176
	global_load_lds_dwordx4 v[222:223], off
	v_lshl_add_u64 v[222:223], v[226:227], 0, s[22:23]
	s_mov_b32 m0, s20
	s_nop 0
	global_load_lds_dwordx4 v[222:223], off
	s_barrier
; #define LDA8(dst, b, h) _Pragma("unroll") for (int m = 0; m < 4; ++m) _Pragma("unroll") for (int k = 0; k < 2; ++k) \
;     dst[m][k] = *(const bf16x8*)((const char*)SA8(b, h) + lds_byte8(wr * 64 + m * 16 + fr, k * 32 + fq * 8))
; #define LDB8(dst, b, h) _Pragma("unroll") for (int n = 0; n < 2; ++n) _Pragma("unroll") for (int k = 0; k < 2; ++k) \
;     dst[n][k] = *(const bf16x8*)((const char*)SB8(b, h) + lds_byte8(wc * 32 + n * 16 + fr, k * 32 + fq * 8))
; #define WAIT_V8(n) asm volatile("s_waitcnt vmcnt(" #n ")" ::: "memory")
; #define WAIT_L8(n) asm volatile("s_waitcnt lgkmcnt(" #n ")" ::: "memory")
; #define BAR8 __builtin_amdgcn_s_barrier()
; #define SCHED8 __builtin_amdgcn_sched_barrier(0)
;     ...
;     BAR8; WAIT_L8(0); MMA8(1, 0, At, B0); BAR8; SCHED8;
;     STAGE8(SB8(1, 1), Bt, K, bcol + 128, tt + 3);
;     WAIT_V8(6); BAR8; MMA8(1, 1, At, B1); BAR8;
;   }
;   { LDB8(B0, 0, 0); LDA8(At, 0, 0); STAGE8(SA8(1, 1), A, lda, brow + 128, nt - 1);
;     BAR8; WAIT_L8(0); MMA8(0, 0, At, B0); BAR8;
;     LDB8(B1, 0, 1); BAR8; WAIT_L8(0); MMA8(0, 1, At, B1); BAR8;
	s_waitcnt lgkmcnt(0)
	s_setprio 1
	s_waitcnt lgkmcnt(0)
	v_mfma_f32_16x16x32_f16 v[64:67], v[190:193], v[174:177], v[64:67]
	v_mfma_f32_16x16x32_f16 v[60:63], v[190:193], v[182:185], v[60:63]
	v_mfma_f32_16x16x32_f16 v[56:59], v[198:201], v[174:177], v[56:59]
	v_mfma_f32_16x16x32_f16 v[52:55], v[198:201], v[182:185], v[52:55]
	v_mfma_f32_16x16x32_f16 v[48:51], v[206:209], v[174:177], v[48:51]
	v_mfma_f32_16x16x32_f16 v[44:47], v[206:209], v[182:185], v[44:47]
	v_mfma_f32_16x16x32_f16 v[40:43], v[214:217], v[174:177], v[40:43]
	v_mfma_f32_16x16x32_f16 v[36:39], v[214:217], v[182:185], v[36:39]
	v_mfma_f32_16x16x32_f16 v[64:67], v[194:197], v[178:181], v[64:67]
	v_mfma_f32_16x16x32_f16 v[60:63], v[194:197], v[186:189], v[60:63]
	v_mfma_f32_16x16x32_f16 v[56:59], v[202:205], v[178:181], v[56:59]
	v_mfma_f32_16x16x32_f16 v[52:55], v[202:205], v[186:189], v[52:55]
	v_mfma_f32_16x16x32_f16 v[48:51], v[210:213], v[178:181], v[48:51]
	v_mfma_f32_16x16x32_f16 v[44:47], v[210:213], v[186:189], v[44:47]
	v_mfma_f32_16x16x32_f16 v[40:43], v[218:221], v[178:181], v[40:43]
	v_mfma_f32_16x16x32_f16 v[36:39], v[218:221], v[186:189], v[36:39]
	s_setprio 0
	s_barrier
	v_readfirstlane_b32 s20, v169
	v_lshl_add_u64 v[174:175], v[228:229], 0, s[60:61]
	s_mov_b32 m0, s20
	v_readfirstlane_b32 s20, v170
	global_load_lds_dwordx4 v[174:175], off
	v_lshl_add_u64 v[174:175], v[236:237], 0, s[60:61]
	s_mov_b32 m0, s20
	s_nop 0
	global_load_lds_dwordx4 v[174:175], off
	s_waitcnt vmcnt(10)
	s_barrier
	s_setprio 1
	v_mfma_f32_16x16x32_f16 v[32:35], v[190:193], v[230:233], v[32:35]
	v_mfma_f32_16x16x32_f16 v[28:31], v[190:193], v[242:245], v[28:31]
	v_mfma_f32_16x16x32_f16 v[24:27], v[198:201], v[230:233], v[24:27]
	v_mfma_f32_16x16x32_f16 v[20:23], v[198:201], v[242:245], v[20:23]
	v_mfma_f32_16x16x32_f16 v[16:19], v[206:209], v[230:233], v[16:19]
	v_mfma_f32_16x16x32_f16 v[12:15], v[206:209], v[242:245], v[12:15]
	v_mfma_f32_16x16x32_f16 v[8:11], v[214:217], v[230:233], v[8:11]
	v_mfma_f32_16x16x32_f16 v[4:7], v[214:217], v[242:245], v[4:7]
	v_mfma_f32_16x16x32_f16 v[32:35], v[194:197], v[238:241], v[32:35]
	v_mfma_f32_16x16x32_f16 v[28:31], v[194:197], v[246:249], v[28:31]
	v_mfma_f32_16x16x32_f16 v[24:27], v[202:205], v[238:241], v[24:27]
	v_mfma_f32_16x16x32_f16 v[20:23], v[202:205], v[246:249], v[20:23]
	v_mfma_f32_16x16x32_f16 v[16:19], v[210:213], v[238:241], v[16:19]
	v_mfma_f32_16x16x32_f16 v[12:15], v[210:213], v[246:249], v[12:15]
	v_mfma_f32_16x16x32_f16 v[8:11], v[218:221], v[238:241], v[8:11]
	v_mfma_f32_16x16x32_f16 v[4:7], v[218:221], v[246:249], v[4:7]
	s_setprio 0
	s_add_i32 s1, s1, 2
	s_add_u32 s14, s14, 0x100
	s_addc_u32 s15, s15, 0
	s_cmp_lt_u32 s1, 12
	s_barrier
	s_cbranch_scc1 .LBB0_242
	s_add_u32 s12, s12, 0x40780
	s_addc_u32 s13, s13, 0
	v_lshl_add_u64 v[132:133], s[12:13], 0, v[132:133]
	v_readfirstlane_b32 s1, v172
	v_lshl_add_u64 v[0:1], v[0:1], 1, v[132:133]
	s_mov_b32 m0, s1
	ds_read_b128 v[138:141], v171
	ds_read_b128 v[142:145], v171 offset:1024
	ds_read_b128 v[160:163], v171 offset:2048
	ds_read_b128 v[164:167], v171 offset:3072
	ds_read_b128 v[174:177], v156
	ds_read_b128 v[178:181], v156 offset:1024
	ds_read_b128 v[182:185], v154
	ds_read_b128 v[186:189], v154 offset:1024
	ds_read_b128 v[190:193], v153
	ds_read_b128 v[194:197], v153 offset:1024
	ds_read_b128 v[198:201], v152
	ds_read_b128 v[202:205], v152 offset:1024
	global_load_lds_dwordx4 v[0:1], off
	v_lshl_add_u64 v[0:1], s[12:13], 0, v[136:137]
	v_readfirstlane_b32 s1, v173
	v_lshl_add_u64 v[0:1], v[134:135], 1, v[0:1]
	s_mov_b32 m0, s1
	s_nop 0
	global_load_lds_dwordx4 v[0:1], off
	s_waitcnt vmcnt(10)
	s_barrier
	s_waitcnt lgkmcnt(0)
	s_setprio 1
	s_waitcnt lgkmcnt(0)
	v_mfma_f32_16x16x32_f16 v[128:131], v[174:177], v[138:141], v[128:131]
	v_mfma_f32_16x16x32_f16 v[124:127], v[174:177], v[160:163], v[124:127]
	v_mfma_f32_16x16x32_f16 v[120:123], v[182:185], v[138:141], v[120:123]
	v_mfma_f32_16x16x32_f16 v[112:115], v[190:193], v[138:141], v[112:115]
	v_mfma_f32_16x16x32_f16 v[128:131], v[178:181], v[142:145], v[128:131]
	v_mfma_f32_16x16x32_f16 v[124:127], v[178:181], v[164:167], v[124:127]
	v_mfma_f32_16x16x32_f16 v[120:123], v[186:189], v[142:145], v[120:123]
	v_mfma_f32_16x16x32_f16 v[116:119], v[182:185], v[160:163], v[116:119]
	v_mfma_f32_16x16x32_f16 v[112:115], v[194:197], v[142:145], v[112:115]
	v_mfma_f32_16x16x32_f16 v[108:111], v[190:193], v[160:163], v[108:111]
	v_mfma_f32_16x16x32_f16 v[104:107], v[198:201], v[138:141], v[104:107]
	v_mfma_f32_16x16x32_f16 v[100:103], v[198:201], v[160:163], v[100:103]
	v_mfma_f32_16x16x32_f16 v[132:135], v[186:189], v[164:167], v[116:119]
	v_mfma_f32_16x16x32_f16 v[170:173], v[194:197], v[164:167], v[108:111]
	v_mfma_f32_16x16x32_f16 v[206:209], v[202:205], v[142:145], v[104:107]
	v_mfma_f32_16x16x32_f16 v[210:213], v[202:205], v[164:167], v[100:103]
	s_setprio 0
	s_barrier
	s_nop 1
	ds_read_b128 v[100:103], v168
	ds_read_b128 v[104:107], v168 offset:1024
	ds_read_b128 v[108:111], v168 offset:2048
	ds_read_b128 v[116:119], v168 offset:3072
	s_waitcnt vmcnt(8)
	s_barrier
; #define LDA8(dst, b, h) _Pragma("unroll") for (int m = 0; m < 4; ++m) _Pragma("unroll") for (int k = 0; k < 2; ++k) \
;     dst[m][k] = *(const bf16x8*)((const char*)SA8(b, h) + lds_byte8(wr * 64 + m * 16 + fr, k * 32 + fq * 8))
; #define LDB8(dst, b, h) _Pragma("unroll") for (int n = 0; n < 2; ++n) _Pragma("unroll") for (int k = 0; k < 2; ++k) \
;     dst[n][k] = *(const bf16x8*)((const char*)SB8(b, h) + lds_byte8(wc * 32 + n * 16 + fr, k * 32 + fq * 8))
; #define WAIT_V8(n) asm volatile("s_waitcnt vmcnt(" #n ")" ::: "memory")
; #define WAIT_L8(n) asm volatile("s_waitcnt lgkmcnt(" #n ")" ::: "memory")
; #define BAR8 __builtin_amdgcn_s_barrier()
;     ...
;     LDB8(B1, 0, 1); BAR8; WAIT_L8(0); MMA8(0, 1, At, B1); BAR8;
;     LDA8(At, 0, 1); WAIT_V8(4); BAR8; WAIT_L8(0); MMA8(1, 0, At, B0); MMA8(1, 1, At, B1); BAR8; }
;   { LDB8(B0, 1, 0); LDA8(At, 1, 0); WAIT_V8(2); BAR8; WAIT_L8(0); MMA8(0, 0, At, B0); BAR8;
	s_waitcnt lgkmcnt(0)
	s_setprio 1
	s_waitcnt lgkmcnt(0)
	v_mfma_f32_16x16x32_f16 v[80:83], v[190:193], v[100:103], v[80:83]
	v_mfma_f32_16x16x32_f16 v[76:79], v[190:193], v[108:111], v[76:79]
	v_mfma_f32_16x16x32_f16 v[72:75], v[198:201], v[100:103], v[72:75]
	v_mfma_f32_16x16x32_f16 v[68:71], v[198:201], v[108:111], v[68:71]
	v_mfma_f32_16x16x32_f16 v[96:99], v[174:177], v[100:103], v[96:99]
	v_mfma_f32_16x16x32_f16 v[92:95], v[174:177], v[108:111], v[92:95]
	v_mfma_f32_16x16x32_f16 v[88:91], v[182:185], v[100:103], v[88:91]
	v_mfma_f32_16x16x32_f16 v[84:87], v[182:185], v[108:111], v[84:87]
	v_mfma_f32_16x16x32_f16 v[80:83], v[194:197], v[104:107], v[80:83]
	v_mfma_f32_16x16x32_f16 v[76:79], v[194:197], v[116:119], v[76:79]
	v_mfma_f32_16x16x32_f16 v[72:75], v[202:205], v[104:107], v[72:75]
	v_mfma_f32_16x16x32_f16 v[68:71], v[202:205], v[116:119], v[68:71]
	v_mfma_f32_16x16x32_f16 v[214:217], v[178:181], v[104:107], v[96:99]
	v_mfma_f32_16x16x32_f16 v[174:177], v[178:181], v[116:119], v[92:95]
	v_mfma_f32_16x16x32_f16 v[178:181], v[186:189], v[104:107], v[88:91]
	v_mfma_f32_16x16x32_f16 v[182:185], v[186:189], v[116:119], v[84:87]
	s_setprio 0
	s_barrier
	s_nop 0
	ds_read_b128 v[84:87], v156 offset:16384
	ds_read_b128 v[88:91], v156 offset:17408
	ds_read_b128 v[92:95], v154 offset:16384
	ds_read_b128 v[96:99], v154 offset:17408
	ds_read_b128 v[186:189], v153 offset:16384
	ds_read_b128 v[190:193], v153 offset:17408
	ds_read_b128 v[194:197], v152 offset:16384
	ds_read_b128 v[198:201], v152 offset:17408
	s_waitcnt vmcnt(4)
	s_barrier
	s_waitcnt lgkmcnt(0)
	s_setprio 1
	s_waitcnt lgkmcnt(0)
	v_mfma_f32_16x16x32_f16 v[64:67], v[84:87], v[138:141], v[64:67]
	v_mfma_f32_16x16x32_f16 v[60:63], v[84:87], v[160:163], v[60:63]
	v_mfma_f32_16x16x32_f16 v[56:59], v[92:95], v[138:141], v[56:59]
	v_mfma_f32_16x16x32_f16 v[52:55], v[92:95], v[160:163], v[52:55]
	v_mfma_f32_16x16x32_f16 v[48:51], v[186:189], v[138:141], v[48:51]
	v_mfma_f32_16x16x32_f16 v[44:47], v[186:189], v[160:163], v[44:47]
	v_mfma_f32_16x16x32_f16 v[40:43], v[194:197], v[138:141], v[40:43]
	v_mfma_f32_16x16x32_f16 v[36:39], v[194:197], v[160:163], v[36:39]
	v_mfma_f32_16x16x32_f16 v[64:67], v[88:91], v[142:145], v[64:67]
	v_mfma_f32_16x16x32_f16 v[60:63], v[88:91], v[164:167], v[60:63]
	v_mfma_f32_16x16x32_f16 v[56:59], v[96:99], v[142:145], v[56:59]
	v_mfma_f32_16x16x32_f16 v[52:55], v[96:99], v[164:167], v[52:55]
	v_mfma_f32_16x16x32_f16 v[48:51], v[190:193], v[142:145], v[48:51]
	v_mfma_f32_16x16x32_f16 v[44:47], v[190:193], v[164:167], v[44:47]
	v_mfma_f32_16x16x32_f16 v[40:43], v[198:201], v[142:145], v[40:43]
	v_mfma_f32_16x16x32_f16 v[36:39], v[198:201], v[164:167], v[36:39]
	s_setprio 0
	s_setprio 1
	v_mfma_f32_16x16x32_f16 v[32:35], v[84:87], v[100:103], v[32:35]
	v_mfma_f32_16x16x32_f16 v[28:31], v[84:87], v[108:111], v[28:31]
	v_mfma_f32_16x16x32_f16 v[24:27], v[92:95], v[100:103], v[24:27]
	v_mfma_f32_16x16x32_f16 v[20:23], v[92:95], v[108:111], v[20:23]
	v_mfma_f32_16x16x32_f16 v[16:19], v[186:189], v[100:103], v[16:19]
	v_mfma_f32_16x16x32_f16 v[12:15], v[186:189], v[108:111], v[12:15]
	v_mfma_f32_16x16x32_f16 v[8:11], v[194:197], v[100:103], v[8:11]
	v_mfma_f32_16x16x32_f16 v[4:7], v[194:197], v[108:111], v[4:7]
	v_mfma_f32_16x16x32_f16 v[136:139], v[88:91], v[104:107], v[32:35]
	v_mfma_f32_16x16x32_f16 v[140:143], v[88:91], v[116:119], v[28:31]
	v_mfma_f32_16x16x32_f16 v[160:163], v[96:99], v[104:107], v[24:27]
	v_mfma_f32_16x16x32_f16 v[164:167], v[96:99], v[116:119], v[20:23]
	v_mfma_f32_16x16x32_f16 v[202:205], v[190:193], v[104:107], v[16:19]
	v_mfma_f32_16x16x32_f16 v[186:189], v[190:193], v[116:119], v[12:15]
	v_mfma_f32_16x16x32_f16 v[190:193], v[198:201], v[104:107], v[8:11]
	v_mfma_f32_16x16x32_f16 v[194:197], v[198:201], v[116:119], v[4:7]
	s_setprio 0
	s_barrier
	ds_read_b128 v[198:201], v159
	ds_read_b128 v[218:221], v159 offset:1024
	ds_read_b128 v[230:233], v159 offset:2048
	ds_read_b128 v[238:241], v159 offset:3072
	ds_read_b128 v[8:11], v156 offset:32768
	ds_read_b128 v[12:15], v156 offset:33792
	ds_read_b128 v[16:19], v154 offset:32768
	ds_read_b128 v[24:27], v154 offset:33792
	ds_read_b128 v[28:31], v153 offset:32768
	ds_read_b128 v[32:35], v153 offset:33792
	ds_read_b128 v[242:245], v152 offset:32768
	ds_read_b128 v[246:249], v152 offset:33792
	s_waitcnt vmcnt(2)
	s_barrier
; #define LDA8(dst, b, h) _Pragma("unroll") for (int m = 0; m < 4; ++m) _Pragma("unroll") for (int k = 0; k < 2; ++k) \
;     dst[m][k] = *(const bf16x8*)((const char*)SA8(b, h) + lds_byte8(wr * 64 + m * 16 + fr, k * 32 + fq * 8))
; #define LDB8(dst, b, h) _Pragma("unroll") for (int n = 0; n < 2; ++n) _Pragma("unroll") for (int k = 0; k < 2; ++k) \
;     dst[n][k] = *(const bf16x8*)((const char*)SB8(b, h) + lds_byte8(wc * 32 + n * 16 + fr, k * 32 + fq * 8))
; #define WAIT_V8(n) asm volatile("s_waitcnt vmcnt(" #n ")" ::: "memory")
; #define WAIT_L8(n) asm volatile("s_waitcnt lgkmcnt(" #n ")" ::: "memory")
; #define BAR8 __builtin_amdgcn_s_barrier()
;     ...
;   { LDB8(B0, 1, 0); LDA8(At, 1, 0); WAIT_V8(2); BAR8; WAIT_L8(0); MMA8(0, 0, At, B0); BAR8;
;     LDB8(B1, 1, 1); WAIT_V8(0); BAR8; WAIT_L8(0); MMA8(0, 1, At, B1); BAR8;
;     LDA8(At, 1, 1); BAR8; WAIT_L8(0); MMA8(1, 0, At, B0); MMA8(1, 1, At, B1); BAR8; }
;   if (wr == 0) BAR8;
	s_waitcnt lgkmcnt(0)
	s_setprio 1
	s_waitcnt lgkmcnt(0)
	v_mfma_f32_16x16x32_f16 v[4:7], v[8:11], v[198:201], v[128:131]
	v_mfma_f32_16x16x32_f16 v[104:107], v[12:15], v[218:221], v[4:7]
	v_mfma_f32_16x16x32_f16 v[4:7], v[8:11], v[230:233], v[124:127]
	v_mfma_f32_16x16x32_f16 v[116:119], v[12:15], v[238:241], v[4:7]
	v_mfma_f32_16x16x32_f16 v[4:7], v[16:19], v[198:201], v[120:123]
	v_mfma_f32_16x16x32_f16 v[100:103], v[24:27], v[218:221], v[4:7]
	v_mfma_f32_16x16x32_f16 v[4:7], v[16:19], v[230:233], v[132:135]
	v_mfma_f32_16x16x32_f16 v[108:111], v[24:27], v[238:241], v[4:7]
	v_mfma_f32_16x16x32_f16 v[4:7], v[28:31], v[198:201], v[112:115]
	v_mfma_f32_16x16x32_f16 v[92:95], v[32:35], v[218:221], v[4:7]
	v_mfma_f32_16x16x32_f16 v[4:7], v[28:31], v[230:233], v[170:173]
	v_mfma_f32_16x16x32_f16 v[96:99], v[32:35], v[238:241], v[4:7]
	v_mfma_f32_16x16x32_f16 v[4:7], v[242:245], v[198:201], v[206:209]
	v_mfma_f32_16x16x32_f16 v[84:87], v[246:249], v[218:221], v[4:7]
	v_mfma_f32_16x16x32_f16 v[4:7], v[242:245], v[230:233], v[210:213]
	v_mfma_f32_16x16x32_f16 v[88:91], v[246:249], v[238:241], v[4:7]
	s_setprio 0
	s_barrier
	ds_read_b128 v[132:135], v157
	ds_read_b128 v[168:171], v157 offset:1024
	ds_read_b128 v[206:209], v157 offset:2048
	ds_read_b128 v[210:213], v157 offset:3072
	s_waitcnt vmcnt(0)
	s_barrier
	s_waitcnt lgkmcnt(0)
	s_setprio 1
	s_waitcnt lgkmcnt(0)
	v_mfma_f32_16x16x32_f16 v[4:7], v[8:11], v[132:135], v[214:217]
	v_mfma_f32_16x16x32_f16 v[8:11], v[8:11], v[206:209], v[174:177]
	v_mfma_f32_16x16x32_f16 v[4:7], v[12:15], v[168:171], v[4:7]
	v_mfma_f32_16x16x32_f16 v[20:23], v[12:15], v[210:213], v[8:11]
	v_mfma_f32_16x16x32_f16 v[8:11], v[16:19], v[132:135], v[178:181]
	v_mfma_f32_16x16x32_f16 v[12:15], v[16:19], v[206:209], v[182:185]
	v_mfma_f32_16x16x32_f16 v[8:11], v[24:27], v[168:171], v[8:11]
	v_mfma_f32_16x16x32_f16 v[24:27], v[24:27], v[210:213], v[12:15]
	v_mfma_f32_16x16x32_f16 v[12:15], v[28:31], v[132:135], v[80:83]
	v_mfma_f32_16x16x32_f16 v[16:19], v[28:31], v[206:209], v[76:79]
	v_mfma_f32_16x16x32_f16 v[12:15], v[32:35], v[168:171], v[12:15]
	v_mfma_f32_16x16x32_f16 v[28:31], v[32:35], v[210:213], v[16:19]
	v_mfma_f32_16x16x32_f16 v[16:19], v[242:245], v[132:135], v[72:75]
	v_mfma_f32_16x16x32_f16 v[32:35], v[242:245], v[206:209], v[68:71]
	v_mfma_f32_16x16x32_f16 v[16:19], v[246:249], v[168:171], v[16:19]
	v_mfma_f32_16x16x32_f16 v[32:35], v[246:249], v[210:213], v[32:35]
	s_setprio 0
	s_barrier
	ds_read_b128 v[172:175], v156 offset:49152
	ds_read_b128 v[156:159], v156 offset:50176
	ds_read_b128 v[176:179], v154 offset:49152
	ds_read_b128 v[180:183], v154 offset:50176
	ds_read_b128 v[214:217], v153 offset:49152
	ds_read_b128 v[242:245], v153 offset:50176
	ds_read_b128 v[246:249], v152 offset:49152
	ds_read_b128 v[150:153], v152 offset:50176
	s_barrier
	s_waitcnt lgkmcnt(0)
	s_setprio 1
	s_waitcnt lgkmcnt(0)
	v_mfma_f32_16x16x32_f16 v[64:67], v[172:175], v[198:201], v[64:67]
	v_mfma_f32_16x16x32_f16 v[60:63], v[172:175], v[230:233], v[60:63]
	v_mfma_f32_16x16x32_f16 v[56:59], v[176:179], v[198:201], v[56:59]
	v_mfma_f32_16x16x32_f16 v[52:55], v[176:179], v[230:233], v[52:55]
	v_mfma_f32_16x16x32_f16 v[48:51], v[214:217], v[198:201], v[48:51]
	v_mfma_f32_16x16x32_f16 v[44:47], v[214:217], v[230:233], v[44:47]
	v_mfma_f32_16x16x32_f16 v[40:43], v[246:249], v[198:201], v[40:43]
	v_mfma_f32_16x16x32_f16 v[36:39], v[246:249], v[230:233], v[36:39]
	v_mfma_f32_16x16x32_f16 v[128:131], v[156:159], v[218:221], v[64:67]
	v_mfma_f32_16x16x32_f16 v[124:127], v[156:159], v[238:241], v[60:63]
	v_mfma_f32_16x16x32_f16 v[120:123], v[180:183], v[218:221], v[56:59]
	v_mfma_f32_16x16x32_f16 v[112:115], v[180:183], v[238:241], v[52:55]
	v_mfma_f32_16x16x32_f16 v[80:83], v[242:245], v[218:221], v[48:51]
	v_mfma_f32_16x16x32_f16 v[76:79], v[242:245], v[238:241], v[44:47]
	v_mfma_f32_16x16x32_f16 v[72:75], v[150:153], v[218:221], v[40:43]
	v_mfma_f32_16x16x32_f16 v[68:71], v[150:153], v[238:241], v[36:39]
	s_setprio 0
	s_setprio 1
	v_mfma_f32_16x16x32_f16 v[40:43], v[172:175], v[206:209], v[140:143]
	v_mfma_f32_16x16x32_f16 v[44:47], v[176:179], v[206:209], v[164:167]
	v_mfma_f32_16x16x32_f16 v[48:51], v[214:217], v[206:209], v[186:189]
	v_mfma_f32_16x16x32_f16 v[36:39], v[172:175], v[132:135], v[136:139]
	v_mfma_f32_16x16x32_f16 v[52:55], v[156:159], v[210:213], v[40:43]
	v_mfma_f32_16x16x32_f16 v[40:43], v[176:179], v[132:135], v[160:163]
	v_mfma_f32_16x16x32_f16 v[56:59], v[180:183], v[210:213], v[44:47]
	v_mfma_f32_16x16x32_f16 v[44:47], v[214:217], v[132:135], v[202:205]
	v_mfma_f32_16x16x32_f16 v[60:63], v[242:245], v[210:213], v[48:51]
	v_mfma_f32_16x16x32_f16 v[48:51], v[246:249], v[132:135], v[190:193]
	v_mfma_f32_16x16x32_f16 v[64:67], v[246:249], v[206:209], v[194:197]
	v_mfma_f32_16x16x32_f16 v[36:39], v[156:159], v[168:171], v[36:39]
	v_mfma_f32_16x16x32_f16 v[40:43], v[180:183], v[168:171], v[40:43]
	v_mfma_f32_16x16x32_f16 v[44:47], v[242:245], v[168:171], v[44:47]
	v_mfma_f32_16x16x32_f16 v[48:51], v[150:153], v[168:171], v[48:51]
	v_mfma_f32_16x16x32_f16 v[64:67], v[150:153], v[210:213], v[64:67]
	s_setprio 0
	s_movk_i32 s1, 0x100
	v_cmp_gt_u32_e32 vcc, s1, v3
	s_barrier
	s_and_saveexec_b64 s[12:13], vcc
	s_cbranch_execz .LBB0_245
	s_barrier

; #define LDA8(dst, b, h) _Pragma("unroll") for (int m = 0; m < 4; ++m) _Pragma("unroll") for (int k = 0; k < 2; ++k) \
;     dst[m][k] = *(const bf16x8*)((const char*)SA8(b, h) + lds_byte8(wr * 64 + m * 16 + fr, k * 32 + fq * 8))
; #define LDB8(dst, b, h) _Pragma("unroll") for (int n = 0; n < 2; ++n) _Pragma("unroll") for (int k = 0; k < 2; ++k) \
;     dst[n][k] = *(const bf16x8*)((const char*)SB8(b, h) + lds_byte8(wc * 32 + n * 16 + fr, k * 32 + fq * 8))
; #define WAIT_L8(n) asm volatile("s_waitcnt lgkmcnt(" #n ")" ::: "memory")
; #define BAR8 __builtin_amdgcn_s_barrier()
; #define SCHED8 __builtin_amdgcn_sched_barrier(0)
;     ...
;     LDB8(B0, 0, 0); SCHED8; LDA8(At, 0, 0); STAGE8(SA8(1, 1), A, lda, brow + 128, tt + 1);
;     WAIT_L8(8); BAR8; WAIT_L8(0); MMA8(0, 0, At, B0); BAR8; SCHED8;
;     LDB8(B1, 0, 1); STAGE8(SB8(0, 0), Bt, K, bcol, tt + 2);
;     BAR8; WAIT_L8(0); MMA8(0, 1, At, B1); BAR8;
;     LDA8(At, 0, 1); STAGE8(SA8(0, 0), A, lda, brow, tt + 2);
;     BAR8; WAIT_L8(0); MMA8(1, 0, At, B0); BAR8; SCHED8;
.LBB0_908:
	ds_read_b128 v[174:177], v171
	ds_read_b128 v[178:181], v171 offset:1024
	ds_read_b128 v[182:185], v171 offset:2048
	ds_read_b128 v[186:189], v171 offset:3072
	v_add_u32_e32 v172, 0xc000, v150
	v_lshl_add_u64 v[222:223], v[142:143], 0, s[12:13]
	v_readfirstlane_b32 s31, v172
	v_lshl_add_u64 v[226:227], v[222:223], 0, s[36:37]
	s_mov_b32 m0, s31
	v_add_u32_e32 v173, 0xe000, v150
	ds_read_b128 v[190:193], v156
	ds_read_b128 v[194:197], v156 offset:1024
	ds_read_b128 v[198:201], v155
	ds_read_b128 v[202:205], v155 offset:1024
	ds_read_b128 v[206:209], v154
	ds_read_b128 v[210:213], v154 offset:1024
	ds_read_b128 v[214:217], v153
	ds_read_b128 v[218:221], v153 offset:1024
	global_load_lds_dwordx4 v[226:227], off
	v_lshl_add_u64 v[226:227], v[144:145], 0, s[12:13]
	v_readfirstlane_b32 s31, v173
	v_lshl_add_u64 v[228:229], v[226:227], 0, s[36:37]
	s_mov_b32 m0, s31
	s_nop 0
	global_load_lds_dwordx4 v[228:229], off
	s_waitcnt lgkmcnt(8)
	s_waitcnt vmcnt(10)
	s_barrier
	s_waitcnt lgkmcnt(0)
	s_setprio 1
	s_waitcnt lgkmcnt(0)
	v_mfma_f32_16x16x32_bf16 v[128:131], v[190:193], v[174:177], v[128:131]
	v_mfma_f32_16x16x32_bf16 v[124:127], v[190:193], v[182:185], v[124:127]
	v_mfma_f32_16x16x32_bf16 v[120:123], v[198:201], v[174:177], v[120:123]
	v_mfma_f32_16x16x32_bf16 v[116:119], v[198:201], v[182:185], v[116:119]
	v_mfma_f32_16x16x32_bf16 v[112:115], v[206:209], v[174:177], v[112:115]
	v_mfma_f32_16x16x32_bf16 v[108:111], v[206:209], v[182:185], v[108:111]
	v_mfma_f32_16x16x32_bf16 v[104:107], v[214:217], v[174:177], v[104:107]
	v_mfma_f32_16x16x32_bf16 v[100:103], v[214:217], v[182:185], v[100:103]
	v_mfma_f32_16x16x32_bf16 v[128:131], v[194:197], v[178:181], v[128:131]
	v_mfma_f32_16x16x32_bf16 v[124:127], v[194:197], v[186:189], v[124:127]
	v_mfma_f32_16x16x32_bf16 v[120:123], v[202:205], v[178:181], v[120:123]
	v_mfma_f32_16x16x32_bf16 v[116:119], v[202:205], v[186:189], v[116:119]
	v_mfma_f32_16x16x32_bf16 v[112:115], v[210:213], v[178:181], v[112:115]
	v_mfma_f32_16x16x32_bf16 v[108:111], v[210:213], v[186:189], v[108:111]
	v_mfma_f32_16x16x32_bf16 v[104:107], v[218:221], v[178:181], v[104:107]
	v_mfma_f32_16x16x32_bf16 v[100:103], v[218:221], v[186:189], v[100:103]
	s_setprio 0
	s_barrier
	v_lshl_add_u64 v[228:229], v[138:139], 0, s[12:13]
	v_readfirstlane_b32 s31, v151
	v_lshl_add_u64 v[236:237], v[228:229], 0, s[38:39]
	s_mov_b32 m0, s31
	ds_read_b128 v[230:233], v167
	ds_read_b128 v[238:241], v167 offset:1024
	ds_read_b128 v[242:245], v167 offset:2048
	ds_read_b128 v[246:249], v167 offset:3072
	global_load_lds_dwordx4 v[236:237], off
	v_lshl_add_u64 v[236:237], v[140:141], 0, s[12:13]
	v_readfirstlane_b32 s31, v157
	v_lshl_add_u64 v[250:251], v[236:237], 0, s[38:39]
	s_mov_b32 m0, s31
	s_nop 0
	global_load_lds_dwordx4 v[250:251], off
	s_waitcnt vmcnt(10)
	s_barrier
	s_waitcnt lgkmcnt(0)
	s_setprio 1
	s_waitcnt lgkmcnt(0)
	v_mfma_f32_16x16x32_bf16 v[96:99], v[190:193], v[230:233], v[96:99]
	v_mfma_f32_16x16x32_bf16 v[92:95], v[190:193], v[242:245], v[92:95]
	v_mfma_f32_16x16x32_bf16 v[88:91], v[198:201], v[230:233], v[88:91]
	v_mfma_f32_16x16x32_bf16 v[84:87], v[198:201], v[242:245], v[84:87]
	v_mfma_f32_16x16x32_bf16 v[80:83], v[206:209], v[230:233], v[80:83]
	v_mfma_f32_16x16x32_bf16 v[76:79], v[206:209], v[242:245], v[76:79]
	v_mfma_f32_16x16x32_bf16 v[72:75], v[214:217], v[230:233], v[72:75]
	v_mfma_f32_16x16x32_bf16 v[68:71], v[214:217], v[242:245], v[68:71]
	v_mfma_f32_16x16x32_bf16 v[96:99], v[194:197], v[238:241], v[96:99]
	v_mfma_f32_16x16x32_bf16 v[92:95], v[194:197], v[246:249], v[92:95]
	v_mfma_f32_16x16x32_bf16 v[88:91], v[202:205], v[238:241], v[88:91]
	v_mfma_f32_16x16x32_bf16 v[84:87], v[202:205], v[246:249], v[84:87]
	v_mfma_f32_16x16x32_bf16 v[80:83], v[210:213], v[238:241], v[80:83]
	v_mfma_f32_16x16x32_bf16 v[76:79], v[210:213], v[246:249], v[76:79]
	v_mfma_f32_16x16x32_bf16 v[72:75], v[218:221], v[238:241], v[72:75]
	v_mfma_f32_16x16x32_bf16 v[68:71], v[218:221], v[246:249], v[68:71]
	s_setprio 0
	v_readfirstlane_b32 s31, v150
	v_lshl_add_u64 v[250:251], v[222:223], 0, s[40:41]
	s_mov_b32 m0, s31
	v_readfirstlane_b32 s31, v152
	s_barrier
	ds_read_b128 v[190:193], v156 offset:16384
	ds_read_b128 v[194:197], v156 offset:17408
	ds_read_b128 v[198:201], v155 offset:16384
	ds_read_b128 v[202:205], v155 offset:17408
	ds_read_b128 v[206:209], v154 offset:16384
	ds_read_b128 v[210:213], v154 offset:17408
	ds_read_b128 v[214:217], v153 offset:16384
	ds_read_b128 v[218:221], v153 offset:17408
	global_load_lds_dwordx4 v[250:251], off
	v_lshl_add_u64 v[250:251], v[226:227], 0, s[40:41]
	s_mov_b32 m0, s31
	s_nop 0
	global_load_lds_dwordx4 v[250:251], off
	s_barrier
	s_waitcnt lgkmcnt(0)
	s_setprio 1
	s_waitcnt lgkmcnt(0)
	v_mfma_f32_16x16x32_bf16 v[64:67], v[190:193], v[174:177], v[64:67]
	v_mfma_f32_16x16x32_bf16 v[60:63], v[190:193], v[182:185], v[60:63]
	v_mfma_f32_16x16x32_bf16 v[56:59], v[198:201], v[174:177], v[56:59]
	v_mfma_f32_16x16x32_bf16 v[52:55], v[198:201], v[182:185], v[52:55]
	v_mfma_f32_16x16x32_bf16 v[48:51], v[206:209], v[174:177], v[48:51]
	v_mfma_f32_16x16x32_bf16 v[44:47], v[206:209], v[182:185], v[44:47]
	v_mfma_f32_16x16x32_bf16 v[40:43], v[214:217], v[174:177], v[40:43]
	v_mfma_f32_16x16x32_bf16 v[36:39], v[214:217], v[182:185], v[36:39]
	v_mfma_f32_16x16x32_bf16 v[64:67], v[194:197], v[178:181], v[64:67]
	v_mfma_f32_16x16x32_bf16 v[60:63], v[194:197], v[186:189], v[60:63]
	v_mfma_f32_16x16x32_bf16 v[56:59], v[202:205], v[178:181], v[56:59]
	v_mfma_f32_16x16x32_bf16 v[52:55], v[202:205], v[186:189], v[52:55]
	v_mfma_f32_16x16x32_bf16 v[48:51], v[210:213], v[178:181], v[48:51]
	v_mfma_f32_16x16x32_bf16 v[44:47], v[210:213], v[186:189], v[44:47]
	v_mfma_f32_16x16x32_bf16 v[40:43], v[218:221], v[178:181], v[40:43]
	v_mfma_f32_16x16x32_bf16 v[36:39], v[218:221], v[186:189], v[36:39]
	s_setprio 0
	s_barrier
; #define LDA8(dst, b, h) _Pragma("unroll") for (int m = 0; m < 4; ++m) _Pragma("unroll") for (int k = 0; k < 2; ++k) \
;     dst[m][k] = *(const bf16x8*)((const char*)SA8(b, h) + lds_byte8(wr * 64 + m * 16 + fr, k * 32 + fq * 8))
; #define LDB8(dst, b, h) _Pragma("unroll") for (int n = 0; n < 2; ++n) _Pragma("unroll") for (int k = 0; k < 2; ++k) \
;     dst[n][k] = *(const bf16x8*)((const char*)SB8(b, h) + lds_byte8(wc * 32 + n * 16 + fr, k * 32 + fq * 8))
; #define WAIT_V8(n) asm volatile("s_waitcnt vmcnt(" #n ")" ::: "memory")
; #define WAIT_L8(n) asm volatile("s_waitcnt lgkmcnt(" #n ")" ::: "memory")
; #define BAR8 __builtin_amdgcn_s_barrier()
; #define SCHED8 __builtin_amdgcn_sched_barrier(0)
;     ...
;     STAGE8(SB8(0, 1), Bt, K, bcol + 128, tt + 2);
;     WAIT_V8(6); BAR8; MMA8(1, 1, At, B1); BAR8;
;     LDB8(B0, 1, 0); SCHED8; LDA8(At, 1, 0); STAGE8(SA8(0, 1), A, lda, brow + 128, tt + 2);
;     WAIT_L8(8); BAR8; WAIT_L8(0); MMA8(0, 0, At, B0); BAR8; SCHED8;
;     LDB8(B1, 1, 1); STAGE8(SB8(1, 0), Bt, K, bcol, tt + 3);
;     BAR8; WAIT_L8(0); MMA8(0, 1, At, B1); BAR8;
;     LDA8(At, 1, 1); STAGE8(SA8(1, 0), A, lda, brow, tt + 3);
;     BAR8; WAIT_L8(0); MMA8(1, 0, At, B0); BAR8; SCHED8;
	v_readfirstlane_b32 s31, v159
	v_lshl_add_u64 v[174:175], v[228:229], 0, s[42:43]
	s_mov_b32 m0, s31
	v_readfirstlane_b32 s31, v161
	global_load_lds_dwordx4 v[174:175], off
	v_lshl_add_u64 v[174:175], v[236:237], 0, s[42:43]
	s_mov_b32 m0, s31
	s_nop 0
	global_load_lds_dwordx4 v[174:175], off
	s_waitcnt vmcnt(10)
	s_barrier
	s_setprio 1
	v_mfma_f32_16x16x32_bf16 v[32:35], v[190:193], v[230:233], v[32:35]
	v_mfma_f32_16x16x32_bf16 v[28:31], v[190:193], v[242:245], v[28:31]
	v_mfma_f32_16x16x32_bf16 v[24:27], v[198:201], v[230:233], v[24:27]
	v_mfma_f32_16x16x32_bf16 v[20:23], v[198:201], v[242:245], v[20:23]
	v_mfma_f32_16x16x32_bf16 v[16:19], v[206:209], v[230:233], v[16:19]
	v_mfma_f32_16x16x32_bf16 v[12:15], v[206:209], v[242:245], v[12:15]
	v_mfma_f32_16x16x32_bf16 v[8:11], v[214:217], v[230:233], v[8:11]
	v_mfma_f32_16x16x32_bf16 v[4:7], v[214:217], v[242:245], v[4:7]
	v_mfma_f32_16x16x32_bf16 v[32:35], v[194:197], v[238:241], v[32:35]
	v_mfma_f32_16x16x32_bf16 v[28:31], v[194:197], v[246:249], v[28:31]
	v_mfma_f32_16x16x32_bf16 v[24:27], v[202:205], v[238:241], v[24:27]
	v_mfma_f32_16x16x32_bf16 v[20:23], v[202:205], v[246:249], v[20:23]
	v_mfma_f32_16x16x32_bf16 v[16:19], v[210:213], v[238:241], v[16:19]
	v_mfma_f32_16x16x32_bf16 v[12:15], v[210:213], v[246:249], v[12:15]
	v_mfma_f32_16x16x32_bf16 v[8:11], v[218:221], v[238:241], v[8:11]
	v_mfma_f32_16x16x32_bf16 v[4:7], v[218:221], v[246:249], v[4:7]
	s_setprio 0
	s_barrier
	ds_read_b128 v[174:177], v160
	ds_read_b128 v[178:181], v160 offset:1024
	ds_read_b128 v[182:185], v160 offset:2048
	ds_read_b128 v[186:189], v160 offset:3072
	v_readfirstlane_b32 s31, v162
	v_lshl_add_u64 v[230:231], v[222:223], 0, s[44:45]
	s_mov_b32 m0, s31
	v_readfirstlane_b32 s31, v163
	ds_read_b128 v[190:193], v156 offset:32768
	ds_read_b128 v[194:197], v156 offset:33792
	ds_read_b128 v[198:201], v155 offset:32768
	ds_read_b128 v[202:205], v155 offset:33792
	ds_read_b128 v[206:209], v154 offset:32768
	ds_read_b128 v[210:213], v154 offset:33792
	ds_read_b128 v[214:217], v153 offset:32768
	ds_read_b128 v[218:221], v153 offset:33792
	global_load_lds_dwordx4 v[230:231], off
	v_lshl_add_u64 v[230:231], v[226:227], 0, s[44:45]
	s_mov_b32 m0, s31
	s_nop 0
	global_load_lds_dwordx4 v[230:231], off
	s_waitcnt lgkmcnt(8)
	s_waitcnt vmcnt(10)
	s_barrier
	s_waitcnt lgkmcnt(0)
	s_setprio 1
	s_waitcnt lgkmcnt(0)
	v_mfma_f32_16x16x32_bf16 v[128:131], v[190:193], v[174:177], v[128:131]
	v_mfma_f32_16x16x32_bf16 v[124:127], v[190:193], v[182:185], v[124:127]
	v_mfma_f32_16x16x32_bf16 v[120:123], v[198:201], v[174:177], v[120:123]
	v_mfma_f32_16x16x32_bf16 v[116:119], v[198:201], v[182:185], v[116:119]
	v_mfma_f32_16x16x32_bf16 v[112:115], v[206:209], v[174:177], v[112:115]
	v_mfma_f32_16x16x32_bf16 v[108:111], v[206:209], v[182:185], v[108:111]
	v_mfma_f32_16x16x32_bf16 v[104:107], v[214:217], v[174:177], v[104:107]
	v_mfma_f32_16x16x32_bf16 v[100:103], v[214:217], v[182:185], v[100:103]
	v_mfma_f32_16x16x32_bf16 v[128:131], v[194:197], v[178:181], v[128:131]
	v_mfma_f32_16x16x32_bf16 v[124:127], v[194:197], v[186:189], v[124:127]
	v_mfma_f32_16x16x32_bf16 v[120:123], v[202:205], v[178:181], v[120:123]
	v_mfma_f32_16x16x32_bf16 v[116:119], v[202:205], v[186:189], v[116:119]
	v_mfma_f32_16x16x32_bf16 v[112:115], v[210:213], v[178:181], v[112:115]
	v_mfma_f32_16x16x32_bf16 v[108:111], v[210:213], v[186:189], v[108:111]
	v_mfma_f32_16x16x32_bf16 v[104:107], v[218:221], v[178:181], v[104:107]
	v_mfma_f32_16x16x32_bf16 v[100:103], v[218:221], v[186:189], v[100:103]
	s_setprio 0
	s_barrier
	v_readfirstlane_b32 s31, v164
	v_lshl_add_u64 v[250:251], v[228:229], 0, s[46:47]
	s_mov_b32 m0, s31
	v_readfirstlane_b32 s31, v165
	ds_read_b128 v[230:233], v158
	ds_read_b128 v[238:241], v158 offset:1024
	ds_read_b128 v[242:245], v158 offset:2048
	ds_read_b128 v[246:249], v158 offset:3072
	global_load_lds_dwordx4 v[250:251], off
	v_lshl_add_u64 v[250:251], v[236:237], 0, s[46:47]
	s_mov_b32 m0, s31
	s_nop 0
	global_load_lds_dwordx4 v[250:251], off
	s_waitcnt vmcnt(10)
	s_barrier
	s_waitcnt lgkmcnt(0)
	s_setprio 1
	s_waitcnt lgkmcnt(0)
	v_mfma_f32_16x16x32_bf16 v[96:99], v[190:193], v[230:233], v[96:99]
	v_mfma_f32_16x16x32_bf16 v[92:95], v[190:193], v[242:245], v[92:95]
	v_mfma_f32_16x16x32_bf16 v[88:91], v[198:201], v[230:233], v[88:91]
	v_mfma_f32_16x16x32_bf16 v[84:87], v[198:201], v[242:245], v[84:87]
	v_mfma_f32_16x16x32_bf16 v[80:83], v[206:209], v[230:233], v[80:83]
	v_mfma_f32_16x16x32_bf16 v[76:79], v[206:209], v[242:245], v[76:79]
	v_mfma_f32_16x16x32_bf16 v[72:75], v[214:217], v[230:233], v[72:75]
	v_mfma_f32_16x16x32_bf16 v[68:71], v[214:217], v[242:245], v[68:71]
	v_mfma_f32_16x16x32_bf16 v[96:99], v[194:197], v[238:241], v[96:99]
	v_mfma_f32_16x16x32_bf16 v[92:95], v[194:197], v[246:249], v[92:95]
	v_mfma_f32_16x16x32_bf16 v[88:91], v[202:205], v[238:241], v[88:91]
	v_mfma_f32_16x16x32_bf16 v[84:87], v[202:205], v[246:249], v[84:87]
	v_mfma_f32_16x16x32_bf16 v[80:83], v[210:213], v[238:241], v[80:83]
	v_mfma_f32_16x16x32_bf16 v[76:79], v[210:213], v[246:249], v[76:79]
	v_mfma_f32_16x16x32_bf16 v[72:75], v[218:221], v[238:241], v[72:75]
	v_mfma_f32_16x16x32_bf16 v[68:71], v[218:221], v[246:249], v[68:71]
	s_setprio 0
	v_readfirstlane_b32 s31, v166
	v_lshl_add_u64 v[222:223], v[222:223], 0, s[48:49]
	s_mov_b32 m0, s31
	v_readfirstlane_b32 s31, v168
	s_barrier
	ds_read_b128 v[190:193], v156 offset:49152
	ds_read_b128 v[194:197], v156 offset:50176
	ds_read_b128 v[198:201], v155 offset:49152
	ds_read_b128 v[202:205], v155 offset:50176
	ds_read_b128 v[206:209], v154 offset:49152
	ds_read_b128 v[210:213], v154 offset:50176
	ds_read_b128 v[214:217], v153 offset:49152
	ds_read_b128 v[218:221], v153 offset:50176
	global_load_lds_dwordx4 v[222:223], off
	v_lshl_add_u64 v[222:223], v[226:227], 0, s[48:49]
	s_mov_b32 m0, s31
	s_nop 0
	global_load_lds_dwordx4 v[222:223], off
	s_barrier
; #define LDA8(dst, b, h) _Pragma("unroll") for (int m = 0; m < 4; ++m) _Pragma("unroll") for (int k = 0; k < 2; ++k) \
;     dst[m][k] = *(const bf16x8*)((const char*)SA8(b, h) + lds_byte8(wr * 64 + m * 16 + fr, k * 32 + fq * 8))
; #define LDB8(dst, b, h) _Pragma("unroll") for (int n = 0; n < 2; ++n) _Pragma("unroll") for (int k = 0; k < 2; ++k) \
;     dst[n][k] = *(const bf16x8*)((const char*)SB8(b, h) + lds_byte8(wc * 32 + n * 16 + fr, k * 32 + fq * 8))
; #define WAIT_V8(n) asm volatile("s_waitcnt vmcnt(" #n ")" ::: "memory")
; #define WAIT_L8(n) asm volatile("s_waitcnt lgkmcnt(" #n ")" ::: "memory")
; #define BAR8 __builtin_amdgcn_s_barrier()
; #define SCHED8 __builtin_amdgcn_sched_barrier(0)
;     ...
;     BAR8; WAIT_L8(0); MMA8(1, 0, At, B0); BAR8; SCHED8;
;     STAGE8(SB8(1, 1), Bt, K, bcol + 128, tt + 3);
;     WAIT_V8(6); BAR8; MMA8(1, 1, At, B1); BAR8;
;   }
;   { LDB8(B0, 0, 0); LDA8(At, 0, 0); STAGE8(SA8(1, 1), A, lda, brow + 128, nt - 1);
;     BAR8; WAIT_L8(0); MMA8(0, 0, At, B0); BAR8;
;     LDB8(B1, 0, 1); BAR8; WAIT_L8(0); MMA8(0, 1, At, B1); BAR8;
	s_waitcnt lgkmcnt(0)
	s_setprio 1
	s_waitcnt lgkmcnt(0)
	v_mfma_f32_16x16x32_bf16 v[64:67], v[190:193], v[174:177], v[64:67]
	v_mfma_f32_16x16x32_bf16 v[60:63], v[190:193], v[182:185], v[60:63]
	v_mfma_f32_16x16x32_bf16 v[56:59], v[198:201], v[174:177], v[56:59]
	v_mfma_f32_16x16x32_bf16 v[52:55], v[198:201], v[182:185], v[52:55]
	v_mfma_f32_16x16x32_bf16 v[48:51], v[206:209], v[174:177], v[48:51]
	v_mfma_f32_16x16x32_bf16 v[44:47], v[206:209], v[182:185], v[44:47]
	v_mfma_f32_16x16x32_bf16 v[40:43], v[214:217], v[174:177], v[40:43]
	v_mfma_f32_16x16x32_bf16 v[36:39], v[214:217], v[182:185], v[36:39]
	v_mfma_f32_16x16x32_bf16 v[64:67], v[194:197], v[178:181], v[64:67]
	v_mfma_f32_16x16x32_bf16 v[60:63], v[194:197], v[186:189], v[60:63]
	v_mfma_f32_16x16x32_bf16 v[56:59], v[202:205], v[178:181], v[56:59]
	v_mfma_f32_16x16x32_bf16 v[52:55], v[202:205], v[186:189], v[52:55]
	v_mfma_f32_16x16x32_bf16 v[48:51], v[210:213], v[178:181], v[48:51]
	v_mfma_f32_16x16x32_bf16 v[44:47], v[210:213], v[186:189], v[44:47]
	v_mfma_f32_16x16x32_bf16 v[40:43], v[218:221], v[178:181], v[40:43]
	v_mfma_f32_16x16x32_bf16 v[36:39], v[218:221], v[186:189], v[36:39]
	s_setprio 0
	s_barrier
	v_readfirstlane_b32 s31, v169
	v_lshl_add_u64 v[174:175], v[228:229], 0, s[50:51]
	s_mov_b32 m0, s31
	v_readfirstlane_b32 s31, v170
	global_load_lds_dwordx4 v[174:175], off
	v_lshl_add_u64 v[174:175], v[236:237], 0, s[50:51]
	s_mov_b32 m0, s31
	s_nop 0
	global_load_lds_dwordx4 v[174:175], off
	s_waitcnt vmcnt(10)
	s_barrier
	s_setprio 1
	v_mfma_f32_16x16x32_bf16 v[32:35], v[190:193], v[230:233], v[32:35]
	v_mfma_f32_16x16x32_bf16 v[28:31], v[190:193], v[242:245], v[28:31]
	v_mfma_f32_16x16x32_bf16 v[24:27], v[198:201], v[230:233], v[24:27]
	v_mfma_f32_16x16x32_bf16 v[20:23], v[198:201], v[242:245], v[20:23]
	v_mfma_f32_16x16x32_bf16 v[16:19], v[206:209], v[230:233], v[16:19]
	v_mfma_f32_16x16x32_bf16 v[12:15], v[206:209], v[242:245], v[12:15]
	v_mfma_f32_16x16x32_bf16 v[8:11], v[214:217], v[230:233], v[8:11]
	v_mfma_f32_16x16x32_bf16 v[4:7], v[214:217], v[242:245], v[4:7]
	v_mfma_f32_16x16x32_bf16 v[32:35], v[194:197], v[238:241], v[32:35]
	v_mfma_f32_16x16x32_bf16 v[28:31], v[194:197], v[246:249], v[28:31]
	v_mfma_f32_16x16x32_bf16 v[24:27], v[202:205], v[238:241], v[24:27]
	v_mfma_f32_16x16x32_bf16 v[20:23], v[202:205], v[246:249], v[20:23]
	v_mfma_f32_16x16x32_bf16 v[16:19], v[210:213], v[238:241], v[16:19]
	v_mfma_f32_16x16x32_bf16 v[12:15], v[210:213], v[246:249], v[12:15]
	v_mfma_f32_16x16x32_bf16 v[8:11], v[218:221], v[238:241], v[8:11]
	v_mfma_f32_16x16x32_bf16 v[4:7], v[218:221], v[246:249], v[4:7]
	s_setprio 0
	s_add_i32 s29, s29, 2
	s_add_u32 s12, s12, 0x100
	s_addc_u32 s13, s13, 0
	s_cmp_lt_u32 s29, 12
	s_barrier
	s_cbranch_scc1 .LBB0_908
	s_add_u32 s2, s2, s27
	s_addc_u32 s3, s3, 0
	s_add_u32 s2, s2, 0x6000780
	s_addc_u32 s3, s3, 0
	v_lshl_add_u64 v[136:137], v[136:137], 1, s[2:3]
	v_readfirstlane_b32 s12, v172
	v_lshl_add_u64 v[0:1], v[0:1], 1, v[136:137]
	s_mov_b32 m0, s12
	ds_read_b128 v[138:141], v171
	ds_read_b128 v[142:145], v171 offset:1024
	ds_read_b128 v[162:165], v171 offset:2048
	ds_read_b128 v[168:171], v171 offset:3072
	ds_read_b128 v[174:177], v156
	ds_read_b128 v[178:181], v156 offset:1024
	ds_read_b128 v[182:185], v155
	ds_read_b128 v[186:189], v155 offset:1024
	ds_read_b128 v[190:193], v154
	ds_read_b128 v[194:197], v154 offset:1024
	ds_read_b128 v[198:201], v153
	ds_read_b128 v[202:205], v153 offset:1024
	global_load_lds_dwordx4 v[0:1], off
	v_lshl_add_u64 v[0:1], v[134:135], 1, s[2:3]
	v_readfirstlane_b32 s2, v173
	v_lshl_add_u64 v[0:1], v[132:133], 1, v[0:1]
	s_mov_b32 m0, s2
	s_nop 0
	global_load_lds_dwordx4 v[0:1], off
	s_waitcnt vmcnt(10)
	s_barrier
	s_waitcnt lgkmcnt(0)
	s_setprio 1
	s_waitcnt lgkmcnt(0)
	v_mfma_f32_16x16x32_bf16 v[128:131], v[174:177], v[138:141], v[128:131]
	v_mfma_f32_16x16x32_bf16 v[124:127], v[174:177], v[162:165], v[124:127]
	v_mfma_f32_16x16x32_bf16 v[120:123], v[182:185], v[138:141], v[120:123]
	v_mfma_f32_16x16x32_bf16 v[112:115], v[190:193], v[138:141], v[112:115]
	v_mfma_f32_16x16x32_bf16 v[128:131], v[178:181], v[142:145], v[128:131]
	v_mfma_f32_16x16x32_bf16 v[124:127], v[178:181], v[168:171], v[124:127]
	v_mfma_f32_16x16x32_bf16 v[120:123], v[186:189], v[142:145], v[120:123]
	v_mfma_f32_16x16x32_bf16 v[116:119], v[182:185], v[162:165], v[116:119]
	v_mfma_f32_16x16x32_bf16 v[112:115], v[194:197], v[142:145], v[112:115]
	v_mfma_f32_16x16x32_bf16 v[108:111], v[190:193], v[162:165], v[108:111]
	v_mfma_f32_16x16x32_bf16 v[104:107], v[198:201], v[138:141], v[104:107]
	v_mfma_f32_16x16x32_bf16 v[100:103], v[198:201], v[162:165], v[100:103]
	v_mfma_f32_16x16x32_bf16 v[132:135], v[186:189], v[168:171], v[116:119]
	v_mfma_f32_16x16x32_bf16 v[206:209], v[194:197], v[168:171], v[108:111]
	v_mfma_f32_16x16x32_bf16 v[210:213], v[202:205], v[142:145], v[104:107]
	v_mfma_f32_16x16x32_bf16 v[214:217], v[202:205], v[168:171], v[100:103]
	s_setprio 0
	s_barrier
	s_nop 1
	ds_read_b128 v[100:103], v167
	ds_read_b128 v[104:107], v167 offset:1024
	ds_read_b128 v[108:111], v167 offset:2048
	ds_read_b128 v[116:119], v167 offset:3072
	s_waitcnt vmcnt(8)
	s_barrier
; #define LDA8(dst, b, h) _Pragma("unroll") for (int m = 0; m < 4; ++m) _Pragma("unroll") for (int k = 0; k < 2; ++k) \
;     dst[m][k] = *(const bf16x8*)((const char*)SA8(b, h) + lds_byte8(wr * 64 + m * 16 + fr, k * 32 + fq * 8))
; #define LDB8(dst, b, h) _Pragma("unroll") for (int n = 0; n < 2; ++n) _Pragma("unroll") for (int k = 0; k < 2; ++k) \
;     dst[n][k] = *(const bf16x8*)((const char*)SB8(b, h) + lds_byte8(wc * 32 + n * 16 + fr, k * 32 + fq * 8))
; #define WAIT_V8(n) asm volatile("s_waitcnt vmcnt(" #n ")" ::: "memory")
; #define WAIT_L8(n) asm volatile("s_waitcnt lgkmcnt(" #n ")" ::: "memory")
; #define BAR8 __builtin_amdgcn_s_barrier()
;     ...
;     LDB8(B1, 0, 1); BAR8; WAIT_L8(0); MMA8(0, 1, At, B1); BAR8;
;     LDA8(At, 0, 1); WAIT_V8(4); BAR8; WAIT_L8(0); MMA8(1, 0, At, B0); MMA8(1, 1, At, B1); BAR8; }
;   { LDB8(B0, 1, 0); LDA8(At, 1, 0); WAIT_V8(2); BAR8; WAIT_L8(0); MMA8(0, 0, At, B0); BAR8;
	s_waitcnt lgkmcnt(0)
	s_setprio 1
	s_waitcnt lgkmcnt(0)
	v_mfma_f32_16x16x32_bf16 v[80:83], v[190:193], v[100:103], v[80:83]
	v_mfma_f32_16x16x32_bf16 v[76:79], v[190:193], v[108:111], v[76:79]
	v_mfma_f32_16x16x32_bf16 v[72:75], v[198:201], v[100:103], v[72:75]
	v_mfma_f32_16x16x32_bf16 v[68:71], v[198:201], v[108:111], v[68:71]
	v_mfma_f32_16x16x32_bf16 v[96:99], v[174:177], v[100:103], v[96:99]
	v_mfma_f32_16x16x32_bf16 v[92:95], v[174:177], v[108:111], v[92:95]
	v_mfma_f32_16x16x32_bf16 v[88:91], v[182:185], v[100:103], v[88:91]
	v_mfma_f32_16x16x32_bf16 v[84:87], v[182:185], v[108:111], v[84:87]
	v_mfma_f32_16x16x32_bf16 v[80:83], v[194:197], v[104:107], v[80:83]
	v_mfma_f32_16x16x32_bf16 v[76:79], v[194:197], v[116:119], v[76:79]
	v_mfma_f32_16x16x32_bf16 v[72:75], v[202:205], v[104:107], v[72:75]
	v_mfma_f32_16x16x32_bf16 v[68:71], v[202:205], v[116:119], v[68:71]
	v_mfma_f32_16x16x32_bf16 v[218:221], v[178:181], v[104:107], v[96:99]
	v_mfma_f32_16x16x32_bf16 v[172:175], v[178:181], v[116:119], v[92:95]
	v_mfma_f32_16x16x32_bf16 v[176:179], v[186:189], v[104:107], v[88:91]
	v_mfma_f32_16x16x32_bf16 v[180:183], v[186:189], v[116:119], v[84:87]
	s_setprio 0
	s_barrier
	s_nop 0
	ds_read_b128 v[84:87], v156 offset:16384
	ds_read_b128 v[88:91], v156 offset:17408
	ds_read_b128 v[92:95], v155 offset:16384
	ds_read_b128 v[96:99], v155 offset:17408
	ds_read_b128 v[184:187], v154 offset:16384
	ds_read_b128 v[188:191], v154 offset:17408
	ds_read_b128 v[192:195], v153 offset:16384
	ds_read_b128 v[196:199], v153 offset:17408
	s_waitcnt vmcnt(4)
	s_barrier
	s_waitcnt lgkmcnt(0)
	s_setprio 1
	s_waitcnt lgkmcnt(0)
	v_mfma_f32_16x16x32_bf16 v[64:67], v[84:87], v[138:141], v[64:67]
	v_mfma_f32_16x16x32_bf16 v[60:63], v[84:87], v[162:165], v[60:63]
	v_mfma_f32_16x16x32_bf16 v[56:59], v[92:95], v[138:141], v[56:59]
	v_mfma_f32_16x16x32_bf16 v[52:55], v[92:95], v[162:165], v[52:55]
	v_mfma_f32_16x16x32_bf16 v[48:51], v[184:187], v[138:141], v[48:51]
	v_mfma_f32_16x16x32_bf16 v[44:47], v[184:187], v[162:165], v[44:47]
	v_mfma_f32_16x16x32_bf16 v[40:43], v[192:195], v[138:141], v[40:43]
	v_mfma_f32_16x16x32_bf16 v[36:39], v[192:195], v[162:165], v[36:39]
	v_mfma_f32_16x16x32_bf16 v[64:67], v[88:91], v[142:145], v[64:67]
	v_mfma_f32_16x16x32_bf16 v[60:63], v[88:91], v[168:171], v[60:63]
	v_mfma_f32_16x16x32_bf16 v[56:59], v[96:99], v[142:145], v[56:59]
	v_mfma_f32_16x16x32_bf16 v[52:55], v[96:99], v[168:171], v[52:55]
	v_mfma_f32_16x16x32_bf16 v[48:51], v[188:191], v[142:145], v[48:51]
	v_mfma_f32_16x16x32_bf16 v[44:47], v[188:191], v[168:171], v[44:47]
	v_mfma_f32_16x16x32_bf16 v[40:43], v[196:199], v[142:145], v[40:43]
	v_mfma_f32_16x16x32_bf16 v[36:39], v[196:199], v[168:171], v[36:39]
	s_setprio 0
	s_setprio 1
	v_mfma_f32_16x16x32_bf16 v[32:35], v[84:87], v[100:103], v[32:35]
	v_mfma_f32_16x16x32_bf16 v[28:31], v[84:87], v[108:111], v[28:31]
	v_mfma_f32_16x16x32_bf16 v[24:27], v[92:95], v[100:103], v[24:27]
	v_mfma_f32_16x16x32_bf16 v[20:23], v[92:95], v[108:111], v[20:23]
	v_mfma_f32_16x16x32_bf16 v[16:19], v[184:187], v[100:103], v[16:19]
	v_mfma_f32_16x16x32_bf16 v[12:15], v[184:187], v[108:111], v[12:15]
	v_mfma_f32_16x16x32_bf16 v[8:11], v[192:195], v[100:103], v[8:11]
	v_mfma_f32_16x16x32_bf16 v[4:7], v[192:195], v[108:111], v[4:7]
	v_mfma_f32_16x16x32_bf16 v[136:139], v[88:91], v[104:107], v[32:35]
	v_mfma_f32_16x16x32_bf16 v[140:143], v[88:91], v[116:119], v[28:31]
	v_mfma_f32_16x16x32_bf16 v[162:165], v[96:99], v[104:107], v[24:27]
	v_mfma_f32_16x16x32_bf16 v[166:169], v[96:99], v[116:119], v[20:23]
	v_mfma_f32_16x16x32_bf16 v[200:203], v[188:191], v[104:107], v[16:19]
	v_mfma_f32_16x16x32_bf16 v[184:187], v[188:191], v[116:119], v[12:15]
	v_mfma_f32_16x16x32_bf16 v[188:191], v[196:199], v[104:107], v[8:11]
	v_mfma_f32_16x16x32_bf16 v[192:195], v[196:199], v[116:119], v[4:7]
	s_setprio 0
	s_barrier
	ds_read_b128 v[196:199], v160
	ds_read_b128 v[230:233], v160 offset:1024
	ds_read_b128 v[238:241], v160 offset:2048
	ds_read_b128 v[242:245], v160 offset:3072
	ds_read_b128 v[8:11], v156 offset:32768
	ds_read_b128 v[12:15], v156 offset:33792
	ds_read_b128 v[16:19], v155 offset:32768
	ds_read_b128 v[24:27], v155 offset:33792
	ds_read_b128 v[28:31], v154 offset:32768
	ds_read_b128 v[32:35], v154 offset:33792
	ds_read_b128 v[246:249], v153 offset:32768
	ds_read_b128 v[226:229], v153 offset:33792
	s_waitcnt vmcnt(2)
	s_barrier
; #define LDA8(dst, b, h) _Pragma("unroll") for (int m = 0; m < 4; ++m) _Pragma("unroll") for (int k = 0; k < 2; ++k) \
;     dst[m][k] = *(const bf16x8*)((const char*)SA8(b, h) + lds_byte8(wr * 64 + m * 16 + fr, k * 32 + fq * 8))
; #define LDB8(dst, b, h) _Pragma("unroll") for (int n = 0; n < 2; ++n) _Pragma("unroll") for (int k = 0; k < 2; ++k) \
;     dst[n][k] = *(const bf16x8*)((const char*)SB8(b, h) + lds_byte8(wc * 32 + n * 16 + fr, k * 32 + fq * 8))
; #define WAIT_V8(n) asm volatile("s_waitcnt vmcnt(" #n ")" ::: "memory")
; #define WAIT_L8(n) asm volatile("s_waitcnt lgkmcnt(" #n ")" ::: "memory")
; #define BAR8 __builtin_amdgcn_s_barrier()
;     ...
;   { LDB8(B0, 1, 0); LDA8(At, 1, 0); WAIT_V8(2); BAR8; WAIT_L8(0); MMA8(0, 0, At, B0); BAR8;
;     LDB8(B1, 1, 1); WAIT_V8(0); BAR8; WAIT_L8(0); MMA8(0, 1, At, B1); BAR8;
;     LDA8(At, 1, 1); BAR8; WAIT_L8(0); MMA8(1, 0, At, B0); MMA8(1, 1, At, B1); BAR8; }
;   if (wr == 0) BAR8;
	s_waitcnt lgkmcnt(0)
	s_setprio 1
	s_waitcnt lgkmcnt(0)
	v_mfma_f32_16x16x32_bf16 v[4:7], v[8:11], v[196:199], v[128:131]
	v_mfma_f32_16x16x32_bf16 v[104:107], v[12:15], v[230:233], v[4:7]
	v_mfma_f32_16x16x32_bf16 v[4:7], v[8:11], v[238:241], v[124:127]
	v_mfma_f32_16x16x32_bf16 v[116:119], v[12:15], v[242:245], v[4:7]
	v_mfma_f32_16x16x32_bf16 v[4:7], v[16:19], v[196:199], v[120:123]
	v_mfma_f32_16x16x32_bf16 v[100:103], v[24:27], v[230:233], v[4:7]
	v_mfma_f32_16x16x32_bf16 v[4:7], v[16:19], v[238:241], v[132:135]
	v_mfma_f32_16x16x32_bf16 v[108:111], v[24:27], v[242:245], v[4:7]
	v_mfma_f32_16x16x32_bf16 v[4:7], v[28:31], v[196:199], v[112:115]
	v_mfma_f32_16x16x32_bf16 v[92:95], v[32:35], v[230:233], v[4:7]
	v_mfma_f32_16x16x32_bf16 v[4:7], v[28:31], v[238:241], v[206:209]
	v_mfma_f32_16x16x32_bf16 v[96:99], v[32:35], v[242:245], v[4:7]
	v_mfma_f32_16x16x32_bf16 v[4:7], v[246:249], v[196:199], v[210:213]
	v_mfma_f32_16x16x32_bf16 v[84:87], v[226:229], v[230:233], v[4:7]
	v_mfma_f32_16x16x32_bf16 v[4:7], v[246:249], v[238:241], v[214:217]
	v_mfma_f32_16x16x32_bf16 v[88:91], v[226:229], v[242:245], v[4:7]
	s_setprio 0
	s_barrier
	ds_read_b128 v[132:135], v158
	ds_read_b128 v[204:207], v158 offset:1024
	ds_read_b128 v[208:211], v158 offset:2048
	ds_read_b128 v[158:161], v158 offset:3072
	s_waitcnt vmcnt(0)
	s_barrier
	s_waitcnt lgkmcnt(0)
	s_setprio 1
	s_waitcnt lgkmcnt(0)
	v_mfma_f32_16x16x32_bf16 v[4:7], v[8:11], v[132:135], v[218:221]
	v_mfma_f32_16x16x32_bf16 v[8:11], v[8:11], v[208:211], v[172:175]
	v_mfma_f32_16x16x32_bf16 v[4:7], v[12:15], v[204:207], v[4:7]
	v_mfma_f32_16x16x32_bf16 v[20:23], v[12:15], v[158:161], v[8:11]
	v_mfma_f32_16x16x32_bf16 v[8:11], v[16:19], v[132:135], v[176:179]
	v_mfma_f32_16x16x32_bf16 v[12:15], v[16:19], v[208:211], v[180:183]
	v_mfma_f32_16x16x32_bf16 v[8:11], v[24:27], v[204:207], v[8:11]
	v_mfma_f32_16x16x32_bf16 v[24:27], v[24:27], v[158:161], v[12:15]
	v_mfma_f32_16x16x32_bf16 v[12:15], v[28:31], v[132:135], v[80:83]
	v_mfma_f32_16x16x32_bf16 v[16:19], v[28:31], v[208:211], v[76:79]
	v_mfma_f32_16x16x32_bf16 v[12:15], v[32:35], v[204:207], v[12:15]
	v_mfma_f32_16x16x32_bf16 v[28:31], v[32:35], v[158:161], v[16:19]
	v_mfma_f32_16x16x32_bf16 v[16:19], v[246:249], v[132:135], v[72:75]
	v_mfma_f32_16x16x32_bf16 v[32:35], v[246:249], v[208:211], v[68:71]
	v_mfma_f32_16x16x32_bf16 v[16:19], v[226:229], v[204:207], v[16:19]
	v_mfma_f32_16x16x32_bf16 v[32:35], v[226:229], v[158:161], v[32:35]
	s_setprio 0
	s_barrier
	ds_read_b128 v[170:173], v156 offset:49152
	ds_read_b128 v[174:177], v156 offset:50176
	ds_read_b128 v[178:181], v155 offset:49152
	ds_read_b128 v[212:215], v155 offset:50176
	ds_read_b128 v[216:219], v154 offset:49152
	ds_read_b128 v[154:157], v154 offset:50176
	ds_read_b128 v[220:223], v153 offset:49152
	ds_read_b128 v[150:153], v153 offset:50176
	s_barrier
	s_waitcnt lgkmcnt(0)
	s_setprio 1
	s_waitcnt lgkmcnt(0)
	v_mfma_f32_16x16x32_bf16 v[64:67], v[170:173], v[196:199], v[64:67]
	v_mfma_f32_16x16x32_bf16 v[60:63], v[170:173], v[238:241], v[60:63]
	v_mfma_f32_16x16x32_bf16 v[56:59], v[178:181], v[196:199], v[56:59]
	v_mfma_f32_16x16x32_bf16 v[52:55], v[178:181], v[238:241], v[52:55]
	v_mfma_f32_16x16x32_bf16 v[48:51], v[216:219], v[196:199], v[48:51]
	v_mfma_f32_16x16x32_bf16 v[44:47], v[216:219], v[238:241], v[44:47]
	v_mfma_f32_16x16x32_bf16 v[40:43], v[220:223], v[196:199], v[40:43]
	v_mfma_f32_16x16x32_bf16 v[36:39], v[220:223], v[238:241], v[36:39]
	v_mfma_f32_16x16x32_bf16 v[128:131], v[174:177], v[230:233], v[64:67]
	v_mfma_f32_16x16x32_bf16 v[124:127], v[174:177], v[242:245], v[60:63]
	v_mfma_f32_16x16x32_bf16 v[120:123], v[212:215], v[230:233], v[56:59]
	v_mfma_f32_16x16x32_bf16 v[112:115], v[212:215], v[242:245], v[52:55]
	v_mfma_f32_16x16x32_bf16 v[80:83], v[154:157], v[230:233], v[48:51]
	v_mfma_f32_16x16x32_bf16 v[76:79], v[154:157], v[242:245], v[44:47]
	v_mfma_f32_16x16x32_bf16 v[72:75], v[150:153], v[230:233], v[40:43]
	v_mfma_f32_16x16x32_bf16 v[68:71], v[150:153], v[242:245], v[36:39]
	s_setprio 0
	s_setprio 1
	v_mfma_f32_16x16x32_bf16 v[40:43], v[170:173], v[208:211], v[140:143]
	v_mfma_f32_16x16x32_bf16 v[44:47], v[178:181], v[208:211], v[166:169]
	v_mfma_f32_16x16x32_bf16 v[48:51], v[216:219], v[208:211], v[184:187]
	v_mfma_f32_16x16x32_bf16 v[36:39], v[170:173], v[132:135], v[136:139]
	v_mfma_f32_16x16x32_bf16 v[52:55], v[174:177], v[158:161], v[40:43]
	v_mfma_f32_16x16x32_bf16 v[40:43], v[178:181], v[132:135], v[162:165]
	v_mfma_f32_16x16x32_bf16 v[56:59], v[212:215], v[158:161], v[44:47]
	v_mfma_f32_16x16x32_bf16 v[44:47], v[216:219], v[132:135], v[200:203]
	v_mfma_f32_16x16x32_bf16 v[60:63], v[154:157], v[158:161], v[48:51]
	v_mfma_f32_16x16x32_bf16 v[48:51], v[220:223], v[132:135], v[188:191]
	v_mfma_f32_16x16x32_bf16 v[64:67], v[220:223], v[208:211], v[192:195]
	v_mfma_f32_16x16x32_bf16 v[36:39], v[174:177], v[204:207], v[36:39]
	v_mfma_f32_16x16x32_bf16 v[40:43], v[212:215], v[204:207], v[40:43]
	v_mfma_f32_16x16x32_bf16 v[44:47], v[154:157], v[204:207], v[44:47]
	v_mfma_f32_16x16x32_bf16 v[48:51], v[150:153], v[204:207], v[48:51]
	v_mfma_f32_16x16x32_bf16 v[64:67], v[150:153], v[158:161], v[64:67]
	s_setprio 0
	s_movk_i32 s2, 0x100
	v_cmp_gt_u32_e32 vcc, s2, v3
	s_barrier
	s_and_saveexec_b64 s[2:3], vcc
	s_cbranch_execz .LBB0_911
	s_barrier

; #define LDA8(dst, b, h) _Pragma("unroll") for (int m = 0; m < 4; ++m) _Pragma("unroll") for (int k = 0; k < 2; ++k) \
;     dst[m][k] = *(const bf16x8*)((const char*)SA8(b, h) + lds_byte8(wr * 64 + m * 16 + fr, k * 32 + fq * 8))
; #define LDB8(dst, b, h) _Pragma("unroll") for (int n = 0; n < 2; ++n) _Pragma("unroll") for (int k = 0; k < 2; ++k) \
;     dst[n][k] = *(const bf16x8*)((const char*)SB8(b, h) + lds_byte8(wc * 32 + n * 16 + fr, k * 32 + fq * 8))
; #define WAIT_L8(n) asm volatile("s_waitcnt lgkmcnt(" #n ")" ::: "memory")
; #define BAR8 __builtin_amdgcn_s_barrier()
; #define SCHED8 __builtin_amdgcn_sched_barrier(0)
;     ...
;     LDB8(B0, 0, 0); SCHED8; LDA8(At, 0, 0); STAGE8(SA8(1, 1), A, lda, brow + 128, tt + 1);
;     WAIT_L8(8); BAR8; WAIT_L8(0); MMA8(0, 0, At, B0); BAR8; SCHED8;
;     LDB8(B1, 0, 1); STAGE8(SB8(0, 0), Bt, K, bcol, tt + 2);
;     BAR8; WAIT_L8(0); MMA8(0, 1, At, B1); BAR8;
;     LDA8(At, 0, 1); STAGE8(SA8(0, 0), A, lda, brow, tt + 2);
;     BAR8; WAIT_L8(0); MMA8(1, 0, At, B0); BAR8; SCHED8;
.LBB0_1005:
	ds_read_b128 v[174:177], v171
	ds_read_b128 v[178:181], v171 offset:1024
	ds_read_b128 v[182:185], v171 offset:2048
	ds_read_b128 v[186:189], v171 offset:3072
	v_add_u32_e32 v172, 0xc000, v150
	v_lshl_add_u64 v[222:223], v[140:141], 0, s[12:13]
	v_readfirstlane_b32 s14, v172
	v_add_u32_e32 v173, 0xe000, v150
	v_lshl_add_u64 v[226:227], v[222:223], 0, s[20:21]
	s_mov_b32 m0, s14
	v_lshl_add_u64 v[236:237], v[138:139], 0, s[12:13]
	v_readfirstlane_b32 s14, v173
	ds_read_b128 v[190:193], v156
	ds_read_b128 v[194:197], v156 offset:1024
	ds_read_b128 v[198:201], v155
	ds_read_b128 v[202:205], v155 offset:1024
	ds_read_b128 v[206:209], v154
	ds_read_b128 v[210:213], v154 offset:1024
	ds_read_b128 v[214:217], v153
	ds_read_b128 v[218:221], v153 offset:1024
	global_load_lds_dwordx4 v[226:227], off
	v_lshl_add_u64 v[226:227], v[236:237], 0, s[20:21]
	s_mov_b32 m0, s14
	s_nop 0
	global_load_lds_dwordx4 v[226:227], off
	s_waitcnt lgkmcnt(8)
	s_waitcnt vmcnt(10)
	s_barrier
	s_waitcnt lgkmcnt(0)
	s_setprio 1
	s_waitcnt lgkmcnt(0)
	v_mfma_f32_16x16x32_bf16 v[128:131], v[190:193], v[174:177], v[128:131]
	v_mfma_f32_16x16x32_bf16 v[124:127], v[190:193], v[182:185], v[124:127]
	v_mfma_f32_16x16x32_bf16 v[120:123], v[198:201], v[174:177], v[120:123]
	v_mfma_f32_16x16x32_bf16 v[116:119], v[198:201], v[182:185], v[116:119]
	v_mfma_f32_16x16x32_bf16 v[112:115], v[206:209], v[174:177], v[112:115]
	v_mfma_f32_16x16x32_bf16 v[108:111], v[206:209], v[182:185], v[108:111]
	v_mfma_f32_16x16x32_bf16 v[104:107], v[214:217], v[174:177], v[104:107]
	v_mfma_f32_16x16x32_bf16 v[100:103], v[214:217], v[182:185], v[100:103]
	v_mfma_f32_16x16x32_bf16 v[128:131], v[194:197], v[178:181], v[128:131]
	v_mfma_f32_16x16x32_bf16 v[124:127], v[194:197], v[186:189], v[124:127]
	v_mfma_f32_16x16x32_bf16 v[120:123], v[202:205], v[178:181], v[120:123]
	v_mfma_f32_16x16x32_bf16 v[116:119], v[202:205], v[186:189], v[116:119]
	v_mfma_f32_16x16x32_bf16 v[112:115], v[210:213], v[178:181], v[112:115]
	v_mfma_f32_16x16x32_bf16 v[108:111], v[210:213], v[186:189], v[108:111]
	v_mfma_f32_16x16x32_bf16 v[104:107], v[218:221], v[178:181], v[104:107]
	v_mfma_f32_16x16x32_bf16 v[100:103], v[218:221], v[186:189], v[100:103]
	s_setprio 0
	s_barrier
	v_lshl_add_u64 v[246:247], v[142:143], 0, s[12:13]
	v_readfirstlane_b32 s14, v151
	v_lshl_add_u64 v[248:249], v[246:247], 0, s[40:41]
	s_mov_b32 m0, s14
	ds_read_b128 v[226:229], v168
	ds_read_b128 v[230:233], v168 offset:1024
	ds_read_b128 v[238:241], v168 offset:2048
	ds_read_b128 v[242:245], v168 offset:3072
	global_load_lds_dwordx4 v[248:249], off
	v_lshl_add_u64 v[248:249], v[144:145], 0, s[12:13]
	v_readfirstlane_b32 s14, v157
	v_lshl_add_u64 v[250:251], v[248:249], 0, s[40:41]
	s_mov_b32 m0, s14
	s_nop 0
	global_load_lds_dwordx4 v[250:251], off
	s_waitcnt vmcnt(10)
	s_barrier
	s_waitcnt lgkmcnt(0)
	s_setprio 1
	s_waitcnt lgkmcnt(0)
	v_mfma_f32_16x16x32_bf16 v[96:99], v[190:193], v[226:229], v[96:99]
	v_mfma_f32_16x16x32_bf16 v[92:95], v[190:193], v[238:241], v[92:95]
	v_mfma_f32_16x16x32_bf16 v[88:91], v[198:201], v[226:229], v[88:91]
	v_mfma_f32_16x16x32_bf16 v[84:87], v[198:201], v[238:241], v[84:87]
	v_mfma_f32_16x16x32_bf16 v[80:83], v[206:209], v[226:229], v[80:83]
	v_mfma_f32_16x16x32_bf16 v[76:79], v[206:209], v[238:241], v[76:79]
	v_mfma_f32_16x16x32_bf16 v[72:75], v[214:217], v[226:229], v[72:75]
	v_mfma_f32_16x16x32_bf16 v[68:71], v[214:217], v[238:241], v[68:71]
	v_mfma_f32_16x16x32_bf16 v[96:99], v[194:197], v[230:233], v[96:99]
	v_mfma_f32_16x16x32_bf16 v[92:95], v[194:197], v[242:245], v[92:95]
	v_mfma_f32_16x16x32_bf16 v[88:91], v[202:205], v[230:233], v[88:91]
	v_mfma_f32_16x16x32_bf16 v[84:87], v[202:205], v[242:245], v[84:87]
	v_mfma_f32_16x16x32_bf16 v[80:83], v[210:213], v[230:233], v[80:83]
	v_mfma_f32_16x16x32_bf16 v[76:79], v[210:213], v[242:245], v[76:79]
	v_mfma_f32_16x16x32_bf16 v[72:75], v[218:221], v[230:233], v[72:75]
	v_mfma_f32_16x16x32_bf16 v[68:71], v[218:221], v[242:245], v[68:71]
	s_setprio 0
	v_readfirstlane_b32 s14, v150
	v_lshl_add_u64 v[250:251], v[222:223], 0, s[42:43]
	s_mov_b32 m0, s14
	v_readfirstlane_b32 s14, v152
	s_barrier
	ds_read_b128 v[190:193], v156 offset:16384
	ds_read_b128 v[194:197], v156 offset:17408
	ds_read_b128 v[198:201], v155 offset:16384
	ds_read_b128 v[202:205], v155 offset:17408
	ds_read_b128 v[206:209], v154 offset:16384
	ds_read_b128 v[210:213], v154 offset:17408
	ds_read_b128 v[214:217], v153 offset:16384
	ds_read_b128 v[218:221], v153 offset:17408
	global_load_lds_dwordx4 v[250:251], off
	v_lshl_add_u64 v[250:251], v[236:237], 0, s[42:43]
	s_mov_b32 m0, s14
	s_nop 0
	global_load_lds_dwordx4 v[250:251], off
	s_barrier
	s_waitcnt lgkmcnt(0)
	s_setprio 1
	s_waitcnt lgkmcnt(0)
	v_mfma_f32_16x16x32_bf16 v[64:67], v[190:193], v[174:177], v[64:67]
	v_mfma_f32_16x16x32_bf16 v[60:63], v[190:193], v[182:185], v[60:63]
	v_mfma_f32_16x16x32_bf16 v[56:59], v[198:201], v[174:177], v[56:59]
	v_mfma_f32_16x16x32_bf16 v[52:55], v[198:201], v[182:185], v[52:55]
	v_mfma_f32_16x16x32_bf16 v[48:51], v[206:209], v[174:177], v[48:51]
	v_mfma_f32_16x16x32_bf16 v[44:47], v[206:209], v[182:185], v[44:47]
	v_mfma_f32_16x16x32_bf16 v[40:43], v[214:217], v[174:177], v[40:43]
	v_mfma_f32_16x16x32_bf16 v[36:39], v[214:217], v[182:185], v[36:39]
	v_mfma_f32_16x16x32_bf16 v[64:67], v[194:197], v[178:181], v[64:67]
	v_mfma_f32_16x16x32_bf16 v[60:63], v[194:197], v[186:189], v[60:63]
	v_mfma_f32_16x16x32_bf16 v[56:59], v[202:205], v[178:181], v[56:59]
	v_mfma_f32_16x16x32_bf16 v[52:55], v[202:205], v[186:189], v[52:55]
	v_mfma_f32_16x16x32_bf16 v[48:51], v[210:213], v[178:181], v[48:51]
	v_mfma_f32_16x16x32_bf16 v[44:47], v[210:213], v[186:189], v[44:47]
	v_mfma_f32_16x16x32_bf16 v[40:43], v[218:221], v[178:181], v[40:43]
	v_mfma_f32_16x16x32_bf16 v[36:39], v[218:221], v[186:189], v[36:39]
	s_setprio 0
	s_barrier
; #define LDA8(dst, b, h) _Pragma("unroll") for (int m = 0; m < 4; ++m) _Pragma("unroll") for (int k = 0; k < 2; ++k) \
;     dst[m][k] = *(const bf16x8*)((const char*)SA8(b, h) + lds_byte8(wr * 64 + m * 16 + fr, k * 32 + fq * 8))
; #define LDB8(dst, b, h) _Pragma("unroll") for (int n = 0; n < 2; ++n) _Pragma("unroll") for (int k = 0; k < 2; ++k) \
;     dst[n][k] = *(const bf16x8*)((const char*)SB8(b, h) + lds_byte8(wc * 32 + n * 16 + fr, k * 32 + fq * 8))
; #define WAIT_V8(n) asm volatile("s_waitcnt vmcnt(" #n ")" ::: "memory")
; #define WAIT_L8(n) asm volatile("s_waitcnt lgkmcnt(" #n ")" ::: "memory")
; #define BAR8 __builtin_amdgcn_s_barrier()
; #define SCHED8 __builtin_amdgcn_sched_barrier(0)
;     ...
;     STAGE8(SB8(0, 1), Bt, K, bcol + 128, tt + 2);
;     WAIT_V8(6); BAR8; MMA8(1, 1, At, B1); BAR8;
;     LDB8(B0, 1, 0); SCHED8; LDA8(At, 1, 0); STAGE8(SA8(0, 1), A, lda, brow + 128, tt + 2);
;     WAIT_L8(8); BAR8; WAIT_L8(0); MMA8(0, 0, At, B0); BAR8; SCHED8;
;     LDB8(B1, 1, 1); STAGE8(SB8(1, 0), Bt, K, bcol, tt + 3);
;     BAR8; WAIT_L8(0); MMA8(0, 1, At, B1); BAR8;
;     LDA8(At, 1, 1); STAGE8(SA8(1, 0), A, lda, brow, tt + 3);
;     BAR8; WAIT_L8(0); MMA8(1, 0, At, B0); BAR8; SCHED8;
	v_readfirstlane_b32 s14, v159
	v_lshl_add_u64 v[174:175], v[246:247], 0, s[44:45]
	s_mov_b32 m0, s14
	v_readfirstlane_b32 s14, v160
	global_load_lds_dwordx4 v[174:175], off
	v_lshl_add_u64 v[174:175], v[248:249], 0, s[44:45]
	s_mov_b32 m0, s14
	s_nop 0
	global_load_lds_dwordx4 v[174:175], off
	s_waitcnt vmcnt(10)
	s_barrier
	s_setprio 1
	v_mfma_f32_16x16x32_bf16 v[32:35], v[190:193], v[226:229], v[32:35]
	v_mfma_f32_16x16x32_bf16 v[28:31], v[190:193], v[238:241], v[28:31]
	v_mfma_f32_16x16x32_bf16 v[24:27], v[198:201], v[226:229], v[24:27]
	v_mfma_f32_16x16x32_bf16 v[20:23], v[198:201], v[238:241], v[20:23]
	v_mfma_f32_16x16x32_bf16 v[16:19], v[206:209], v[226:229], v[16:19]
	v_mfma_f32_16x16x32_bf16 v[12:15], v[206:209], v[238:241], v[12:15]
	v_mfma_f32_16x16x32_bf16 v[8:11], v[214:217], v[226:229], v[8:11]
	v_mfma_f32_16x16x32_bf16 v[4:7], v[214:217], v[238:241], v[4:7]
	v_mfma_f32_16x16x32_bf16 v[32:35], v[194:197], v[230:233], v[32:35]
	v_mfma_f32_16x16x32_bf16 v[28:31], v[194:197], v[242:245], v[28:31]
	v_mfma_f32_16x16x32_bf16 v[24:27], v[202:205], v[230:233], v[24:27]
	v_mfma_f32_16x16x32_bf16 v[20:23], v[202:205], v[242:245], v[20:23]
	v_mfma_f32_16x16x32_bf16 v[16:19], v[210:213], v[230:233], v[16:19]
	v_mfma_f32_16x16x32_bf16 v[12:15], v[210:213], v[242:245], v[12:15]
	v_mfma_f32_16x16x32_bf16 v[8:11], v[218:221], v[230:233], v[8:11]
	v_mfma_f32_16x16x32_bf16 v[4:7], v[218:221], v[242:245], v[4:7]
	s_setprio 0
	s_barrier
	ds_read_b128 v[174:177], v161
	ds_read_b128 v[178:181], v161 offset:1024
	ds_read_b128 v[182:185], v161 offset:2048
	ds_read_b128 v[186:189], v161 offset:3072
	v_readfirstlane_b32 s14, v162
	v_lshl_add_u64 v[226:227], v[222:223], 0, s[46:47]
	s_mov_b32 m0, s14
	v_readfirstlane_b32 s14, v163
	ds_read_b128 v[190:193], v156 offset:32768
	ds_read_b128 v[194:197], v156 offset:33792
	ds_read_b128 v[198:201], v155 offset:32768
	ds_read_b128 v[202:205], v155 offset:33792
	ds_read_b128 v[206:209], v154 offset:32768
	ds_read_b128 v[210:213], v154 offset:33792
	ds_read_b128 v[214:217], v153 offset:32768
	ds_read_b128 v[218:221], v153 offset:33792
	global_load_lds_dwordx4 v[226:227], off
	v_lshl_add_u64 v[226:227], v[236:237], 0, s[46:47]
	s_mov_b32 m0, s14
	s_nop 0
	global_load_lds_dwordx4 v[226:227], off
	s_waitcnt lgkmcnt(8)
	s_waitcnt vmcnt(10)
	s_barrier
	s_waitcnt lgkmcnt(0)
	s_setprio 1
	s_waitcnt lgkmcnt(0)
	v_mfma_f32_16x16x32_bf16 v[128:131], v[190:193], v[174:177], v[128:131]
	v_mfma_f32_16x16x32_bf16 v[124:127], v[190:193], v[182:185], v[124:127]
	v_mfma_f32_16x16x32_bf16 v[120:123], v[198:201], v[174:177], v[120:123]
	v_mfma_f32_16x16x32_bf16 v[116:119], v[198:201], v[182:185], v[116:119]
	v_mfma_f32_16x16x32_bf16 v[112:115], v[206:209], v[174:177], v[112:115]
	v_mfma_f32_16x16x32_bf16 v[108:111], v[206:209], v[182:185], v[108:111]
	v_mfma_f32_16x16x32_bf16 v[104:107], v[214:217], v[174:177], v[104:107]
	v_mfma_f32_16x16x32_bf16 v[100:103], v[214:217], v[182:185], v[100:103]
	v_mfma_f32_16x16x32_bf16 v[128:131], v[194:197], v[178:181], v[128:131]
	v_mfma_f32_16x16x32_bf16 v[124:127], v[194:197], v[186:189], v[124:127]
	v_mfma_f32_16x16x32_bf16 v[120:123], v[202:205], v[178:181], v[120:123]
	v_mfma_f32_16x16x32_bf16 v[116:119], v[202:205], v[186:189], v[116:119]
	v_mfma_f32_16x16x32_bf16 v[112:115], v[210:213], v[178:181], v[112:115]
	v_mfma_f32_16x16x32_bf16 v[108:111], v[210:213], v[186:189], v[108:111]
	v_mfma_f32_16x16x32_bf16 v[104:107], v[218:221], v[178:181], v[104:107]
	v_mfma_f32_16x16x32_bf16 v[100:103], v[218:221], v[186:189], v[100:103]
	s_setprio 0
	s_barrier
	v_readfirstlane_b32 s14, v164
	v_lshl_add_u64 v[250:251], v[246:247], 0, s[48:49]
	s_mov_b32 m0, s14
	v_readfirstlane_b32 s14, v165
	ds_read_b128 v[226:229], v158
	ds_read_b128 v[230:233], v158 offset:1024
	ds_read_b128 v[238:241], v158 offset:2048
	ds_read_b128 v[242:245], v158 offset:3072
	global_load_lds_dwordx4 v[250:251], off
	v_lshl_add_u64 v[250:251], v[248:249], 0, s[48:49]
	s_mov_b32 m0, s14
	s_nop 0
	global_load_lds_dwordx4 v[250:251], off
	s_waitcnt vmcnt(10)
	s_barrier
	s_waitcnt lgkmcnt(0)
	s_setprio 1
	s_waitcnt lgkmcnt(0)
	v_mfma_f32_16x16x32_bf16 v[96:99], v[190:193], v[226:229], v[96:99]
	v_mfma_f32_16x16x32_bf16 v[92:95], v[190:193], v[238:241], v[92:95]
	v_mfma_f32_16x16x32_bf16 v[88:91], v[198:201], v[226:229], v[88:91]
	v_mfma_f32_16x16x32_bf16 v[84:87], v[198:201], v[238:241], v[84:87]
	v_mfma_f32_16x16x32_bf16 v[80:83], v[206:209], v[226:229], v[80:83]
	v_mfma_f32_16x16x32_bf16 v[76:79], v[206:209], v[238:241], v[76:79]
	v_mfma_f32_16x16x32_bf16 v[72:75], v[214:217], v[226:229], v[72:75]
	v_mfma_f32_16x16x32_bf16 v[68:71], v[214:217], v[238:241], v[68:71]
	v_mfma_f32_16x16x32_bf16 v[96:99], v[194:197], v[230:233], v[96:99]
	v_mfma_f32_16x16x32_bf16 v[92:95], v[194:197], v[242:245], v[92:95]
	v_mfma_f32_16x16x32_bf16 v[88:91], v[202:205], v[230:233], v[88:91]
	v_mfma_f32_16x16x32_bf16 v[84:87], v[202:205], v[242:245], v[84:87]
	v_mfma_f32_16x16x32_bf16 v[80:83], v[210:213], v[230:233], v[80:83]
	v_mfma_f32_16x16x32_bf16 v[76:79], v[210:213], v[242:245], v[76:79]
	v_mfma_f32_16x16x32_bf16 v[72:75], v[218:221], v[230:233], v[72:75]
	v_mfma_f32_16x16x32_bf16 v[68:71], v[218:221], v[242:245], v[68:71]
	s_setprio 0
	v_readfirstlane_b32 s14, v166
	v_lshl_add_u64 v[222:223], v[222:223], 0, s[50:51]
	s_mov_b32 m0, s14
	v_readfirstlane_b32 s14, v167
	s_barrier
	ds_read_b128 v[190:193], v156 offset:49152
	ds_read_b128 v[194:197], v156 offset:50176
	ds_read_b128 v[198:201], v155 offset:49152
	ds_read_b128 v[202:205], v155 offset:50176
	ds_read_b128 v[206:209], v154 offset:49152
	ds_read_b128 v[210:213], v154 offset:50176
	ds_read_b128 v[214:217], v153 offset:49152
	ds_read_b128 v[218:221], v153 offset:50176
	global_load_lds_dwordx4 v[222:223], off
	v_lshl_add_u64 v[222:223], v[236:237], 0, s[50:51]
	s_mov_b32 m0, s14
	s_nop 0
	global_load_lds_dwordx4 v[222:223], off
	s_barrier
; #define LDA8(dst, b, h) _Pragma("unroll") for (int m = 0; m < 4; ++m) _Pragma("unroll") for (int k = 0; k < 2; ++k) \
;     dst[m][k] = *(const bf16x8*)((const char*)SA8(b, h) + lds_byte8(wr * 64 + m * 16 + fr, k * 32 + fq * 8))
; #define LDB8(dst, b, h) _Pragma("unroll") for (int n = 0; n < 2; ++n) _Pragma("unroll") for (int k = 0; k < 2; ++k) \
;     dst[n][k] = *(const bf16x8*)((const char*)SB8(b, h) + lds_byte8(wc * 32 + n * 16 + fr, k * 32 + fq * 8))
; #define WAIT_V8(n) asm volatile("s_waitcnt vmcnt(" #n ")" ::: "memory")
; #define WAIT_L8(n) asm volatile("s_waitcnt lgkmcnt(" #n ")" ::: "memory")
; #define BAR8 __builtin_amdgcn_s_barrier()
; #define SCHED8 __builtin_amdgcn_sched_barrier(0)
;     ...
;     WAIT_L8(8); BAR8; WAIT_L8(0); MMA8(0, 0, At, B0); BAR8; SCHED8;
;     LDB8(B1, 1, 1); STAGE8(SB8(1, 0), Bt, K, bcol, tt + 3);
;     BAR8; WAIT_L8(0); MMA8(0, 1, At, B1); BAR8;
;     LDA8(At, 1, 1); STAGE8(SA8(1, 0), A, lda, brow, tt + 3);
;     BAR8; WAIT_L8(0); MMA8(1, 0, At, B0); BAR8; SCHED8;
;     STAGE8(SB8(1, 1), Bt, K, bcol + 128, tt + 3);
;     WAIT_V8(6); BAR8; MMA8(1, 1, At, B1); BAR8;
;   }
;   { LDB8(B0, 0, 0); LDA8(At, 0, 0); STAGE8(SA8(1, 1), A, lda, brow + 128, nt - 1);
;     BAR8; WAIT_L8(0); MMA8(0, 0, At, B0); BAR8;
;     LDB8(B1, 0, 1); BAR8; WAIT_L8(0); MMA8(0, 1, At, B1); BAR8;
;     LDA8(At, 0, 1); WAIT_V8(4); BAR8; WAIT_L8(0); MMA8(1, 0, At, B0); MMA8(1, 1, At, B1); BAR8; }
	s_waitcnt lgkmcnt(0)
	s_setprio 1
	s_waitcnt lgkmcnt(0)
	v_mfma_f32_16x16x32_bf16 v[64:67], v[190:193], v[174:177], v[64:67]
	v_mfma_f32_16x16x32_bf16 v[60:63], v[190:193], v[182:185], v[60:63]
	v_mfma_f32_16x16x32_bf16 v[56:59], v[198:201], v[174:177], v[56:59]
	v_mfma_f32_16x16x32_bf16 v[52:55], v[198:201], v[182:185], v[52:55]
	v_mfma_f32_16x16x32_bf16 v[48:51], v[206:209], v[174:177], v[48:51]
	v_mfma_f32_16x16x32_bf16 v[44:47], v[206:209], v[182:185], v[44:47]
	v_mfma_f32_16x16x32_bf16 v[40:43], v[214:217], v[174:177], v[40:43]
	v_mfma_f32_16x16x32_bf16 v[36:39], v[214:217], v[182:185], v[36:39]
	v_mfma_f32_16x16x32_bf16 v[64:67], v[194:197], v[178:181], v[64:67]
	v_mfma_f32_16x16x32_bf16 v[60:63], v[194:197], v[186:189], v[60:63]
	v_mfma_f32_16x16x32_bf16 v[56:59], v[202:205], v[178:181], v[56:59]
	v_mfma_f32_16x16x32_bf16 v[52:55], v[202:205], v[186:189], v[52:55]
	v_mfma_f32_16x16x32_bf16 v[48:51], v[210:213], v[178:181], v[48:51]
	v_mfma_f32_16x16x32_bf16 v[44:47], v[210:213], v[186:189], v[44:47]
	v_mfma_f32_16x16x32_bf16 v[40:43], v[218:221], v[178:181], v[40:43]
	v_mfma_f32_16x16x32_bf16 v[36:39], v[218:221], v[186:189], v[36:39]
	s_setprio 0
	s_barrier
	v_readfirstlane_b32 s14, v169
	v_lshl_add_u64 v[174:175], v[246:247], 0, s[52:53]
	s_mov_b32 m0, s14
	v_readfirstlane_b32 s14, v170
	global_load_lds_dwordx4 v[174:175], off
	v_lshl_add_u64 v[174:175], v[248:249], 0, s[52:53]
	s_mov_b32 m0, s14
	s_nop 0
	global_load_lds_dwordx4 v[174:175], off
	s_waitcnt vmcnt(10)
	s_barrier
	s_setprio 1
	v_mfma_f32_16x16x32_bf16 v[32:35], v[190:193], v[226:229], v[32:35]
	v_mfma_f32_16x16x32_bf16 v[28:31], v[190:193], v[238:241], v[28:31]
	v_mfma_f32_16x16x32_bf16 v[24:27], v[198:201], v[226:229], v[24:27]
	v_mfma_f32_16x16x32_bf16 v[20:23], v[198:201], v[238:241], v[20:23]
	v_mfma_f32_16x16x32_bf16 v[16:19], v[206:209], v[226:229], v[16:19]
	v_mfma_f32_16x16x32_bf16 v[12:15], v[206:209], v[238:241], v[12:15]
	v_mfma_f32_16x16x32_bf16 v[8:11], v[214:217], v[226:229], v[8:11]
	v_mfma_f32_16x16x32_bf16 v[4:7], v[214:217], v[238:241], v[4:7]
	v_mfma_f32_16x16x32_bf16 v[32:35], v[194:197], v[230:233], v[32:35]
	v_mfma_f32_16x16x32_bf16 v[28:31], v[194:197], v[242:245], v[28:31]
	v_mfma_f32_16x16x32_bf16 v[24:27], v[202:205], v[230:233], v[24:27]
	v_mfma_f32_16x16x32_bf16 v[20:23], v[202:205], v[242:245], v[20:23]
	v_mfma_f32_16x16x32_bf16 v[16:19], v[210:213], v[230:233], v[16:19]
	v_mfma_f32_16x16x32_bf16 v[12:15], v[210:213], v[242:245], v[12:15]
	v_mfma_f32_16x16x32_bf16 v[8:11], v[218:221], v[230:233], v[8:11]
	v_mfma_f32_16x16x32_bf16 v[4:7], v[218:221], v[242:245], v[4:7]
	s_setprio 0
	s_add_i32 s1, s1, 2
	s_add_u32 s12, s12, 0x100
	s_addc_u32 s13, s13, 0
	s_cmp_lt_u32 s1, 12
	s_barrier
	s_cbranch_scc1 .LBB0_1005
	s_add_u32 s8, s8, 0x40780
	s_addc_u32 s9, s9, 0
	v_lshl_add_u64 v[132:133], s[8:9], 0, v[132:133]
	v_readfirstlane_b32 s1, v172
	v_lshl_add_u64 v[0:1], v[0:1], 1, v[132:133]
	s_mov_b32 m0, s1
	ds_read_b128 v[138:141], v171
	ds_read_b128 v[142:145], v171 offset:1024
	ds_read_b128 v[162:165], v171 offset:2048
	ds_read_b128 v[174:177], v171 offset:3072
	ds_read_b128 v[178:181], v156
	ds_read_b128 v[182:185], v156 offset:1024
	ds_read_b128 v[186:189], v155
	ds_read_b128 v[190:193], v155 offset:1024
	ds_read_b128 v[194:197], v154
	ds_read_b128 v[198:201], v154 offset:1024
	ds_read_b128 v[202:205], v153
	ds_read_b128 v[206:209], v153 offset:1024
	global_load_lds_dwordx4 v[0:1], off
	v_lshl_add_u64 v[0:1], s[8:9], 0, v[136:137]
	v_readfirstlane_b32 s1, v173
	v_lshl_add_u64 v[0:1], v[134:135], 1, v[0:1]
	s_mov_b32 m0, s1
	s_nop 0
	global_load_lds_dwordx4 v[0:1], off
	s_waitcnt vmcnt(10)
	s_barrier
	s_waitcnt lgkmcnt(0)
	s_setprio 1
	s_waitcnt lgkmcnt(0)
	v_mfma_f32_16x16x32_bf16 v[128:131], v[178:181], v[138:141], v[128:131]
	v_mfma_f32_16x16x32_bf16 v[124:127], v[178:181], v[162:165], v[124:127]
	v_mfma_f32_16x16x32_bf16 v[120:123], v[186:189], v[138:141], v[120:123]
	v_mfma_f32_16x16x32_bf16 v[112:115], v[194:197], v[138:141], v[112:115]
	v_mfma_f32_16x16x32_bf16 v[128:131], v[182:185], v[142:145], v[128:131]
	v_mfma_f32_16x16x32_bf16 v[124:127], v[182:185], v[174:177], v[124:127]
	v_mfma_f32_16x16x32_bf16 v[120:123], v[190:193], v[142:145], v[120:123]
	v_mfma_f32_16x16x32_bf16 v[116:119], v[186:189], v[162:165], v[116:119]
	v_mfma_f32_16x16x32_bf16 v[112:115], v[198:201], v[142:145], v[112:115]
	v_mfma_f32_16x16x32_bf16 v[108:111], v[194:197], v[162:165], v[108:111]
	v_mfma_f32_16x16x32_bf16 v[104:107], v[202:205], v[138:141], v[104:107]
	v_mfma_f32_16x16x32_bf16 v[100:103], v[202:205], v[162:165], v[100:103]
	v_mfma_f32_16x16x32_bf16 v[132:135], v[190:193], v[174:177], v[116:119]
	v_mfma_f32_16x16x32_bf16 v[170:173], v[198:201], v[174:177], v[108:111]
	v_mfma_f32_16x16x32_bf16 v[210:213], v[206:209], v[142:145], v[104:107]
	v_mfma_f32_16x16x32_bf16 v[214:217], v[206:209], v[174:177], v[100:103]
	s_setprio 0
	s_barrier
	s_nop 1
	ds_read_b128 v[100:103], v168
	ds_read_b128 v[104:107], v168 offset:1024
	ds_read_b128 v[108:111], v168 offset:2048
	ds_read_b128 v[116:119], v168 offset:3072
	s_waitcnt vmcnt(8)
	s_barrier
; #define LDA8(dst, b, h) _Pragma("unroll") for (int m = 0; m < 4; ++m) _Pragma("unroll") for (int k = 0; k < 2; ++k) \
;     dst[m][k] = *(const bf16x8*)((const char*)SA8(b, h) + lds_byte8(wr * 64 + m * 16 + fr, k * 32 + fq * 8))
; #define LDB8(dst, b, h) _Pragma("unroll") for (int n = 0; n < 2; ++n) _Pragma("unroll") for (int k = 0; k < 2; ++k) \
;     dst[n][k] = *(const bf16x8*)((const char*)SB8(b, h) + lds_byte8(wc * 32 + n * 16 + fr, k * 32 + fq * 8))
; #define WAIT_V8(n) asm volatile("s_waitcnt vmcnt(" #n ")" ::: "memory")
; #define WAIT_L8(n) asm volatile("s_waitcnt lgkmcnt(" #n ")" ::: "memory")
; #define BAR8 __builtin_amdgcn_s_barrier()
;     ...
;     LDB8(B1, 0, 1); BAR8; WAIT_L8(0); MMA8(0, 1, At, B1); BAR8;
;     LDA8(At, 0, 1); WAIT_V8(4); BAR8; WAIT_L8(0); MMA8(1, 0, At, B0); MMA8(1, 1, At, B1); BAR8; }
;   { LDB8(B0, 1, 0); LDA8(At, 1, 0); WAIT_V8(2); BAR8; WAIT_L8(0); MMA8(0, 0, At, B0); BAR8;
	s_waitcnt lgkmcnt(0)
	s_setprio 1
	s_waitcnt lgkmcnt(0)
	v_mfma_f32_16x16x32_bf16 v[80:83], v[194:197], v[100:103], v[80:83]
	v_mfma_f32_16x16x32_bf16 v[76:79], v[194:197], v[108:111], v[76:79]
	v_mfma_f32_16x16x32_bf16 v[72:75], v[202:205], v[100:103], v[72:75]
	v_mfma_f32_16x16x32_bf16 v[68:71], v[202:205], v[108:111], v[68:71]
	v_mfma_f32_16x16x32_bf16 v[96:99], v[178:181], v[100:103], v[96:99]
	v_mfma_f32_16x16x32_bf16 v[92:95], v[178:181], v[108:111], v[92:95]
	v_mfma_f32_16x16x32_bf16 v[88:91], v[186:189], v[100:103], v[88:91]
	v_mfma_f32_16x16x32_bf16 v[84:87], v[186:189], v[108:111], v[84:87]
	v_mfma_f32_16x16x32_bf16 v[80:83], v[198:201], v[104:107], v[80:83]
	v_mfma_f32_16x16x32_bf16 v[76:79], v[198:201], v[116:119], v[76:79]
	v_mfma_f32_16x16x32_bf16 v[72:75], v[206:209], v[104:107], v[72:75]
	v_mfma_f32_16x16x32_bf16 v[68:71], v[206:209], v[116:119], v[68:71]
	v_mfma_f32_16x16x32_bf16 v[166:169], v[182:185], v[104:107], v[96:99]
	v_mfma_f32_16x16x32_bf16 v[178:181], v[182:185], v[116:119], v[92:95]
	v_mfma_f32_16x16x32_bf16 v[182:185], v[190:193], v[104:107], v[88:91]
	v_mfma_f32_16x16x32_bf16 v[186:189], v[190:193], v[116:119], v[84:87]
	s_setprio 0
	s_barrier
	s_nop 0
	ds_read_b128 v[84:87], v156 offset:16384
	ds_read_b128 v[88:91], v156 offset:17408
	ds_read_b128 v[92:95], v155 offset:16384
	ds_read_b128 v[96:99], v155 offset:17408
	ds_read_b128 v[190:193], v154 offset:16384
	ds_read_b128 v[194:197], v154 offset:17408
	ds_read_b128 v[198:201], v153 offset:16384
	ds_read_b128 v[202:205], v153 offset:17408
	s_waitcnt vmcnt(4)
	s_barrier
	s_waitcnt lgkmcnt(0)
	s_setprio 1
	s_waitcnt lgkmcnt(0)
	v_mfma_f32_16x16x32_bf16 v[64:67], v[84:87], v[138:141], v[64:67]
	v_mfma_f32_16x16x32_bf16 v[60:63], v[84:87], v[162:165], v[60:63]
	v_mfma_f32_16x16x32_bf16 v[56:59], v[92:95], v[138:141], v[56:59]
	v_mfma_f32_16x16x32_bf16 v[52:55], v[92:95], v[162:165], v[52:55]
	v_mfma_f32_16x16x32_bf16 v[48:51], v[190:193], v[138:141], v[48:51]
	v_mfma_f32_16x16x32_bf16 v[44:47], v[190:193], v[162:165], v[44:47]
	v_mfma_f32_16x16x32_bf16 v[40:43], v[198:201], v[138:141], v[40:43]
	v_mfma_f32_16x16x32_bf16 v[36:39], v[198:201], v[162:165], v[36:39]
	v_mfma_f32_16x16x32_bf16 v[64:67], v[88:91], v[142:145], v[64:67]
	v_mfma_f32_16x16x32_bf16 v[60:63], v[88:91], v[174:177], v[60:63]
	v_mfma_f32_16x16x32_bf16 v[56:59], v[96:99], v[142:145], v[56:59]
	v_mfma_f32_16x16x32_bf16 v[52:55], v[96:99], v[174:177], v[52:55]
	v_mfma_f32_16x16x32_bf16 v[48:51], v[194:197], v[142:145], v[48:51]
	v_mfma_f32_16x16x32_bf16 v[44:47], v[194:197], v[174:177], v[44:47]
	v_mfma_f32_16x16x32_bf16 v[40:43], v[202:205], v[142:145], v[40:43]
	v_mfma_f32_16x16x32_bf16 v[36:39], v[202:205], v[174:177], v[36:39]
	s_setprio 0
	s_setprio 1
	v_mfma_f32_16x16x32_bf16 v[32:35], v[84:87], v[100:103], v[32:35]
	v_mfma_f32_16x16x32_bf16 v[28:31], v[84:87], v[108:111], v[28:31]
	v_mfma_f32_16x16x32_bf16 v[24:27], v[92:95], v[100:103], v[24:27]
	v_mfma_f32_16x16x32_bf16 v[20:23], v[92:95], v[108:111], v[20:23]
	v_mfma_f32_16x16x32_bf16 v[16:19], v[190:193], v[100:103], v[16:19]
	v_mfma_f32_16x16x32_bf16 v[12:15], v[190:193], v[108:111], v[12:15]
	v_mfma_f32_16x16x32_bf16 v[8:11], v[198:201], v[100:103], v[8:11]
	v_mfma_f32_16x16x32_bf16 v[4:7], v[198:201], v[108:111], v[4:7]
	v_mfma_f32_16x16x32_bf16 v[136:139], v[88:91], v[104:107], v[32:35]
	v_mfma_f32_16x16x32_bf16 v[140:143], v[88:91], v[116:119], v[28:31]
	v_mfma_f32_16x16x32_bf16 v[162:165], v[96:99], v[104:107], v[24:27]
	v_mfma_f32_16x16x32_bf16 v[174:177], v[96:99], v[116:119], v[20:23]
	v_mfma_f32_16x16x32_bf16 v[206:209], v[194:197], v[104:107], v[16:19]
	v_mfma_f32_16x16x32_bf16 v[190:193], v[194:197], v[116:119], v[12:15]
	v_mfma_f32_16x16x32_bf16 v[194:197], v[202:205], v[104:107], v[8:11]
	v_mfma_f32_16x16x32_bf16 v[198:201], v[202:205], v[116:119], v[4:7]
	s_setprio 0
	s_barrier
	ds_read_b128 v[202:205], v161
	ds_read_b128 v[218:221], v161 offset:1024
	ds_read_b128 v[226:229], v161 offset:2048
	ds_read_b128 v[230:233], v161 offset:3072
	ds_read_b128 v[8:11], v156 offset:32768
	ds_read_b128 v[12:15], v156 offset:33792
	ds_read_b128 v[16:19], v155 offset:32768
	ds_read_b128 v[24:27], v155 offset:33792
	ds_read_b128 v[28:31], v154 offset:32768
	ds_read_b128 v[32:35], v154 offset:33792
	ds_read_b128 v[238:241], v153 offset:32768
	ds_read_b128 v[242:245], v153 offset:33792
	s_waitcnt vmcnt(2)
	s_barrier
; #define LDA8(dst, b, h) _Pragma("unroll") for (int m = 0; m < 4; ++m) _Pragma("unroll") for (int k = 0; k < 2; ++k) \
;     dst[m][k] = *(const bf16x8*)((const char*)SA8(b, h) + lds_byte8(wr * 64 + m * 16 + fr, k * 32 + fq * 8))
; #define LDB8(dst, b, h) _Pragma("unroll") for (int n = 0; n < 2; ++n) _Pragma("unroll") for (int k = 0; k < 2; ++k) \
;     dst[n][k] = *(const bf16x8*)((const char*)SB8(b, h) + lds_byte8(wc * 32 + n * 16 + fr, k * 32 + fq * 8))
; #define WAIT_V8(n) asm volatile("s_waitcnt vmcnt(" #n ")" ::: "memory")
; #define WAIT_L8(n) asm volatile("s_waitcnt lgkmcnt(" #n ")" ::: "memory")
; #define BAR8 __builtin_amdgcn_s_barrier()
;     ...
;   { LDB8(B0, 1, 0); LDA8(At, 1, 0); WAIT_V8(2); BAR8; WAIT_L8(0); MMA8(0, 0, At, B0); BAR8;
;     LDB8(B1, 1, 1); WAIT_V8(0); BAR8; WAIT_L8(0); MMA8(0, 1, At, B1); BAR8;
;     LDA8(At, 1, 1); BAR8; WAIT_L8(0); MMA8(1, 0, At, B0); MMA8(1, 1, At, B1); BAR8; }
;   if (wr == 0) BAR8;
;   __syncthreads();
;     ...
;   if (t < 256) {
;     float rs = 1.f;
;     if (e.ss) {
;       const float* sp = e.ss + (size_t)(m0 + t) * e.nss;
;       float s = 0.f;
;       for (int i = 0; i < e.nss; ++i) s += sp[i];
;       rs = rsqrtf(s * e.inv_n + EPS);
;     }
;     ((float*)(smem + SMEM_RSTD))[t] = rs;
	s_waitcnt lgkmcnt(0)
	s_setprio 1
	s_waitcnt lgkmcnt(0)
	v_mfma_f32_16x16x32_bf16 v[4:7], v[8:11], v[202:205], v[128:131]
	v_mfma_f32_16x16x32_bf16 v[104:107], v[12:15], v[218:221], v[4:7]
	v_mfma_f32_16x16x32_bf16 v[4:7], v[8:11], v[226:229], v[124:127]
	v_mfma_f32_16x16x32_bf16 v[116:119], v[12:15], v[230:233], v[4:7]
	v_mfma_f32_16x16x32_bf16 v[4:7], v[16:19], v[202:205], v[120:123]
	v_mfma_f32_16x16x32_bf16 v[100:103], v[24:27], v[218:221], v[4:7]
	v_mfma_f32_16x16x32_bf16 v[4:7], v[16:19], v[226:229], v[132:135]
	v_mfma_f32_16x16x32_bf16 v[108:111], v[24:27], v[230:233], v[4:7]
	v_mfma_f32_16x16x32_bf16 v[4:7], v[28:31], v[202:205], v[112:115]
	v_mfma_f32_16x16x32_bf16 v[92:95], v[32:35], v[218:221], v[4:7]
	v_mfma_f32_16x16x32_bf16 v[4:7], v[28:31], v[226:229], v[170:173]
	v_mfma_f32_16x16x32_bf16 v[96:99], v[32:35], v[230:233], v[4:7]
	v_mfma_f32_16x16x32_bf16 v[4:7], v[238:241], v[202:205], v[210:213]
	v_mfma_f32_16x16x32_bf16 v[84:87], v[242:245], v[218:221], v[4:7]
	v_mfma_f32_16x16x32_bf16 v[4:7], v[238:241], v[226:229], v[214:217]
	v_mfma_f32_16x16x32_bf16 v[88:91], v[242:245], v[230:233], v[4:7]
	s_setprio 0
	s_barrier
	ds_read_b128 v[132:135], v158
	ds_read_b128 v[170:173], v158 offset:1024
	ds_read_b128 v[210:213], v158 offset:2048
	ds_read_b128 v[158:161], v158 offset:3072
	s_waitcnt vmcnt(0)
	s_barrier
	s_waitcnt lgkmcnt(0)
	s_setprio 1
	s_waitcnt lgkmcnt(0)
	v_mfma_f32_16x16x32_bf16 v[4:7], v[8:11], v[132:135], v[166:169]
	v_mfma_f32_16x16x32_bf16 v[8:11], v[8:11], v[210:213], v[178:181]
	v_mfma_f32_16x16x32_bf16 v[4:7], v[12:15], v[170:173], v[4:7]
	v_mfma_f32_16x16x32_bf16 v[20:23], v[12:15], v[158:161], v[8:11]
	v_mfma_f32_16x16x32_bf16 v[8:11], v[16:19], v[132:135], v[182:185]
	v_mfma_f32_16x16x32_bf16 v[12:15], v[16:19], v[210:213], v[186:189]
	v_mfma_f32_16x16x32_bf16 v[8:11], v[24:27], v[170:173], v[8:11]
	v_mfma_f32_16x16x32_bf16 v[24:27], v[24:27], v[158:161], v[12:15]
	v_mfma_f32_16x16x32_bf16 v[12:15], v[28:31], v[132:135], v[80:83]
	v_mfma_f32_16x16x32_bf16 v[16:19], v[28:31], v[210:213], v[76:79]
	v_mfma_f32_16x16x32_bf16 v[12:15], v[32:35], v[170:173], v[12:15]
	v_mfma_f32_16x16x32_bf16 v[28:31], v[32:35], v[158:161], v[16:19]
	v_mfma_f32_16x16x32_bf16 v[16:19], v[238:241], v[132:135], v[72:75]
	v_mfma_f32_16x16x32_bf16 v[32:35], v[238:241], v[210:213], v[68:71]
	v_mfma_f32_16x16x32_bf16 v[16:19], v[242:245], v[170:173], v[16:19]
	v_mfma_f32_16x16x32_bf16 v[32:35], v[242:245], v[158:161], v[32:35]
	s_setprio 0
	s_barrier
	ds_read_b128 v[166:169], v156 offset:49152
	ds_read_b128 v[178:181], v156 offset:50176
	ds_read_b128 v[182:185], v155 offset:49152
	ds_read_b128 v[186:189], v155 offset:50176
	ds_read_b128 v[214:217], v154 offset:49152
	ds_read_b128 v[154:157], v154 offset:50176
	ds_read_b128 v[238:241], v153 offset:49152
	ds_read_b128 v[150:153], v153 offset:50176
	s_barrier
	s_waitcnt lgkmcnt(0)
	s_setprio 1
	s_waitcnt lgkmcnt(0)
	v_mfma_f32_16x16x32_bf16 v[64:67], v[166:169], v[202:205], v[64:67]
	v_mfma_f32_16x16x32_bf16 v[60:63], v[166:169], v[226:229], v[60:63]
	v_mfma_f32_16x16x32_bf16 v[56:59], v[182:185], v[202:205], v[56:59]
	v_mfma_f32_16x16x32_bf16 v[52:55], v[182:185], v[226:229], v[52:55]
	v_mfma_f32_16x16x32_bf16 v[48:51], v[214:217], v[202:205], v[48:51]
	v_mfma_f32_16x16x32_bf16 v[44:47], v[214:217], v[226:229], v[44:47]
	v_mfma_f32_16x16x32_bf16 v[40:43], v[238:241], v[202:205], v[40:43]
	v_mfma_f32_16x16x32_bf16 v[36:39], v[238:241], v[226:229], v[36:39]
	v_mfma_f32_16x16x32_bf16 v[128:131], v[178:181], v[218:221], v[64:67]
	v_mfma_f32_16x16x32_bf16 v[124:127], v[178:181], v[230:233], v[60:63]
	v_mfma_f32_16x16x32_bf16 v[120:123], v[186:189], v[218:221], v[56:59]
	v_mfma_f32_16x16x32_bf16 v[112:115], v[186:189], v[230:233], v[52:55]
	v_mfma_f32_16x16x32_bf16 v[80:83], v[154:157], v[218:221], v[48:51]
	v_mfma_f32_16x16x32_bf16 v[76:79], v[154:157], v[230:233], v[44:47]
	v_mfma_f32_16x16x32_bf16 v[72:75], v[150:153], v[218:221], v[40:43]
	v_mfma_f32_16x16x32_bf16 v[68:71], v[150:153], v[230:233], v[36:39]
	s_setprio 0
	s_setprio 1
	v_mfma_f32_16x16x32_bf16 v[36:39], v[166:169], v[132:135], v[136:139]
	v_mfma_f32_16x16x32_bf16 v[64:67], v[178:181], v[170:173], v[36:39]
	v_mfma_f32_16x16x32_bf16 v[36:39], v[166:169], v[210:213], v[140:143]
	v_mfma_f32_16x16x32_bf16 v[60:63], v[178:181], v[158:161], v[36:39]
	v_mfma_f32_16x16x32_bf16 v[36:39], v[182:185], v[132:135], v[162:165]
	v_mfma_f32_16x16x32_bf16 v[56:59], v[186:189], v[170:173], v[36:39]
	v_mfma_f32_16x16x32_bf16 v[36:39], v[182:185], v[210:213], v[174:177]
	v_mfma_f32_16x16x32_bf16 v[52:55], v[186:189], v[158:161], v[36:39]
	v_mfma_f32_16x16x32_bf16 v[36:39], v[214:217], v[132:135], v[206:209]
	v_mfma_f32_16x16x32_bf16 v[48:51], v[154:157], v[170:173], v[36:39]
	v_mfma_f32_16x16x32_bf16 v[36:39], v[214:217], v[210:213], v[190:193]
	v_mfma_f32_16x16x32_bf16 v[44:47], v[154:157], v[158:161], v[36:39]
	v_mfma_f32_16x16x32_bf16 v[36:39], v[238:241], v[132:135], v[194:197]
	v_mfma_f32_16x16x32_bf16 v[40:43], v[150:153], v[170:173], v[36:39]
	v_mfma_f32_16x16x32_bf16 v[36:39], v[238:241], v[210:213], v[198:201]
	v_mfma_f32_16x16x32_bf16 v[36:39], v[150:153], v[158:161], v[36:39]
	s_setprio 0
	s_movk_i32 s1, 0x100
	v_cmp_gt_u32_e32 vcc, s1, v3
	s_barrier
	s_and_saveexec_b64 s[8:9], vcc
	s_cbranch_execz .LBB0_1008
	s_barrier

; #define LDA8(dst, b, h) _Pragma("unroll") for (int m = 0; m < 4; ++m) _Pragma("unroll") for (int k = 0; k < 2; ++k) \
;     dst[m][k] = *(const bf16x8*)((const char*)SA8(b, h) + lds_byte8(wr * 64 + m * 16 + fr, k * 32 + fq * 8))
; #define LDB8(dst, b, h) _Pragma("unroll") for (int n = 0; n < 2; ++n) _Pragma("unroll") for (int k = 0; k < 2; ++k) \
;     dst[n][k] = *(const bf16x8*)((const char*)SB8(b, h) + lds_byte8(wc * 32 + n * 16 + fr, k * 32 + fq * 8))
; #define WAIT_V8(n) asm volatile("s_waitcnt vmcnt(" #n ")" ::: "memory")
; #define WAIT_L8(n) asm volatile("s_waitcnt lgkmcnt(" #n ")" ::: "memory")
; #define BAR8 __builtin_amdgcn_s_barrier()
; #define SCHED8 __builtin_amdgcn_sched_barrier(0)
;     ...
;   for (int tt = 0; tt < nt - 2; tt += 2) {
;     LDB8(B0, 0, 0); SCHED8; LDA8(At, 0, 0); STAGE8(SA8(1, 1), A, lda, brow + 128, tt + 1);
;     WAIT_L8(8); BAR8; WAIT_L8(0); MMA8(0, 0, At, B0); BAR8; SCHED8;
;     LDB8(B1, 0, 1); STAGE8(SB8(0, 0), Bt, K, bcol, tt + 2);
;     BAR8; WAIT_L8(0); MMA8(0, 1, At, B1); BAR8;
;     LDA8(At, 0, 1); STAGE8(SA8(0, 0), A, lda, brow, tt + 2);
;     BAR8; WAIT_L8(0); MMA8(1, 0, At, B0); BAR8; SCHED8;
;     STAGE8(SB8(0, 1), Bt, K, bcol + 128, tt + 2);
;     WAIT_V8(6); BAR8; MMA8(1, 1, At, B1); BAR8;
.LBB0_1015:
	ds_read_b128 v[174:177], v171
	ds_read_b128 v[178:181], v171 offset:1024
	ds_read_b128 v[182:185], v171 offset:2048
	ds_read_b128 v[186:189], v171 offset:3072
	v_add_u32_e32 v172, 0xc000, v150
	v_lshl_add_u64 v[222:223], v[140:141], 0, s[12:13]
	v_readfirstlane_b32 s15, v172
	v_add_u32_e32 v173, 0xe000, v150
	v_lshl_add_u64 v[226:227], v[222:223], 0, s[34:35]
	s_mov_b32 m0, s15
	v_lshl_add_u64 v[236:237], v[138:139], 0, s[12:13]
	v_readfirstlane_b32 s15, v173
	ds_read_b128 v[190:193], v156
	ds_read_b128 v[194:197], v156 offset:1024
	ds_read_b128 v[198:201], v155
	ds_read_b128 v[202:205], v155 offset:1024
	ds_read_b128 v[206:209], v154
	ds_read_b128 v[210:213], v154 offset:1024
	ds_read_b128 v[214:217], v153
	ds_read_b128 v[218:221], v153 offset:1024
	global_load_lds_dwordx4 v[226:227], off
	v_lshl_add_u64 v[226:227], v[236:237], 0, s[34:35]
	s_mov_b32 m0, s15
	s_nop 0
	global_load_lds_dwordx4 v[226:227], off
	s_waitcnt lgkmcnt(8)
	s_waitcnt vmcnt(10)
	s_barrier
	s_waitcnt lgkmcnt(0)
	s_setprio 1
	s_waitcnt lgkmcnt(0)
	v_mfma_f32_16x16x32_f16 v[128:131], v[190:193], v[174:177], v[128:131]
	v_mfma_f32_16x16x32_f16 v[124:127], v[190:193], v[182:185], v[124:127]
	v_mfma_f32_16x16x32_f16 v[120:123], v[198:201], v[174:177], v[120:123]
	v_mfma_f32_16x16x32_f16 v[116:119], v[198:201], v[182:185], v[116:119]
	v_mfma_f32_16x16x32_f16 v[112:115], v[206:209], v[174:177], v[112:115]
	v_mfma_f32_16x16x32_f16 v[108:111], v[206:209], v[182:185], v[108:111]
	v_mfma_f32_16x16x32_f16 v[104:107], v[214:217], v[174:177], v[104:107]
	v_mfma_f32_16x16x32_f16 v[100:103], v[214:217], v[182:185], v[100:103]
	v_mfma_f32_16x16x32_f16 v[128:131], v[194:197], v[178:181], v[128:131]
	v_mfma_f32_16x16x32_f16 v[124:127], v[194:197], v[186:189], v[124:127]
	v_mfma_f32_16x16x32_f16 v[120:123], v[202:205], v[178:181], v[120:123]
	v_mfma_f32_16x16x32_f16 v[116:119], v[202:205], v[186:189], v[116:119]
	v_mfma_f32_16x16x32_f16 v[112:115], v[210:213], v[178:181], v[112:115]
	v_mfma_f32_16x16x32_f16 v[108:111], v[210:213], v[186:189], v[108:111]
	v_mfma_f32_16x16x32_f16 v[104:107], v[218:221], v[178:181], v[104:107]
	v_mfma_f32_16x16x32_f16 v[100:103], v[218:221], v[186:189], v[100:103]
	s_setprio 0
	s_barrier
	v_lshl_add_u64 v[246:247], v[142:143], 0, s[12:13]
	v_readfirstlane_b32 s15, v151
	v_lshl_add_u64 v[248:249], v[246:247], 0, s[40:41]
	s_mov_b32 m0, s15
	ds_read_b128 v[226:229], v168
	ds_read_b128 v[230:233], v168 offset:1024
	ds_read_b128 v[238:241], v168 offset:2048
	ds_read_b128 v[242:245], v168 offset:3072
	global_load_lds_dwordx4 v[248:249], off
	v_lshl_add_u64 v[248:249], v[144:145], 0, s[12:13]
	v_readfirstlane_b32 s15, v157
	v_lshl_add_u64 v[250:251], v[248:249], 0, s[40:41]
	s_mov_b32 m0, s15
	s_nop 0
	global_load_lds_dwordx4 v[250:251], off
	s_waitcnt vmcnt(10)
	s_barrier
	s_waitcnt lgkmcnt(0)
	s_setprio 1
	s_waitcnt lgkmcnt(0)
	v_mfma_f32_16x16x32_f16 v[96:99], v[190:193], v[226:229], v[96:99]
	v_mfma_f32_16x16x32_f16 v[92:95], v[190:193], v[238:241], v[92:95]
	v_mfma_f32_16x16x32_f16 v[88:91], v[198:201], v[226:229], v[88:91]
	v_mfma_f32_16x16x32_f16 v[84:87], v[198:201], v[238:241], v[84:87]
	v_mfma_f32_16x16x32_f16 v[80:83], v[206:209], v[226:229], v[80:83]
	v_mfma_f32_16x16x32_f16 v[76:79], v[206:209], v[238:241], v[76:79]
	v_mfma_f32_16x16x32_f16 v[72:75], v[214:217], v[226:229], v[72:75]
	v_mfma_f32_16x16x32_f16 v[68:71], v[214:217], v[238:241], v[68:71]
	v_mfma_f32_16x16x32_f16 v[96:99], v[194:197], v[230:233], v[96:99]
	v_mfma_f32_16x16x32_f16 v[92:95], v[194:197], v[242:245], v[92:95]
	v_mfma_f32_16x16x32_f16 v[88:91], v[202:205], v[230:233], v[88:91]
	v_mfma_f32_16x16x32_f16 v[84:87], v[202:205], v[242:245], v[84:87]
	v_mfma_f32_16x16x32_f16 v[80:83], v[210:213], v[230:233], v[80:83]
	v_mfma_f32_16x16x32_f16 v[76:79], v[210:213], v[242:245], v[76:79]
	v_mfma_f32_16x16x32_f16 v[72:75], v[218:221], v[230:233], v[72:75]
	v_mfma_f32_16x16x32_f16 v[68:71], v[218:221], v[242:245], v[68:71]
	s_setprio 0
	v_readfirstlane_b32 s15, v150
	v_lshl_add_u64 v[250:251], v[222:223], 0, s[10:11]
	s_mov_b32 m0, s15
	v_readfirstlane_b32 s15, v152
	s_barrier
	ds_read_b128 v[190:193], v156 offset:16384
	ds_read_b128 v[194:197], v156 offset:17408
	ds_read_b128 v[198:201], v155 offset:16384
	ds_read_b128 v[202:205], v155 offset:17408
	ds_read_b128 v[206:209], v154 offset:16384
	ds_read_b128 v[210:213], v154 offset:17408
	ds_read_b128 v[214:217], v153 offset:16384
	ds_read_b128 v[218:221], v153 offset:17408
	global_load_lds_dwordx4 v[250:251], off
	v_lshl_add_u64 v[250:251], v[236:237], 0, s[10:11]
	s_mov_b32 m0, s15
	s_nop 0
	global_load_lds_dwordx4 v[250:251], off
	s_barrier
	s_waitcnt lgkmcnt(0)
	s_setprio 1
	s_waitcnt lgkmcnt(0)
	v_mfma_f32_16x16x32_f16 v[64:67], v[190:193], v[174:177], v[64:67]
	v_mfma_f32_16x16x32_f16 v[60:63], v[190:193], v[182:185], v[60:63]
	v_mfma_f32_16x16x32_f16 v[56:59], v[198:201], v[174:177], v[56:59]
	v_mfma_f32_16x16x32_f16 v[52:55], v[198:201], v[182:185], v[52:55]
	v_mfma_f32_16x16x32_f16 v[48:51], v[206:209], v[174:177], v[48:51]
	v_mfma_f32_16x16x32_f16 v[44:47], v[206:209], v[182:185], v[44:47]
	v_mfma_f32_16x16x32_f16 v[40:43], v[214:217], v[174:177], v[40:43]
	v_mfma_f32_16x16x32_f16 v[36:39], v[214:217], v[182:185], v[36:39]
	v_mfma_f32_16x16x32_f16 v[64:67], v[194:197], v[178:181], v[64:67]
	v_mfma_f32_16x16x32_f16 v[60:63], v[194:197], v[186:189], v[60:63]
	v_mfma_f32_16x16x32_f16 v[56:59], v[202:205], v[178:181], v[56:59]
	v_mfma_f32_16x16x32_f16 v[52:55], v[202:205], v[186:189], v[52:55]
	v_mfma_f32_16x16x32_f16 v[48:51], v[210:213], v[178:181], v[48:51]
	v_mfma_f32_16x16x32_f16 v[44:47], v[210:213], v[186:189], v[44:47]
	v_mfma_f32_16x16x32_f16 v[40:43], v[218:221], v[178:181], v[40:43]
	v_mfma_f32_16x16x32_f16 v[36:39], v[218:221], v[186:189], v[36:39]
	s_setprio 0
	s_barrier
; #define LDA8(dst, b, h) _Pragma("unroll") for (int m = 0; m < 4; ++m) _Pragma("unroll") for (int k = 0; k < 2; ++k) \
;     dst[m][k] = *(const bf16x8*)((const char*)SA8(b, h) + lds_byte8(wr * 64 + m * 16 + fr, k * 32 + fq * 8))
; #define LDB8(dst, b, h) _Pragma("unroll") for (int n = 0; n < 2; ++n) _Pragma("unroll") for (int k = 0; k < 2; ++k) \
;     dst[n][k] = *(const bf16x8*)((const char*)SB8(b, h) + lds_byte8(wc * 32 + n * 16 + fr, k * 32 + fq * 8))
; #define WAIT_V8(n) asm volatile("s_waitcnt vmcnt(" #n ")" ::: "memory")
; #define WAIT_L8(n) asm volatile("s_waitcnt lgkmcnt(" #n ")" ::: "memory")
; #define BAR8 __builtin_amdgcn_s_barrier()
; #define SCHED8 __builtin_amdgcn_sched_barrier(0)
;     ...
;     WAIT_V8(6); BAR8; MMA8(1, 1, At, B1); BAR8;
;     LDB8(B0, 1, 0); SCHED8; LDA8(At, 1, 0); STAGE8(SA8(0, 1), A, lda, brow + 128, tt + 2);
;     WAIT_L8(8); BAR8; WAIT_L8(0); MMA8(0, 0, At, B0); BAR8; SCHED8;
;     LDB8(B1, 1, 1); STAGE8(SB8(1, 0), Bt, K, bcol, tt + 3);
;     BAR8; WAIT_L8(0); MMA8(0, 1, At, B1); BAR8;
;     LDA8(At, 1, 1); STAGE8(SA8(1, 0), A, lda, brow, tt + 3);
;     BAR8; WAIT_L8(0); MMA8(1, 0, At, B0); BAR8; SCHED8;
	v_readfirstlane_b32 s15, v159
	v_lshl_add_u64 v[174:175], v[246:247], 0, s[42:43]
	s_mov_b32 m0, s15
	v_readfirstlane_b32 s15, v160
	global_load_lds_dwordx4 v[174:175], off
	v_lshl_add_u64 v[174:175], v[248:249], 0, s[42:43]
	s_mov_b32 m0, s15
	s_nop 0
	global_load_lds_dwordx4 v[174:175], off
	s_waitcnt vmcnt(10)
	s_barrier
	s_setprio 1
	v_mfma_f32_16x16x32_f16 v[32:35], v[190:193], v[226:229], v[32:35]
	v_mfma_f32_16x16x32_f16 v[28:31], v[190:193], v[238:241], v[28:31]
	v_mfma_f32_16x16x32_f16 v[24:27], v[198:201], v[226:229], v[24:27]
	v_mfma_f32_16x16x32_f16 v[20:23], v[198:201], v[238:241], v[20:23]
	v_mfma_f32_16x16x32_f16 v[16:19], v[206:209], v[226:229], v[16:19]
	v_mfma_f32_16x16x32_f16 v[12:15], v[206:209], v[238:241], v[12:15]
	v_mfma_f32_16x16x32_f16 v[8:11], v[214:217], v[226:229], v[8:11]
	v_mfma_f32_16x16x32_f16 v[4:7], v[214:217], v[238:241], v[4:7]
	v_mfma_f32_16x16x32_f16 v[32:35], v[194:197], v[230:233], v[32:35]
	v_mfma_f32_16x16x32_f16 v[28:31], v[194:197], v[242:245], v[28:31]
	v_mfma_f32_16x16x32_f16 v[24:27], v[202:205], v[230:233], v[24:27]
	v_mfma_f32_16x16x32_f16 v[20:23], v[202:205], v[242:245], v[20:23]
	v_mfma_f32_16x16x32_f16 v[16:19], v[210:213], v[230:233], v[16:19]
	v_mfma_f32_16x16x32_f16 v[12:15], v[210:213], v[242:245], v[12:15]
	v_mfma_f32_16x16x32_f16 v[8:11], v[218:221], v[230:233], v[8:11]
	v_mfma_f32_16x16x32_f16 v[4:7], v[218:221], v[242:245], v[4:7]
	s_setprio 0
	s_barrier
	ds_read_b128 v[174:177], v161
	ds_read_b128 v[178:181], v161 offset:1024
	ds_read_b128 v[182:185], v161 offset:2048
	ds_read_b128 v[186:189], v161 offset:3072
	v_readfirstlane_b32 s15, v162
	v_lshl_add_u64 v[226:227], v[222:223], 0, s[18:19]
	s_mov_b32 m0, s15
	v_readfirstlane_b32 s15, v163
	ds_read_b128 v[190:193], v156 offset:32768
	ds_read_b128 v[194:197], v156 offset:33792
	ds_read_b128 v[198:201], v155 offset:32768
	ds_read_b128 v[202:205], v155 offset:33792
	ds_read_b128 v[206:209], v154 offset:32768
	ds_read_b128 v[210:213], v154 offset:33792
	ds_read_b128 v[214:217], v153 offset:32768
	ds_read_b128 v[218:221], v153 offset:33792
	global_load_lds_dwordx4 v[226:227], off
	v_lshl_add_u64 v[226:227], v[236:237], 0, s[18:19]
	s_mov_b32 m0, s15
	s_nop 0
	global_load_lds_dwordx4 v[226:227], off
	s_waitcnt lgkmcnt(8)
	s_waitcnt vmcnt(10)
	s_barrier
	s_waitcnt lgkmcnt(0)
	s_setprio 1
	s_waitcnt lgkmcnt(0)
	v_mfma_f32_16x16x32_f16 v[128:131], v[190:193], v[174:177], v[128:131]
	v_mfma_f32_16x16x32_f16 v[124:127], v[190:193], v[182:185], v[124:127]
	v_mfma_f32_16x16x32_f16 v[120:123], v[198:201], v[174:177], v[120:123]
	v_mfma_f32_16x16x32_f16 v[116:119], v[198:201], v[182:185], v[116:119]
	v_mfma_f32_16x16x32_f16 v[112:115], v[206:209], v[174:177], v[112:115]
	v_mfma_f32_16x16x32_f16 v[108:111], v[206:209], v[182:185], v[108:111]
	v_mfma_f32_16x16x32_f16 v[104:107], v[214:217], v[174:177], v[104:107]
	v_mfma_f32_16x16x32_f16 v[100:103], v[214:217], v[182:185], v[100:103]
	v_mfma_f32_16x16x32_f16 v[128:131], v[194:197], v[178:181], v[128:131]
	v_mfma_f32_16x16x32_f16 v[124:127], v[194:197], v[186:189], v[124:127]
	v_mfma_f32_16x16x32_f16 v[120:123], v[202:205], v[178:181], v[120:123]
	v_mfma_f32_16x16x32_f16 v[116:119], v[202:205], v[186:189], v[116:119]
	v_mfma_f32_16x16x32_f16 v[112:115], v[210:213], v[178:181], v[112:115]
	v_mfma_f32_16x16x32_f16 v[108:111], v[210:213], v[186:189], v[108:111]
	v_mfma_f32_16x16x32_f16 v[104:107], v[218:221], v[178:181], v[104:107]
	v_mfma_f32_16x16x32_f16 v[100:103], v[218:221], v[186:189], v[100:103]
	s_setprio 0
	s_barrier
	v_readfirstlane_b32 s15, v164
	v_lshl_add_u64 v[250:251], v[246:247], 0, s[44:45]
	s_mov_b32 m0, s15
	v_readfirstlane_b32 s15, v165
	ds_read_b128 v[226:229], v158
	ds_read_b128 v[230:233], v158 offset:1024
	ds_read_b128 v[238:241], v158 offset:2048
	ds_read_b128 v[242:245], v158 offset:3072
	global_load_lds_dwordx4 v[250:251], off
	v_lshl_add_u64 v[250:251], v[248:249], 0, s[44:45]
	s_mov_b32 m0, s15
	s_nop 0
	global_load_lds_dwordx4 v[250:251], off
	s_waitcnt vmcnt(10)
	s_barrier
	s_waitcnt lgkmcnt(0)
	s_setprio 1
	s_waitcnt lgkmcnt(0)
	v_mfma_f32_16x16x32_f16 v[96:99], v[190:193], v[226:229], v[96:99]
	v_mfma_f32_16x16x32_f16 v[92:95], v[190:193], v[238:241], v[92:95]
	v_mfma_f32_16x16x32_f16 v[88:91], v[198:201], v[226:229], v[88:91]
	v_mfma_f32_16x16x32_f16 v[84:87], v[198:201], v[238:241], v[84:87]
	v_mfma_f32_16x16x32_f16 v[80:83], v[206:209], v[226:229], v[80:83]
	v_mfma_f32_16x16x32_f16 v[76:79], v[206:209], v[238:241], v[76:79]
	v_mfma_f32_16x16x32_f16 v[72:75], v[214:217], v[226:229], v[72:75]
	v_mfma_f32_16x16x32_f16 v[68:71], v[214:217], v[238:241], v[68:71]
	v_mfma_f32_16x16x32_f16 v[96:99], v[194:197], v[230:233], v[96:99]
	v_mfma_f32_16x16x32_f16 v[92:95], v[194:197], v[242:245], v[92:95]
	v_mfma_f32_16x16x32_f16 v[88:91], v[202:205], v[230:233], v[88:91]
	v_mfma_f32_16x16x32_f16 v[84:87], v[202:205], v[242:245], v[84:87]
	v_mfma_f32_16x16x32_f16 v[80:83], v[210:213], v[230:233], v[80:83]
	v_mfma_f32_16x16x32_f16 v[76:79], v[210:213], v[242:245], v[76:79]
	v_mfma_f32_16x16x32_f16 v[72:75], v[218:221], v[230:233], v[72:75]
	v_mfma_f32_16x16x32_f16 v[68:71], v[218:221], v[242:245], v[68:71]
	s_setprio 0
	v_readfirstlane_b32 s15, v166
	v_lshl_add_u64 v[222:223], v[222:223], 0, s[22:23]
	s_mov_b32 m0, s15
	v_readfirstlane_b32 s15, v167
	s_barrier
	ds_read_b128 v[190:193], v156 offset:49152
	ds_read_b128 v[194:197], v156 offset:50176
	ds_read_b128 v[198:201], v155 offset:49152
	ds_read_b128 v[202:205], v155 offset:50176
	ds_read_b128 v[206:209], v154 offset:49152
	ds_read_b128 v[210:213], v154 offset:50176
	ds_read_b128 v[214:217], v153 offset:49152
	ds_read_b128 v[218:221], v153 offset:50176
	global_load_lds_dwordx4 v[222:223], off
	v_lshl_add_u64 v[222:223], v[236:237], 0, s[22:23]
	s_mov_b32 m0, s15
	s_nop 0
	global_load_lds_dwordx4 v[222:223], off
	s_barrier
; #define LDA8(dst, b, h) _Pragma("unroll") for (int m = 0; m < 4; ++m) _Pragma("unroll") for (int k = 0; k < 2; ++k) \
;     dst[m][k] = *(const bf16x8*)((const char*)SA8(b, h) + lds_byte8(wr * 64 + m * 16 + fr, k * 32 + fq * 8))
; #define LDB8(dst, b, h) _Pragma("unroll") for (int n = 0; n < 2; ++n) _Pragma("unroll") for (int k = 0; k < 2; ++k) \
;     dst[n][k] = *(const bf16x8*)((const char*)SB8(b, h) + lds_byte8(wc * 32 + n * 16 + fr, k * 32 + fq * 8))
; #define WAIT_V8(n) asm volatile("s_waitcnt vmcnt(" #n ")" ::: "memory")
; #define WAIT_L8(n) asm volatile("s_waitcnt lgkmcnt(" #n ")" ::: "memory")
; #define BAR8 __builtin_amdgcn_s_barrier()
; #define SCHED8 __builtin_amdgcn_sched_barrier(0)
;     ...
;     BAR8; WAIT_L8(0); MMA8(1, 0, At, B0); BAR8; SCHED8;
;     STAGE8(SB8(1, 1), Bt, K, bcol + 128, tt + 3);
;     WAIT_V8(6); BAR8; MMA8(1, 1, At, B1); BAR8;
;   }
;   { LDB8(B0, 0, 0); LDA8(At, 0, 0); STAGE8(SA8(1, 1), A, lda, brow + 128, nt - 1);
;     BAR8; WAIT_L8(0); MMA8(0, 0, At, B0); BAR8;
;     LDB8(B1, 0, 1); BAR8; WAIT_L8(0); MMA8(0, 1, At, B1); BAR8;
;     LDA8(At, 0, 1); WAIT_V8(4); BAR8; WAIT_L8(0); MMA8(1, 0, At, B0); MMA8(1, 1, At, B1); BAR8; }
	s_waitcnt lgkmcnt(0)
	s_setprio 1
	s_waitcnt lgkmcnt(0)
	v_mfma_f32_16x16x32_f16 v[64:67], v[190:193], v[174:177], v[64:67]
	v_mfma_f32_16x16x32_f16 v[60:63], v[190:193], v[182:185], v[60:63]
	v_mfma_f32_16x16x32_f16 v[56:59], v[198:201], v[174:177], v[56:59]
	v_mfma_f32_16x16x32_f16 v[52:55], v[198:201], v[182:185], v[52:55]
	v_mfma_f32_16x16x32_f16 v[48:51], v[206:209], v[174:177], v[48:51]
	v_mfma_f32_16x16x32_f16 v[44:47], v[206:209], v[182:185], v[44:47]
	v_mfma_f32_16x16x32_f16 v[40:43], v[214:217], v[174:177], v[40:43]
	v_mfma_f32_16x16x32_f16 v[36:39], v[214:217], v[182:185], v[36:39]
	v_mfma_f32_16x16x32_f16 v[64:67], v[194:197], v[178:181], v[64:67]
	v_mfma_f32_16x16x32_f16 v[60:63], v[194:197], v[186:189], v[60:63]
	v_mfma_f32_16x16x32_f16 v[56:59], v[202:205], v[178:181], v[56:59]
	v_mfma_f32_16x16x32_f16 v[52:55], v[202:205], v[186:189], v[52:55]
	v_mfma_f32_16x16x32_f16 v[48:51], v[210:213], v[178:181], v[48:51]
	v_mfma_f32_16x16x32_f16 v[44:47], v[210:213], v[186:189], v[44:47]
	v_mfma_f32_16x16x32_f16 v[40:43], v[218:221], v[178:181], v[40:43]
	v_mfma_f32_16x16x32_f16 v[36:39], v[218:221], v[186:189], v[36:39]
	s_setprio 0
	s_barrier
	v_readfirstlane_b32 s15, v169
	v_lshl_add_u64 v[174:175], v[246:247], 0, s[46:47]
	s_mov_b32 m0, s15
	v_readfirstlane_b32 s15, v170
	global_load_lds_dwordx4 v[174:175], off
	v_lshl_add_u64 v[174:175], v[248:249], 0, s[46:47]
	s_mov_b32 m0, s15
	s_nop 0
	global_load_lds_dwordx4 v[174:175], off
	s_waitcnt vmcnt(10)
	s_barrier
	s_setprio 1
	v_mfma_f32_16x16x32_f16 v[32:35], v[190:193], v[226:229], v[32:35]
	v_mfma_f32_16x16x32_f16 v[28:31], v[190:193], v[238:241], v[28:31]
	v_mfma_f32_16x16x32_f16 v[24:27], v[198:201], v[226:229], v[24:27]
	v_mfma_f32_16x16x32_f16 v[20:23], v[198:201], v[238:241], v[20:23]
	v_mfma_f32_16x16x32_f16 v[16:19], v[206:209], v[226:229], v[16:19]
	v_mfma_f32_16x16x32_f16 v[12:15], v[206:209], v[238:241], v[12:15]
	v_mfma_f32_16x16x32_f16 v[8:11], v[214:217], v[226:229], v[8:11]
	v_mfma_f32_16x16x32_f16 v[4:7], v[214:217], v[238:241], v[4:7]
	v_mfma_f32_16x16x32_f16 v[32:35], v[194:197], v[230:233], v[32:35]
	v_mfma_f32_16x16x32_f16 v[28:31], v[194:197], v[242:245], v[28:31]
	v_mfma_f32_16x16x32_f16 v[24:27], v[202:205], v[230:233], v[24:27]
	v_mfma_f32_16x16x32_f16 v[20:23], v[202:205], v[242:245], v[20:23]
	v_mfma_f32_16x16x32_f16 v[16:19], v[210:213], v[230:233], v[16:19]
	v_mfma_f32_16x16x32_f16 v[12:15], v[210:213], v[242:245], v[12:15]
	v_mfma_f32_16x16x32_f16 v[8:11], v[218:221], v[230:233], v[8:11]
	v_mfma_f32_16x16x32_f16 v[4:7], v[218:221], v[242:245], v[4:7]
	s_setprio 0
	s_add_i32 s14, s14, 2
	s_add_u32 s12, s12, 0x100
	s_addc_u32 s13, s13, 0
	s_cmp_lt_u32 s14, 12
	s_barrier
	s_cbranch_scc1 .LBB0_1015
	s_add_u32 s8, s8, 0x40780
	s_addc_u32 s9, s9, 0
	v_lshl_add_u64 v[132:133], s[8:9], 0, v[132:133]
	v_readfirstlane_b32 s12, v172
	v_lshl_add_u64 v[0:1], v[0:1], 1, v[132:133]
	s_mov_b32 m0, s12
	ds_read_b128 v[138:141], v171
	ds_read_b128 v[142:145], v171 offset:1024
	ds_read_b128 v[162:165], v171 offset:2048
	ds_read_b128 v[174:177], v171 offset:3072
	ds_read_b128 v[178:181], v156
	ds_read_b128 v[182:185], v156 offset:1024
	ds_read_b128 v[186:189], v155
	ds_read_b128 v[190:193], v155 offset:1024
	ds_read_b128 v[194:197], v154
	ds_read_b128 v[198:201], v154 offset:1024
	ds_read_b128 v[202:205], v153
	ds_read_b128 v[206:209], v153 offset:1024
	global_load_lds_dwordx4 v[0:1], off
	v_lshl_add_u64 v[0:1], s[8:9], 0, v[136:137]
	v_readfirstlane_b32 s8, v173
	v_lshl_add_u64 v[0:1], v[134:135], 1, v[0:1]
	s_mov_b32 m0, s8
	s_nop 0
	global_load_lds_dwordx4 v[0:1], off
	s_waitcnt vmcnt(10)
	s_barrier
	s_waitcnt lgkmcnt(0)
	s_setprio 1
	s_waitcnt lgkmcnt(0)
	v_mfma_f32_16x16x32_f16 v[128:131], v[178:181], v[138:141], v[128:131]
	v_mfma_f32_16x16x32_f16 v[124:127], v[178:181], v[162:165], v[124:127]
	v_mfma_f32_16x16x32_f16 v[120:123], v[186:189], v[138:141], v[120:123]
	v_mfma_f32_16x16x32_f16 v[112:115], v[194:197], v[138:141], v[112:115]
	v_mfma_f32_16x16x32_f16 v[128:131], v[182:185], v[142:145], v[128:131]
	v_mfma_f32_16x16x32_f16 v[124:127], v[182:185], v[174:177], v[124:127]
	v_mfma_f32_16x16x32_f16 v[120:123], v[190:193], v[142:145], v[120:123]
	v_mfma_f32_16x16x32_f16 v[116:119], v[186:189], v[162:165], v[116:119]
	v_mfma_f32_16x16x32_f16 v[112:115], v[198:201], v[142:145], v[112:115]
	v_mfma_f32_16x16x32_f16 v[108:111], v[194:197], v[162:165], v[108:111]
	v_mfma_f32_16x16x32_f16 v[104:107], v[202:205], v[138:141], v[104:107]
	v_mfma_f32_16x16x32_f16 v[100:103], v[202:205], v[162:165], v[100:103]
	v_mfma_f32_16x16x32_f16 v[132:135], v[190:193], v[174:177], v[116:119]
	v_mfma_f32_16x16x32_f16 v[170:173], v[198:201], v[174:177], v[108:111]
	v_mfma_f32_16x16x32_f16 v[210:213], v[206:209], v[142:145], v[104:107]
	v_mfma_f32_16x16x32_f16 v[214:217], v[206:209], v[174:177], v[100:103]
	s_setprio 0
	s_barrier
	s_nop 1
	ds_read_b128 v[100:103], v168
	ds_read_b128 v[104:107], v168 offset:1024
	ds_read_b128 v[108:111], v168 offset:2048
	ds_read_b128 v[116:119], v168 offset:3072
	s_waitcnt vmcnt(8)
	s_barrier
; #define LDA8(dst, b, h) _Pragma("unroll") for (int m = 0; m < 4; ++m) _Pragma("unroll") for (int k = 0; k < 2; ++k) \
;     dst[m][k] = *(const bf16x8*)((const char*)SA8(b, h) + lds_byte8(wr * 64 + m * 16 + fr, k * 32 + fq * 8))
; #define LDB8(dst, b, h) _Pragma("unroll") for (int n = 0; n < 2; ++n) _Pragma("unroll") for (int k = 0; k < 2; ++k) \
;     dst[n][k] = *(const bf16x8*)((const char*)SB8(b, h) + lds_byte8(wc * 32 + n * 16 + fr, k * 32 + fq * 8))
; #define WAIT_V8(n) asm volatile("s_waitcnt vmcnt(" #n ")" ::: "memory")
; #define WAIT_L8(n) asm volatile("s_waitcnt lgkmcnt(" #n ")" ::: "memory")
; #define BAR8 __builtin_amdgcn_s_barrier()
;     ...
;     LDB8(B1, 0, 1); BAR8; WAIT_L8(0); MMA8(0, 1, At, B1); BAR8;
;     LDA8(At, 0, 1); WAIT_V8(4); BAR8; WAIT_L8(0); MMA8(1, 0, At, B0); MMA8(1, 1, At, B1); BAR8; }
;   { LDB8(B0, 1, 0); LDA8(At, 1, 0); WAIT_V8(2); BAR8; WAIT_L8(0); MMA8(0, 0, At, B0); BAR8;
	s_waitcnt lgkmcnt(0)
	s_setprio 1
	s_waitcnt lgkmcnt(0)
	v_mfma_f32_16x16x32_f16 v[80:83], v[194:197], v[100:103], v[80:83]
	v_mfma_f32_16x16x32_f16 v[76:79], v[194:197], v[108:111], v[76:79]
	v_mfma_f32_16x16x32_f16 v[72:75], v[202:205], v[100:103], v[72:75]
	v_mfma_f32_16x16x32_f16 v[68:71], v[202:205], v[108:111], v[68:71]
	v_mfma_f32_16x16x32_f16 v[96:99], v[178:181], v[100:103], v[96:99]
	v_mfma_f32_16x16x32_f16 v[92:95], v[178:181], v[108:111], v[92:95]
	v_mfma_f32_16x16x32_f16 v[88:91], v[186:189], v[100:103], v[88:91]
	v_mfma_f32_16x16x32_f16 v[84:87], v[186:189], v[108:111], v[84:87]
	v_mfma_f32_16x16x32_f16 v[80:83], v[198:201], v[104:107], v[80:83]
	v_mfma_f32_16x16x32_f16 v[76:79], v[198:201], v[116:119], v[76:79]
	v_mfma_f32_16x16x32_f16 v[72:75], v[206:209], v[104:107], v[72:75]
	v_mfma_f32_16x16x32_f16 v[68:71], v[206:209], v[116:119], v[68:71]
	v_mfma_f32_16x16x32_f16 v[166:169], v[182:185], v[104:107], v[96:99]
	v_mfma_f32_16x16x32_f16 v[178:181], v[182:185], v[116:119], v[92:95]
	v_mfma_f32_16x16x32_f16 v[182:185], v[190:193], v[104:107], v[88:91]
	v_mfma_f32_16x16x32_f16 v[186:189], v[190:193], v[116:119], v[84:87]
	s_setprio 0
	s_barrier
	s_nop 0
	ds_read_b128 v[84:87], v156 offset:16384
	ds_read_b128 v[88:91], v156 offset:17408
	ds_read_b128 v[92:95], v155 offset:16384
	ds_read_b128 v[96:99], v155 offset:17408
	ds_read_b128 v[190:193], v154 offset:16384
	ds_read_b128 v[194:197], v154 offset:17408
	ds_read_b128 v[198:201], v153 offset:16384
	ds_read_b128 v[202:205], v153 offset:17408
	s_waitcnt vmcnt(4)
	s_barrier
	s_waitcnt lgkmcnt(0)
	s_setprio 1
	s_waitcnt lgkmcnt(0)
	v_mfma_f32_16x16x32_f16 v[64:67], v[84:87], v[138:141], v[64:67]
	v_mfma_f32_16x16x32_f16 v[60:63], v[84:87], v[162:165], v[60:63]
	v_mfma_f32_16x16x32_f16 v[56:59], v[92:95], v[138:141], v[56:59]
	v_mfma_f32_16x16x32_f16 v[52:55], v[92:95], v[162:165], v[52:55]
	v_mfma_f32_16x16x32_f16 v[48:51], v[190:193], v[138:141], v[48:51]
	v_mfma_f32_16x16x32_f16 v[44:47], v[190:193], v[162:165], v[44:47]
	v_mfma_f32_16x16x32_f16 v[40:43], v[198:201], v[138:141], v[40:43]
	v_mfma_f32_16x16x32_f16 v[36:39], v[198:201], v[162:165], v[36:39]
	v_mfma_f32_16x16x32_f16 v[64:67], v[88:91], v[142:145], v[64:67]
	v_mfma_f32_16x16x32_f16 v[60:63], v[88:91], v[174:177], v[60:63]
	v_mfma_f32_16x16x32_f16 v[56:59], v[96:99], v[142:145], v[56:59]
	v_mfma_f32_16x16x32_f16 v[52:55], v[96:99], v[174:177], v[52:55]
	v_mfma_f32_16x16x32_f16 v[48:51], v[194:197], v[142:145], v[48:51]
	v_mfma_f32_16x16x32_f16 v[44:47], v[194:197], v[174:177], v[44:47]
	v_mfma_f32_16x16x32_f16 v[40:43], v[202:205], v[142:145], v[40:43]
	v_mfma_f32_16x16x32_f16 v[36:39], v[202:205], v[174:177], v[36:39]
	s_setprio 0
	s_setprio 1
	v_mfma_f32_16x16x32_f16 v[32:35], v[84:87], v[100:103], v[32:35]
	v_mfma_f32_16x16x32_f16 v[28:31], v[84:87], v[108:111], v[28:31]
	v_mfma_f32_16x16x32_f16 v[24:27], v[92:95], v[100:103], v[24:27]
	v_mfma_f32_16x16x32_f16 v[20:23], v[92:95], v[108:111], v[20:23]
	v_mfma_f32_16x16x32_f16 v[16:19], v[190:193], v[100:103], v[16:19]
	v_mfma_f32_16x16x32_f16 v[12:15], v[190:193], v[108:111], v[12:15]
	v_mfma_f32_16x16x32_f16 v[8:11], v[198:201], v[100:103], v[8:11]
	v_mfma_f32_16x16x32_f16 v[4:7], v[198:201], v[108:111], v[4:7]
	v_mfma_f32_16x16x32_f16 v[136:139], v[88:91], v[104:107], v[32:35]
	v_mfma_f32_16x16x32_f16 v[140:143], v[88:91], v[116:119], v[28:31]
	v_mfma_f32_16x16x32_f16 v[162:165], v[96:99], v[104:107], v[24:27]
	v_mfma_f32_16x16x32_f16 v[174:177], v[96:99], v[116:119], v[20:23]
	v_mfma_f32_16x16x32_f16 v[206:209], v[194:197], v[104:107], v[16:19]
	v_mfma_f32_16x16x32_f16 v[190:193], v[194:197], v[116:119], v[12:15]
	v_mfma_f32_16x16x32_f16 v[194:197], v[202:205], v[104:107], v[8:11]
	v_mfma_f32_16x16x32_f16 v[198:201], v[202:205], v[116:119], v[4:7]
	s_setprio 0
	s_barrier
	ds_read_b128 v[202:205], v161
	ds_read_b128 v[218:221], v161 offset:1024
	ds_read_b128 v[226:229], v161 offset:2048
	ds_read_b128 v[230:233], v161 offset:3072
	ds_read_b128 v[8:11], v156 offset:32768
	ds_read_b128 v[12:15], v156 offset:33792
	ds_read_b128 v[16:19], v155 offset:32768
	ds_read_b128 v[24:27], v155 offset:33792
	ds_read_b128 v[28:31], v154 offset:32768
	ds_read_b128 v[32:35], v154 offset:33792
	ds_read_b128 v[238:241], v153 offset:32768
	ds_read_b128 v[242:245], v153 offset:33792
	s_waitcnt vmcnt(2)
	s_barrier
; #define LDA8(dst, b, h) _Pragma("unroll") for (int m = 0; m < 4; ++m) _Pragma("unroll") for (int k = 0; k < 2; ++k) \
;     dst[m][k] = *(const bf16x8*)((const char*)SA8(b, h) + lds_byte8(wr * 64 + m * 16 + fr, k * 32 + fq * 8))
; #define LDB8(dst, b, h) _Pragma("unroll") for (int n = 0; n < 2; ++n) _Pragma("unroll") for (int k = 0; k < 2; ++k) \
;     dst[n][k] = *(const bf16x8*)((const char*)SB8(b, h) + lds_byte8(wc * 32 + n * 16 + fr, k * 32 + fq * 8))
; #define WAIT_V8(n) asm volatile("s_waitcnt vmcnt(" #n ")" ::: "memory")
; #define WAIT_L8(n) asm volatile("s_waitcnt lgkmcnt(" #n ")" ::: "memory")
; #define BAR8 __builtin_amdgcn_s_barrier()
;     ...
;   { LDB8(B0, 1, 0); LDA8(At, 1, 0); WAIT_V8(2); BAR8; WAIT_L8(0); MMA8(0, 0, At, B0); BAR8;
;     LDB8(B1, 1, 1); WAIT_V8(0); BAR8; WAIT_L8(0); MMA8(0, 1, At, B1); BAR8;
;     LDA8(At, 1, 1); BAR8; WAIT_L8(0); MMA8(1, 0, At, B0); MMA8(1, 1, At, B1); BAR8; }
;   if (wr == 0) BAR8;
;   __syncthreads();
;     ...
;   if (t < 256) {
;     float rs = 1.f;
;     if (e.ss) {
;       const float* sp = e.ss + (size_t)(m0 + t) * e.nss;
;       float s = 0.f;
;       for (int i = 0; i < e.nss; ++i) s += sp[i];
;       rs = rsqrtf(s * e.inv_n + EPS);
;     }
;     ((float*)(smem + SMEM_RSTD))[t] = rs;
	s_waitcnt lgkmcnt(0)
	s_setprio 1
	s_waitcnt lgkmcnt(0)
	v_mfma_f32_16x16x32_f16 v[4:7], v[8:11], v[202:205], v[128:131]
	v_mfma_f32_16x16x32_f16 v[104:107], v[12:15], v[218:221], v[4:7]
	v_mfma_f32_16x16x32_f16 v[4:7], v[8:11], v[226:229], v[124:127]
	v_mfma_f32_16x16x32_f16 v[116:119], v[12:15], v[230:233], v[4:7]
	v_mfma_f32_16x16x32_f16 v[4:7], v[16:19], v[202:205], v[120:123]
	v_mfma_f32_16x16x32_f16 v[100:103], v[24:27], v[218:221], v[4:7]
	v_mfma_f32_16x16x32_f16 v[4:7], v[16:19], v[226:229], v[132:135]
	v_mfma_f32_16x16x32_f16 v[108:111], v[24:27], v[230:233], v[4:7]
	v_mfma_f32_16x16x32_f16 v[4:7], v[28:31], v[202:205], v[112:115]
	v_mfma_f32_16x16x32_f16 v[92:95], v[32:35], v[218:221], v[4:7]
	v_mfma_f32_16x16x32_f16 v[4:7], v[28:31], v[226:229], v[170:173]
	v_mfma_f32_16x16x32_f16 v[96:99], v[32:35], v[230:233], v[4:7]
	v_mfma_f32_16x16x32_f16 v[4:7], v[238:241], v[202:205], v[210:213]
	v_mfma_f32_16x16x32_f16 v[84:87], v[242:245], v[218:221], v[4:7]
	v_mfma_f32_16x16x32_f16 v[4:7], v[238:241], v[226:229], v[214:217]
	v_mfma_f32_16x16x32_f16 v[88:91], v[242:245], v[230:233], v[4:7]
	s_setprio 0
	s_barrier
	ds_read_b128 v[132:135], v158
	ds_read_b128 v[170:173], v158 offset:1024
	ds_read_b128 v[210:213], v158 offset:2048
	ds_read_b128 v[158:161], v158 offset:3072
	s_waitcnt vmcnt(0)
	s_barrier
	s_waitcnt lgkmcnt(0)
	s_setprio 1
	s_waitcnt lgkmcnt(0)
	v_mfma_f32_16x16x32_f16 v[4:7], v[8:11], v[132:135], v[166:169]
	v_mfma_f32_16x16x32_f16 v[8:11], v[8:11], v[210:213], v[178:181]
	v_mfma_f32_16x16x32_f16 v[4:7], v[12:15], v[170:173], v[4:7]
	v_mfma_f32_16x16x32_f16 v[20:23], v[12:15], v[158:161], v[8:11]
	v_mfma_f32_16x16x32_f16 v[8:11], v[16:19], v[132:135], v[182:185]
	v_mfma_f32_16x16x32_f16 v[12:15], v[16:19], v[210:213], v[186:189]
	v_mfma_f32_16x16x32_f16 v[8:11], v[24:27], v[170:173], v[8:11]
	v_mfma_f32_16x16x32_f16 v[24:27], v[24:27], v[158:161], v[12:15]
	v_mfma_f32_16x16x32_f16 v[12:15], v[28:31], v[132:135], v[80:83]
	v_mfma_f32_16x16x32_f16 v[16:19], v[28:31], v[210:213], v[76:79]
	v_mfma_f32_16x16x32_f16 v[12:15], v[32:35], v[170:173], v[12:15]
	v_mfma_f32_16x16x32_f16 v[28:31], v[32:35], v[158:161], v[16:19]
	v_mfma_f32_16x16x32_f16 v[16:19], v[238:241], v[132:135], v[72:75]
	v_mfma_f32_16x16x32_f16 v[32:35], v[238:241], v[210:213], v[68:71]
	v_mfma_f32_16x16x32_f16 v[16:19], v[242:245], v[170:173], v[16:19]
	v_mfma_f32_16x16x32_f16 v[32:35], v[242:245], v[158:161], v[32:35]
	s_setprio 0
	s_barrier
	ds_read_b128 v[166:169], v156 offset:49152
	ds_read_b128 v[178:181], v156 offset:50176
	ds_read_b128 v[182:185], v155 offset:49152
	ds_read_b128 v[186:189], v155 offset:50176
	ds_read_b128 v[214:217], v154 offset:49152
	ds_read_b128 v[154:157], v154 offset:50176
	ds_read_b128 v[238:241], v153 offset:49152
	ds_read_b128 v[150:153], v153 offset:50176
	s_barrier
	s_waitcnt lgkmcnt(0)
	s_setprio 1
	s_waitcnt lgkmcnt(0)
	v_mfma_f32_16x16x32_f16 v[64:67], v[166:169], v[202:205], v[64:67]
	v_mfma_f32_16x16x32_f16 v[60:63], v[166:169], v[226:229], v[60:63]
	v_mfma_f32_16x16x32_f16 v[56:59], v[182:185], v[202:205], v[56:59]
	v_mfma_f32_16x16x32_f16 v[52:55], v[182:185], v[226:229], v[52:55]
	v_mfma_f32_16x16x32_f16 v[48:51], v[214:217], v[202:205], v[48:51]
	v_mfma_f32_16x16x32_f16 v[44:47], v[214:217], v[226:229], v[44:47]
	v_mfma_f32_16x16x32_f16 v[40:43], v[238:241], v[202:205], v[40:43]
	v_mfma_f32_16x16x32_f16 v[36:39], v[238:241], v[226:229], v[36:39]
	v_mfma_f32_16x16x32_f16 v[128:131], v[178:181], v[218:221], v[64:67]
	v_mfma_f32_16x16x32_f16 v[124:127], v[178:181], v[230:233], v[60:63]
	v_mfma_f32_16x16x32_f16 v[120:123], v[186:189], v[218:221], v[56:59]
	v_mfma_f32_16x16x32_f16 v[112:115], v[186:189], v[230:233], v[52:55]
	v_mfma_f32_16x16x32_f16 v[80:83], v[154:157], v[218:221], v[48:51]
	v_mfma_f32_16x16x32_f16 v[76:79], v[154:157], v[230:233], v[44:47]
	v_mfma_f32_16x16x32_f16 v[72:75], v[150:153], v[218:221], v[40:43]
	v_mfma_f32_16x16x32_f16 v[68:71], v[150:153], v[230:233], v[36:39]
	s_setprio 0
	s_setprio 1
	v_mfma_f32_16x16x32_f16 v[36:39], v[166:169], v[132:135], v[136:139]
	v_mfma_f32_16x16x32_f16 v[64:67], v[178:181], v[170:173], v[36:39]
	v_mfma_f32_16x16x32_f16 v[36:39], v[166:169], v[210:213], v[140:143]
	v_mfma_f32_16x16x32_f16 v[60:63], v[178:181], v[158:161], v[36:39]
	v_mfma_f32_16x16x32_f16 v[36:39], v[182:185], v[132:135], v[162:165]
	v_mfma_f32_16x16x32_f16 v[56:59], v[186:189], v[170:173], v[36:39]
	v_mfma_f32_16x16x32_f16 v[36:39], v[182:185], v[210:213], v[174:177]
	v_mfma_f32_16x16x32_f16 v[52:55], v[186:189], v[158:161], v[36:39]
	v_mfma_f32_16x16x32_f16 v[36:39], v[214:217], v[132:135], v[206:209]
	v_mfma_f32_16x16x32_f16 v[48:51], v[154:157], v[170:173], v[36:39]
	v_mfma_f32_16x16x32_f16 v[36:39], v[214:217], v[210:213], v[190:193]
	v_mfma_f32_16x16x32_f16 v[44:47], v[154:157], v[158:161], v[36:39]
	v_mfma_f32_16x16x32_f16 v[36:39], v[238:241], v[132:135], v[194:197]
	v_mfma_f32_16x16x32_f16 v[40:43], v[150:153], v[170:173], v[36:39]
	v_mfma_f32_16x16x32_f16 v[36:39], v[238:241], v[210:213], v[198:201]
	v_mfma_f32_16x16x32_f16 v[36:39], v[150:153], v[158:161], v[36:39]
	s_setprio 0
	s_movk_i32 s8, 0x100
	v_cmp_gt_u32_e32 vcc, s8, v3
	s_barrier
	s_and_saveexec_b64 s[8:9], vcc
	s_cbranch_execz .LBB0_1018
	s_barrier

; #define LDA8(dst, b, h) _Pragma("unroll") for (int m = 0; m < 4; ++m) _Pragma("unroll") for (int k = 0; k < 2; ++k) \
;     dst[m][k] = *(const bf16x8*)((const char*)SA8(b, h) + lds_byte8(wr * 64 + m * 16 + fr, k * 32 + fq * 8))
; #define LDB8(dst, b, h) _Pragma("unroll") for (int n = 0; n < 2; ++n) _Pragma("unroll") for (int k = 0; k < 2; ++k) \
;     dst[n][k] = *(const bf16x8*)((const char*)SB8(b, h) + lds_byte8(wc * 32 + n * 16 + fr, k * 32 + fq * 8))
; #define WAIT_V8(n) asm volatile("s_waitcnt vmcnt(" #n ")" ::: "memory")
; #define WAIT_L8(n) asm volatile("s_waitcnt lgkmcnt(" #n ")" ::: "memory")
; #define BAR8 __builtin_amdgcn_s_barrier()
; #define SCHED8 __builtin_amdgcn_sched_barrier(0)
;     ...
;   for (int tt = 0; tt < nt - 2; tt += 2) {
;     LDB8(B0, 0, 0); SCHED8; LDA8(At, 0, 0); STAGE8(SA8(1, 1), A, lda, brow + 128, tt + 1);
;     WAIT_L8(8); BAR8; WAIT_L8(0); MMA8(0, 0, At, B0); BAR8; SCHED8;
;     LDB8(B1, 0, 1); STAGE8(SB8(0, 0), Bt, K, bcol, tt + 2);
;     BAR8; WAIT_L8(0); MMA8(0, 1, At, B1); BAR8;
;     LDA8(At, 0, 1); STAGE8(SA8(0, 0), A, lda, brow, tt + 2);
;     BAR8; WAIT_L8(0); MMA8(1, 0, At, B0); BAR8; SCHED8;
;     STAGE8(SB8(0, 1), Bt, K, bcol + 128, tt + 2);
;     WAIT_V8(6); BAR8; MMA8(1, 1, At, B1); BAR8;
.LBB0_1152:
	ds_read_b128 v[174:177], v171
	ds_read_b128 v[178:181], v171 offset:1024
	ds_read_b128 v[182:185], v171 offset:2048
	ds_read_b128 v[186:189], v171 offset:3072
	v_add_u32_e32 v172, 0xc000, v150
	v_lshl_add_u64 v[222:223], v[142:143], 0, s[12:13]
	v_readfirstlane_b32 s31, v172
	v_add_u32_e32 v173, 0xe000, v150
	v_lshl_add_u64 v[226:227], v[222:223], 0, s[36:37]
	s_mov_b32 m0, s31
	v_lshl_add_u64 v[236:237], v[144:145], 0, s[12:13]
	v_readfirstlane_b32 s31, v173
	ds_read_b128 v[190:193], v156
	ds_read_b128 v[194:197], v156 offset:1024
	ds_read_b128 v[198:201], v155
	ds_read_b128 v[202:205], v155 offset:1024
	ds_read_b128 v[206:209], v154
	ds_read_b128 v[210:213], v154 offset:1024
	ds_read_b128 v[214:217], v153
	ds_read_b128 v[218:221], v153 offset:1024
	global_load_lds_dwordx4 v[226:227], off
	v_lshl_add_u64 v[226:227], v[236:237], 0, s[36:37]
	s_mov_b32 m0, s31
	s_nop 0
	global_load_lds_dwordx4 v[226:227], off
	s_waitcnt lgkmcnt(8)
	s_waitcnt vmcnt(10)
	s_barrier
	s_waitcnt lgkmcnt(0)
	s_setprio 1
	s_waitcnt lgkmcnt(0)
	v_mfma_f32_16x16x32_bf16 v[128:131], v[190:193], v[174:177], v[128:131]
	v_mfma_f32_16x16x32_bf16 v[124:127], v[190:193], v[182:185], v[124:127]
	v_mfma_f32_16x16x32_bf16 v[120:123], v[198:201], v[174:177], v[120:123]
	v_mfma_f32_16x16x32_bf16 v[116:119], v[198:201], v[182:185], v[116:119]
	v_mfma_f32_16x16x32_bf16 v[112:115], v[206:209], v[174:177], v[112:115]
	v_mfma_f32_16x16x32_bf16 v[108:111], v[206:209], v[182:185], v[108:111]
	v_mfma_f32_16x16x32_bf16 v[104:107], v[214:217], v[174:177], v[104:107]
	v_mfma_f32_16x16x32_bf16 v[100:103], v[214:217], v[182:185], v[100:103]
	v_mfma_f32_16x16x32_bf16 v[128:131], v[194:197], v[178:181], v[128:131]
	v_mfma_f32_16x16x32_bf16 v[124:127], v[194:197], v[186:189], v[124:127]
	v_mfma_f32_16x16x32_bf16 v[120:123], v[202:205], v[178:181], v[120:123]
	v_mfma_f32_16x16x32_bf16 v[116:119], v[202:205], v[186:189], v[116:119]
	v_mfma_f32_16x16x32_bf16 v[112:115], v[210:213], v[178:181], v[112:115]
	v_mfma_f32_16x16x32_bf16 v[108:111], v[210:213], v[186:189], v[108:111]
	v_mfma_f32_16x16x32_bf16 v[104:107], v[218:221], v[178:181], v[104:107]
	v_mfma_f32_16x16x32_bf16 v[100:103], v[218:221], v[186:189], v[100:103]
	s_setprio 0
	s_barrier
	v_lshl_add_u64 v[246:247], v[138:139], 0, s[12:13]
	v_readfirstlane_b32 s31, v151
	v_lshl_add_u64 v[248:249], v[246:247], 0, s[38:39]
	s_mov_b32 m0, s31
	ds_read_b128 v[226:229], v167
	ds_read_b128 v[230:233], v167 offset:1024
	ds_read_b128 v[238:241], v167 offset:2048
	ds_read_b128 v[242:245], v167 offset:3072
	global_load_lds_dwordx4 v[248:249], off
	v_lshl_add_u64 v[248:249], v[140:141], 0, s[12:13]
	v_readfirstlane_b32 s31, v157
	v_lshl_add_u64 v[250:251], v[248:249], 0, s[38:39]
	s_mov_b32 m0, s31
	s_nop 0
	global_load_lds_dwordx4 v[250:251], off
	s_waitcnt vmcnt(10)
	s_barrier
	s_waitcnt lgkmcnt(0)
	s_setprio 1
	s_waitcnt lgkmcnt(0)
	v_mfma_f32_16x16x32_bf16 v[96:99], v[190:193], v[226:229], v[96:99]
	v_mfma_f32_16x16x32_bf16 v[92:95], v[190:193], v[238:241], v[92:95]
	v_mfma_f32_16x16x32_bf16 v[88:91], v[198:201], v[226:229], v[88:91]
	v_mfma_f32_16x16x32_bf16 v[84:87], v[198:201], v[238:241], v[84:87]
	v_mfma_f32_16x16x32_bf16 v[80:83], v[206:209], v[226:229], v[80:83]
	v_mfma_f32_16x16x32_bf16 v[76:79], v[206:209], v[238:241], v[76:79]
	v_mfma_f32_16x16x32_bf16 v[72:75], v[214:217], v[226:229], v[72:75]
	v_mfma_f32_16x16x32_bf16 v[68:71], v[214:217], v[238:241], v[68:71]
	v_mfma_f32_16x16x32_bf16 v[96:99], v[194:197], v[230:233], v[96:99]
	v_mfma_f32_16x16x32_bf16 v[92:95], v[194:197], v[242:245], v[92:95]
	v_mfma_f32_16x16x32_bf16 v[88:91], v[202:205], v[230:233], v[88:91]
	v_mfma_f32_16x16x32_bf16 v[84:87], v[202:205], v[242:245], v[84:87]
	v_mfma_f32_16x16x32_bf16 v[80:83], v[210:213], v[230:233], v[80:83]
	v_mfma_f32_16x16x32_bf16 v[76:79], v[210:213], v[242:245], v[76:79]
	v_mfma_f32_16x16x32_bf16 v[72:75], v[218:221], v[230:233], v[72:75]
	v_mfma_f32_16x16x32_bf16 v[68:71], v[218:221], v[242:245], v[68:71]
	s_setprio 0
	v_readfirstlane_b32 s31, v150
	v_lshl_add_u64 v[250:251], v[222:223], 0, s[40:41]
	s_mov_b32 m0, s31
	v_readfirstlane_b32 s31, v152
	s_barrier
	ds_read_b128 v[190:193], v156 offset:16384
	ds_read_b128 v[194:197], v156 offset:17408
	ds_read_b128 v[198:201], v155 offset:16384
	ds_read_b128 v[202:205], v155 offset:17408
	ds_read_b128 v[206:209], v154 offset:16384
	ds_read_b128 v[210:213], v154 offset:17408
	ds_read_b128 v[214:217], v153 offset:16384
	ds_read_b128 v[218:221], v153 offset:17408
	global_load_lds_dwordx4 v[250:251], off
	v_lshl_add_u64 v[250:251], v[236:237], 0, s[40:41]
	s_mov_b32 m0, s31
	s_nop 0
	global_load_lds_dwordx4 v[250:251], off
	s_barrier
	s_waitcnt lgkmcnt(0)
	s_setprio 1
	s_waitcnt lgkmcnt(0)
	v_mfma_f32_16x16x32_bf16 v[64:67], v[190:193], v[174:177], v[64:67]
	v_mfma_f32_16x16x32_bf16 v[60:63], v[190:193], v[182:185], v[60:63]
	v_mfma_f32_16x16x32_bf16 v[56:59], v[198:201], v[174:177], v[56:59]
	v_mfma_f32_16x16x32_bf16 v[52:55], v[198:201], v[182:185], v[52:55]
	v_mfma_f32_16x16x32_bf16 v[48:51], v[206:209], v[174:177], v[48:51]
	v_mfma_f32_16x16x32_bf16 v[44:47], v[206:209], v[182:185], v[44:47]
	v_mfma_f32_16x16x32_bf16 v[40:43], v[214:217], v[174:177], v[40:43]
	v_mfma_f32_16x16x32_bf16 v[36:39], v[214:217], v[182:185], v[36:39]
	v_mfma_f32_16x16x32_bf16 v[64:67], v[194:197], v[178:181], v[64:67]
	v_mfma_f32_16x16x32_bf16 v[60:63], v[194:197], v[186:189], v[60:63]
	v_mfma_f32_16x16x32_bf16 v[56:59], v[202:205], v[178:181], v[56:59]
	v_mfma_f32_16x16x32_bf16 v[52:55], v[202:205], v[186:189], v[52:55]
	v_mfma_f32_16x16x32_bf16 v[48:51], v[210:213], v[178:181], v[48:51]
	v_mfma_f32_16x16x32_bf16 v[44:47], v[210:213], v[186:189], v[44:47]
	v_mfma_f32_16x16x32_bf16 v[40:43], v[218:221], v[178:181], v[40:43]
	v_mfma_f32_16x16x32_bf16 v[36:39], v[218:221], v[186:189], v[36:39]
	s_setprio 0
	s_barrier
; #define LDA8(dst, b, h) _Pragma("unroll") for (int m = 0; m < 4; ++m) _Pragma("unroll") for (int k = 0; k < 2; ++k) \
;     dst[m][k] = *(const bf16x8*)((const char*)SA8(b, h) + lds_byte8(wr * 64 + m * 16 + fr, k * 32 + fq * 8))
; #define LDB8(dst, b, h) _Pragma("unroll") for (int n = 0; n < 2; ++n) _Pragma("unroll") for (int k = 0; k < 2; ++k) \
;     dst[n][k] = *(const bf16x8*)((const char*)SB8(b, h) + lds_byte8(wc * 32 + n * 16 + fr, k * 32 + fq * 8))
; #define WAIT_V8(n) asm volatile("s_waitcnt vmcnt(" #n ")" ::: "memory")
; #define WAIT_L8(n) asm volatile("s_waitcnt lgkmcnt(" #n ")" ::: "memory")
; #define BAR8 __builtin_amdgcn_s_barrier()
; #define SCHED8 __builtin_amdgcn_sched_barrier(0)
;     ...
;     WAIT_V8(6); BAR8; MMA8(1, 1, At, B1); BAR8;
;     LDB8(B0, 1, 0); SCHED8; LDA8(At, 1, 0); STAGE8(SA8(0, 1), A, lda, brow + 128, tt + 2);
;     WAIT_L8(8); BAR8; WAIT_L8(0); MMA8(0, 0, At, B0); BAR8; SCHED8;
;     LDB8(B1, 1, 1); STAGE8(SB8(1, 0), Bt, K, bcol, tt + 3);
;     BAR8; WAIT_L8(0); MMA8(0, 1, At, B1); BAR8;
;     LDA8(At, 1, 1); STAGE8(SA8(1, 0), A, lda, brow, tt + 3);
;     BAR8; WAIT_L8(0); MMA8(1, 0, At, B0); BAR8; SCHED8;
	v_readfirstlane_b32 s31, v159
	v_lshl_add_u64 v[174:175], v[246:247], 0, s[42:43]
	s_mov_b32 m0, s31
	v_readfirstlane_b32 s31, v161
	global_load_lds_dwordx4 v[174:175], off
	v_lshl_add_u64 v[174:175], v[248:249], 0, s[42:43]
	s_mov_b32 m0, s31
	s_nop 0
	global_load_lds_dwordx4 v[174:175], off
	s_waitcnt vmcnt(10)
	s_barrier
	s_setprio 1
	v_mfma_f32_16x16x32_bf16 v[32:35], v[190:193], v[226:229], v[32:35]
	v_mfma_f32_16x16x32_bf16 v[28:31], v[190:193], v[238:241], v[28:31]
	v_mfma_f32_16x16x32_bf16 v[24:27], v[198:201], v[226:229], v[24:27]
	v_mfma_f32_16x16x32_bf16 v[20:23], v[198:201], v[238:241], v[20:23]
	v_mfma_f32_16x16x32_bf16 v[16:19], v[206:209], v[226:229], v[16:19]
	v_mfma_f32_16x16x32_bf16 v[12:15], v[206:209], v[238:241], v[12:15]
	v_mfma_f32_16x16x32_bf16 v[8:11], v[214:217], v[226:229], v[8:11]
	v_mfma_f32_16x16x32_bf16 v[4:7], v[214:217], v[238:241], v[4:7]
	v_mfma_f32_16x16x32_bf16 v[32:35], v[194:197], v[230:233], v[32:35]
	v_mfma_f32_16x16x32_bf16 v[28:31], v[194:197], v[242:245], v[28:31]
	v_mfma_f32_16x16x32_bf16 v[24:27], v[202:205], v[230:233], v[24:27]
	v_mfma_f32_16x16x32_bf16 v[20:23], v[202:205], v[242:245], v[20:23]
	v_mfma_f32_16x16x32_bf16 v[16:19], v[210:213], v[230:233], v[16:19]
	v_mfma_f32_16x16x32_bf16 v[12:15], v[210:213], v[242:245], v[12:15]
	v_mfma_f32_16x16x32_bf16 v[8:11], v[218:221], v[230:233], v[8:11]
	v_mfma_f32_16x16x32_bf16 v[4:7], v[218:221], v[242:245], v[4:7]
	s_setprio 0
	s_barrier
	ds_read_b128 v[174:177], v160
	ds_read_b128 v[178:181], v160 offset:1024
	ds_read_b128 v[182:185], v160 offset:2048
	ds_read_b128 v[186:189], v160 offset:3072
	v_readfirstlane_b32 s31, v162
	v_lshl_add_u64 v[226:227], v[222:223], 0, s[44:45]
	s_mov_b32 m0, s31
	v_readfirstlane_b32 s31, v163
	ds_read_b128 v[190:193], v156 offset:32768
	ds_read_b128 v[194:197], v156 offset:33792
	ds_read_b128 v[198:201], v155 offset:32768
	ds_read_b128 v[202:205], v155 offset:33792
	ds_read_b128 v[206:209], v154 offset:32768
	ds_read_b128 v[210:213], v154 offset:33792
	ds_read_b128 v[214:217], v153 offset:32768
	ds_read_b128 v[218:221], v153 offset:33792
	global_load_lds_dwordx4 v[226:227], off
	v_lshl_add_u64 v[226:227], v[236:237], 0, s[44:45]
	s_mov_b32 m0, s31
	s_nop 0
	global_load_lds_dwordx4 v[226:227], off
	s_waitcnt lgkmcnt(8)
	s_waitcnt vmcnt(10)
	s_barrier
	s_waitcnt lgkmcnt(0)
	s_setprio 1
	s_waitcnt lgkmcnt(0)
	v_mfma_f32_16x16x32_bf16 v[128:131], v[190:193], v[174:177], v[128:131]
	v_mfma_f32_16x16x32_bf16 v[124:127], v[190:193], v[182:185], v[124:127]
	v_mfma_f32_16x16x32_bf16 v[120:123], v[198:201], v[174:177], v[120:123]
	v_mfma_f32_16x16x32_bf16 v[116:119], v[198:201], v[182:185], v[116:119]
	v_mfma_f32_16x16x32_bf16 v[112:115], v[206:209], v[174:177], v[112:115]
	v_mfma_f32_16x16x32_bf16 v[108:111], v[206:209], v[182:185], v[108:111]
	v_mfma_f32_16x16x32_bf16 v[104:107], v[214:217], v[174:177], v[104:107]
	v_mfma_f32_16x16x32_bf16 v[100:103], v[214:217], v[182:185], v[100:103]
	v_mfma_f32_16x16x32_bf16 v[128:131], v[194:197], v[178:181], v[128:131]
	v_mfma_f32_16x16x32_bf16 v[124:127], v[194:197], v[186:189], v[124:127]
	v_mfma_f32_16x16x32_bf16 v[120:123], v[202:205], v[178:181], v[120:123]
	v_mfma_f32_16x16x32_bf16 v[116:119], v[202:205], v[186:189], v[116:119]
	v_mfma_f32_16x16x32_bf16 v[112:115], v[210:213], v[178:181], v[112:115]
	v_mfma_f32_16x16x32_bf16 v[108:111], v[210:213], v[186:189], v[108:111]
	v_mfma_f32_16x16x32_bf16 v[104:107], v[218:221], v[178:181], v[104:107]
	v_mfma_f32_16x16x32_bf16 v[100:103], v[218:221], v[186:189], v[100:103]
	s_setprio 0
	s_barrier
	v_readfirstlane_b32 s31, v164
	v_lshl_add_u64 v[250:251], v[246:247], 0, s[46:47]
	s_mov_b32 m0, s31
	v_readfirstlane_b32 s31, v165
	ds_read_b128 v[226:229], v158
	ds_read_b128 v[230:233], v158 offset:1024
	ds_read_b128 v[238:241], v158 offset:2048
	ds_read_b128 v[242:245], v158 offset:3072
	global_load_lds_dwordx4 v[250:251], off
	v_lshl_add_u64 v[250:251], v[248:249], 0, s[46:47]
	s_mov_b32 m0, s31
	s_nop 0
	global_load_lds_dwordx4 v[250:251], off
	s_waitcnt vmcnt(10)
	s_barrier
	s_waitcnt lgkmcnt(0)
	s_setprio 1
	s_waitcnt lgkmcnt(0)
	v_mfma_f32_16x16x32_bf16 v[96:99], v[190:193], v[226:229], v[96:99]
	v_mfma_f32_16x16x32_bf16 v[92:95], v[190:193], v[238:241], v[92:95]
	v_mfma_f32_16x16x32_bf16 v[88:91], v[198:201], v[226:229], v[88:91]
	v_mfma_f32_16x16x32_bf16 v[84:87], v[198:201], v[238:241], v[84:87]
	v_mfma_f32_16x16x32_bf16 v[80:83], v[206:209], v[226:229], v[80:83]
	v_mfma_f32_16x16x32_bf16 v[76:79], v[206:209], v[238:241], v[76:79]
	v_mfma_f32_16x16x32_bf16 v[72:75], v[214:217], v[226:229], v[72:75]
	v_mfma_f32_16x16x32_bf16 v[68:71], v[214:217], v[238:241], v[68:71]
	v_mfma_f32_16x16x32_bf16 v[96:99], v[194:197], v[230:233], v[96:99]
	v_mfma_f32_16x16x32_bf16 v[92:95], v[194:197], v[242:245], v[92:95]
	v_mfma_f32_16x16x32_bf16 v[88:91], v[202:205], v[230:233], v[88:91]
	v_mfma_f32_16x16x32_bf16 v[84:87], v[202:205], v[242:245], v[84:87]
	v_mfma_f32_16x16x32_bf16 v[80:83], v[210:213], v[230:233], v[80:83]
	v_mfma_f32_16x16x32_bf16 v[76:79], v[210:213], v[242:245], v[76:79]
	v_mfma_f32_16x16x32_bf16 v[72:75], v[218:221], v[230:233], v[72:75]
	v_mfma_f32_16x16x32_bf16 v[68:71], v[218:221], v[242:245], v[68:71]
	s_setprio 0
	v_readfirstlane_b32 s31, v166
	v_lshl_add_u64 v[222:223], v[222:223], 0, s[48:49]
	s_mov_b32 m0, s31
	v_readfirstlane_b32 s31, v168
	s_barrier
	ds_read_b128 v[190:193], v156 offset:49152
	ds_read_b128 v[194:197], v156 offset:50176
	ds_read_b128 v[198:201], v155 offset:49152
	ds_read_b128 v[202:205], v155 offset:50176
	ds_read_b128 v[206:209], v154 offset:49152
	ds_read_b128 v[210:213], v154 offset:50176
	ds_read_b128 v[214:217], v153 offset:49152
	ds_read_b128 v[218:221], v153 offset:50176
	global_load_lds_dwordx4 v[222:223], off
	v_lshl_add_u64 v[222:223], v[236:237], 0, s[48:49]
	s_mov_b32 m0, s31
	s_nop 0
	global_load_lds_dwordx4 v[222:223], off
	s_barrier
; #define LDA8(dst, b, h) _Pragma("unroll") for (int m = 0; m < 4; ++m) _Pragma("unroll") for (int k = 0; k < 2; ++k) \
;     dst[m][k] = *(const bf16x8*)((const char*)SA8(b, h) + lds_byte8(wr * 64 + m * 16 + fr, k * 32 + fq * 8))
; #define LDB8(dst, b, h) _Pragma("unroll") for (int n = 0; n < 2; ++n) _Pragma("unroll") for (int k = 0; k < 2; ++k) \
;     dst[n][k] = *(const bf16x8*)((const char*)SB8(b, h) + lds_byte8(wc * 32 + n * 16 + fr, k * 32 + fq * 8))
; #define WAIT_V8(n) asm volatile("s_waitcnt vmcnt(" #n ")" ::: "memory")
; #define WAIT_L8(n) asm volatile("s_waitcnt lgkmcnt(" #n ")" ::: "memory")
; #define BAR8 __builtin_amdgcn_s_barrier()
; #define SCHED8 __builtin_amdgcn_sched_barrier(0)
;     ...
;     BAR8; WAIT_L8(0); MMA8(1, 0, At, B0); BAR8; SCHED8;
;     STAGE8(SB8(1, 1), Bt, K, bcol + 128, tt + 3);
;     WAIT_V8(6); BAR8; MMA8(1, 1, At, B1); BAR8;
;   }
;   { LDB8(B0, 0, 0); LDA8(At, 0, 0); STAGE8(SA8(1, 1), A, lda, brow + 128, nt - 1);
;     BAR8; WAIT_L8(0); MMA8(0, 0, At, B0); BAR8;
;     LDB8(B1, 0, 1); BAR8; WAIT_L8(0); MMA8(0, 1, At, B1); BAR8;
;     LDA8(At, 0, 1); WAIT_V8(4); BAR8; WAIT_L8(0); MMA8(1, 0, At, B0); MMA8(1, 1, At, B1); BAR8; }
	s_waitcnt lgkmcnt(0)
	s_setprio 1
	s_waitcnt lgkmcnt(0)
	v_mfma_f32_16x16x32_bf16 v[64:67], v[190:193], v[174:177], v[64:67]
	v_mfma_f32_16x16x32_bf16 v[60:63], v[190:193], v[182:185], v[60:63]
	v_mfma_f32_16x16x32_bf16 v[56:59], v[198:201], v[174:177], v[56:59]
	v_mfma_f32_16x16x32_bf16 v[52:55], v[198:201], v[182:185], v[52:55]
	v_mfma_f32_16x16x32_bf16 v[48:51], v[206:209], v[174:177], v[48:51]
	v_mfma_f32_16x16x32_bf16 v[44:47], v[206:209], v[182:185], v[44:47]
	v_mfma_f32_16x16x32_bf16 v[40:43], v[214:217], v[174:177], v[40:43]
	v_mfma_f32_16x16x32_bf16 v[36:39], v[214:217], v[182:185], v[36:39]
	v_mfma_f32_16x16x32_bf16 v[64:67], v[194:197], v[178:181], v[64:67]
	v_mfma_f32_16x16x32_bf16 v[60:63], v[194:197], v[186:189], v[60:63]
	v_mfma_f32_16x16x32_bf16 v[56:59], v[202:205], v[178:181], v[56:59]
	v_mfma_f32_16x16x32_bf16 v[52:55], v[202:205], v[186:189], v[52:55]
	v_mfma_f32_16x16x32_bf16 v[48:51], v[210:213], v[178:181], v[48:51]
	v_mfma_f32_16x16x32_bf16 v[44:47], v[210:213], v[186:189], v[44:47]
	v_mfma_f32_16x16x32_bf16 v[40:43], v[218:221], v[178:181], v[40:43]
	v_mfma_f32_16x16x32_bf16 v[36:39], v[218:221], v[186:189], v[36:39]
	s_setprio 0
	s_barrier
	v_readfirstlane_b32 s31, v169
	v_lshl_add_u64 v[174:175], v[246:247], 0, s[50:51]
	s_mov_b32 m0, s31
	v_readfirstlane_b32 s31, v170
	global_load_lds_dwordx4 v[174:175], off
	v_lshl_add_u64 v[174:175], v[248:249], 0, s[50:51]
	s_mov_b32 m0, s31
	s_nop 0
	global_load_lds_dwordx4 v[174:175], off
	s_waitcnt vmcnt(10)
	s_barrier
	s_setprio 1
	v_mfma_f32_16x16x32_bf16 v[32:35], v[190:193], v[226:229], v[32:35]
	v_mfma_f32_16x16x32_bf16 v[28:31], v[190:193], v[238:241], v[28:31]
	v_mfma_f32_16x16x32_bf16 v[24:27], v[198:201], v[226:229], v[24:27]
	v_mfma_f32_16x16x32_bf16 v[20:23], v[198:201], v[238:241], v[20:23]
	v_mfma_f32_16x16x32_bf16 v[16:19], v[206:209], v[226:229], v[16:19]
	v_mfma_f32_16x16x32_bf16 v[12:15], v[206:209], v[238:241], v[12:15]
	v_mfma_f32_16x16x32_bf16 v[8:11], v[214:217], v[226:229], v[8:11]
	v_mfma_f32_16x16x32_bf16 v[4:7], v[214:217], v[238:241], v[4:7]
	v_mfma_f32_16x16x32_bf16 v[32:35], v[194:197], v[230:233], v[32:35]
	v_mfma_f32_16x16x32_bf16 v[28:31], v[194:197], v[242:245], v[28:31]
	v_mfma_f32_16x16x32_bf16 v[24:27], v[202:205], v[230:233], v[24:27]
	v_mfma_f32_16x16x32_bf16 v[20:23], v[202:205], v[242:245], v[20:23]
	v_mfma_f32_16x16x32_bf16 v[16:19], v[210:213], v[230:233], v[16:19]
	v_mfma_f32_16x16x32_bf16 v[12:15], v[210:213], v[242:245], v[12:15]
	v_mfma_f32_16x16x32_bf16 v[8:11], v[218:221], v[230:233], v[8:11]
	v_mfma_f32_16x16x32_bf16 v[4:7], v[218:221], v[242:245], v[4:7]
	s_setprio 0
	s_add_i32 s29, s29, 2
	s_add_u32 s12, s12, 0x100
	s_addc_u32 s13, s13, 0
	s_cmp_lt_u32 s29, 4
	s_barrier
	s_cbranch_scc1 .LBB0_1152
	s_add_u32 s2, s2, s27
	s_addc_u32 s3, s3, 0
	s_add_u32 s2, s2, 0x3000380
	s_addc_u32 s3, s3, 0
	v_lshl_add_u64 v[136:137], v[136:137], 1, s[2:3]
	v_readfirstlane_b32 s12, v172
	v_lshl_add_u64 v[0:1], v[0:1], 1, v[136:137]
	s_mov_b32 m0, s12
	ds_read_b128 v[138:141], v171
	ds_read_b128 v[142:145], v171 offset:1024
	ds_read_b128 v[162:165], v171 offset:2048
	ds_read_b128 v[168:171], v171 offset:3072
	ds_read_b128 v[174:177], v156
	ds_read_b128 v[178:181], v156 offset:1024
	ds_read_b128 v[182:185], v155
	ds_read_b128 v[186:189], v155 offset:1024
	ds_read_b128 v[190:193], v154
	ds_read_b128 v[194:197], v154 offset:1024
	ds_read_b128 v[198:201], v153
	ds_read_b128 v[202:205], v153 offset:1024
	global_load_lds_dwordx4 v[0:1], off
	v_lshl_add_u64 v[0:1], v[134:135], 1, s[2:3]
	v_readfirstlane_b32 s2, v173
	v_lshl_add_u64 v[0:1], v[132:133], 1, v[0:1]
	s_mov_b32 m0, s2
	s_nop 0
	global_load_lds_dwordx4 v[0:1], off
	s_waitcnt vmcnt(10)
	s_barrier
	s_waitcnt lgkmcnt(0)
	s_setprio 1
	s_waitcnt lgkmcnt(0)
	v_mfma_f32_16x16x32_bf16 v[128:131], v[174:177], v[138:141], v[128:131]
	v_mfma_f32_16x16x32_bf16 v[124:127], v[174:177], v[162:165], v[124:127]
	v_mfma_f32_16x16x32_bf16 v[120:123], v[182:185], v[138:141], v[120:123]
	v_mfma_f32_16x16x32_bf16 v[112:115], v[190:193], v[138:141], v[112:115]
	v_mfma_f32_16x16x32_bf16 v[128:131], v[178:181], v[142:145], v[128:131]
	v_mfma_f32_16x16x32_bf16 v[124:127], v[178:181], v[168:171], v[124:127]
	v_mfma_f32_16x16x32_bf16 v[120:123], v[186:189], v[142:145], v[120:123]
	v_mfma_f32_16x16x32_bf16 v[116:119], v[182:185], v[162:165], v[116:119]
	v_mfma_f32_16x16x32_bf16 v[112:115], v[194:197], v[142:145], v[112:115]
	v_mfma_f32_16x16x32_bf16 v[108:111], v[190:193], v[162:165], v[108:111]
	v_mfma_f32_16x16x32_bf16 v[104:107], v[198:201], v[138:141], v[104:107]
	v_mfma_f32_16x16x32_bf16 v[100:103], v[198:201], v[162:165], v[100:103]
	v_mfma_f32_16x16x32_bf16 v[132:135], v[186:189], v[168:171], v[116:119]
	v_mfma_f32_16x16x32_bf16 v[206:209], v[194:197], v[168:171], v[108:111]
	v_mfma_f32_16x16x32_bf16 v[210:213], v[202:205], v[142:145], v[104:107]
	v_mfma_f32_16x16x32_bf16 v[214:217], v[202:205], v[168:171], v[100:103]
	s_setprio 0
	s_barrier
	s_nop 1
	ds_read_b128 v[100:103], v167
	ds_read_b128 v[104:107], v167 offset:1024
	ds_read_b128 v[108:111], v167 offset:2048
	ds_read_b128 v[116:119], v167 offset:3072
	s_waitcnt vmcnt(8)
	s_barrier
; #define LDA8(dst, b, h) _Pragma("unroll") for (int m = 0; m < 4; ++m) _Pragma("unroll") for (int k = 0; k < 2; ++k) \
;     dst[m][k] = *(const bf16x8*)((const char*)SA8(b, h) + lds_byte8(wr * 64 + m * 16 + fr, k * 32 + fq * 8))
; #define LDB8(dst, b, h) _Pragma("unroll") for (int n = 0; n < 2; ++n) _Pragma("unroll") for (int k = 0; k < 2; ++k) \
;     dst[n][k] = *(const bf16x8*)((const char*)SB8(b, h) + lds_byte8(wc * 32 + n * 16 + fr, k * 32 + fq * 8))
; #define WAIT_V8(n) asm volatile("s_waitcnt vmcnt(" #n ")" ::: "memory")
; #define WAIT_L8(n) asm volatile("s_waitcnt lgkmcnt(" #n ")" ::: "memory")
; #define BAR8 __builtin_amdgcn_s_barrier()
;     ...
;     LDB8(B1, 0, 1); BAR8; WAIT_L8(0); MMA8(0, 1, At, B1); BAR8;
;     LDA8(At, 0, 1); WAIT_V8(4); BAR8; WAIT_L8(0); MMA8(1, 0, At, B0); MMA8(1, 1, At, B1); BAR8; }
;   { LDB8(B0, 1, 0); LDA8(At, 1, 0); WAIT_V8(2); BAR8; WAIT_L8(0); MMA8(0, 0, At, B0); BAR8;
	s_waitcnt lgkmcnt(0)
	s_setprio 1
	s_waitcnt lgkmcnt(0)
	v_mfma_f32_16x16x32_bf16 v[80:83], v[190:193], v[100:103], v[80:83]
	v_mfma_f32_16x16x32_bf16 v[76:79], v[190:193], v[108:111], v[76:79]
	v_mfma_f32_16x16x32_bf16 v[72:75], v[198:201], v[100:103], v[72:75]
	v_mfma_f32_16x16x32_bf16 v[68:71], v[198:201], v[108:111], v[68:71]
	v_mfma_f32_16x16x32_bf16 v[96:99], v[174:177], v[100:103], v[96:99]
	v_mfma_f32_16x16x32_bf16 v[92:95], v[174:177], v[108:111], v[92:95]
	v_mfma_f32_16x16x32_bf16 v[88:91], v[182:185], v[100:103], v[88:91]
	v_mfma_f32_16x16x32_bf16 v[84:87], v[182:185], v[108:111], v[84:87]
	v_mfma_f32_16x16x32_bf16 v[80:83], v[194:197], v[104:107], v[80:83]
	v_mfma_f32_16x16x32_bf16 v[76:79], v[194:197], v[116:119], v[76:79]
	v_mfma_f32_16x16x32_bf16 v[72:75], v[202:205], v[104:107], v[72:75]
	v_mfma_f32_16x16x32_bf16 v[68:71], v[202:205], v[116:119], v[68:71]
	v_mfma_f32_16x16x32_bf16 v[218:221], v[178:181], v[104:107], v[96:99]
	v_mfma_f32_16x16x32_bf16 v[172:175], v[178:181], v[116:119], v[92:95]
	v_mfma_f32_16x16x32_bf16 v[176:179], v[186:189], v[104:107], v[88:91]
	v_mfma_f32_16x16x32_bf16 v[180:183], v[186:189], v[116:119], v[84:87]
	s_setprio 0
	s_barrier
	s_nop 0
	ds_read_b128 v[84:87], v156 offset:16384
	ds_read_b128 v[88:91], v156 offset:17408
	ds_read_b128 v[92:95], v155 offset:16384
	ds_read_b128 v[96:99], v155 offset:17408
	ds_read_b128 v[184:187], v154 offset:16384
	ds_read_b128 v[188:191], v154 offset:17408
	ds_read_b128 v[192:195], v153 offset:16384
	ds_read_b128 v[196:199], v153 offset:17408
	s_waitcnt vmcnt(4)
	s_barrier
	s_waitcnt lgkmcnt(0)
	s_setprio 1
	s_waitcnt lgkmcnt(0)
	v_mfma_f32_16x16x32_bf16 v[64:67], v[84:87], v[138:141], v[64:67]
	v_mfma_f32_16x16x32_bf16 v[60:63], v[84:87], v[162:165], v[60:63]
	v_mfma_f32_16x16x32_bf16 v[56:59], v[92:95], v[138:141], v[56:59]
	v_mfma_f32_16x16x32_bf16 v[52:55], v[92:95], v[162:165], v[52:55]
	v_mfma_f32_16x16x32_bf16 v[48:51], v[184:187], v[138:141], v[48:51]
	v_mfma_f32_16x16x32_bf16 v[44:47], v[184:187], v[162:165], v[44:47]
	v_mfma_f32_16x16x32_bf16 v[40:43], v[192:195], v[138:141], v[40:43]
	v_mfma_f32_16x16x32_bf16 v[36:39], v[192:195], v[162:165], v[36:39]
	v_mfma_f32_16x16x32_bf16 v[64:67], v[88:91], v[142:145], v[64:67]
	v_mfma_f32_16x16x32_bf16 v[60:63], v[88:91], v[168:171], v[60:63]
	v_mfma_f32_16x16x32_bf16 v[56:59], v[96:99], v[142:145], v[56:59]
	v_mfma_f32_16x16x32_bf16 v[52:55], v[96:99], v[168:171], v[52:55]
	v_mfma_f32_16x16x32_bf16 v[48:51], v[188:191], v[142:145], v[48:51]
	v_mfma_f32_16x16x32_bf16 v[44:47], v[188:191], v[168:171], v[44:47]
	v_mfma_f32_16x16x32_bf16 v[40:43], v[196:199], v[142:145], v[40:43]
	v_mfma_f32_16x16x32_bf16 v[36:39], v[196:199], v[168:171], v[36:39]
	s_setprio 0
	s_setprio 1
	v_mfma_f32_16x16x32_bf16 v[32:35], v[84:87], v[100:103], v[32:35]
	v_mfma_f32_16x16x32_bf16 v[28:31], v[84:87], v[108:111], v[28:31]
	v_mfma_f32_16x16x32_bf16 v[24:27], v[92:95], v[100:103], v[24:27]
	v_mfma_f32_16x16x32_bf16 v[20:23], v[92:95], v[108:111], v[20:23]
	v_mfma_f32_16x16x32_bf16 v[16:19], v[184:187], v[100:103], v[16:19]
	v_mfma_f32_16x16x32_bf16 v[12:15], v[184:187], v[108:111], v[12:15]
	v_mfma_f32_16x16x32_bf16 v[8:11], v[192:195], v[100:103], v[8:11]
	v_mfma_f32_16x16x32_bf16 v[4:7], v[192:195], v[108:111], v[4:7]
	v_mfma_f32_16x16x32_bf16 v[136:139], v[88:91], v[104:107], v[32:35]
	v_mfma_f32_16x16x32_bf16 v[140:143], v[88:91], v[116:119], v[28:31]
	v_mfma_f32_16x16x32_bf16 v[162:165], v[96:99], v[104:107], v[24:27]
	v_mfma_f32_16x16x32_bf16 v[166:169], v[96:99], v[116:119], v[20:23]
	v_mfma_f32_16x16x32_bf16 v[200:203], v[188:191], v[104:107], v[16:19]
	v_mfma_f32_16x16x32_bf16 v[184:187], v[188:191], v[116:119], v[12:15]
	v_mfma_f32_16x16x32_bf16 v[188:191], v[196:199], v[104:107], v[8:11]
	v_mfma_f32_16x16x32_bf16 v[192:195], v[196:199], v[116:119], v[4:7]
	s_setprio 0
	s_barrier
	ds_read_b128 v[196:199], v160
	ds_read_b128 v[226:229], v160 offset:1024
	ds_read_b128 v[230:233], v160 offset:2048
	ds_read_b128 v[238:241], v160 offset:3072
	ds_read_b128 v[8:11], v156 offset:32768
	ds_read_b128 v[12:15], v156 offset:33792
	ds_read_b128 v[16:19], v155 offset:32768
	ds_read_b128 v[24:27], v155 offset:33792
	ds_read_b128 v[28:31], v154 offset:32768
	ds_read_b128 v[32:35], v154 offset:33792
	ds_read_b128 v[242:245], v153 offset:32768
	ds_read_b128 v[246:249], v153 offset:33792
	s_waitcnt vmcnt(2)
	s_barrier
; #define LDA8(dst, b, h) _Pragma("unroll") for (int m = 0; m < 4; ++m) _Pragma("unroll") for (int k = 0; k < 2; ++k) \
;     dst[m][k] = *(const bf16x8*)((const char*)SA8(b, h) + lds_byte8(wr * 64 + m * 16 + fr, k * 32 + fq * 8))
; #define LDB8(dst, b, h) _Pragma("unroll") for (int n = 0; n < 2; ++n) _Pragma("unroll") for (int k = 0; k < 2; ++k) \
;     dst[n][k] = *(const bf16x8*)((const char*)SB8(b, h) + lds_byte8(wc * 32 + n * 16 + fr, k * 32 + fq * 8))
; #define WAIT_V8(n) asm volatile("s_waitcnt vmcnt(" #n ")" ::: "memory")
; #define WAIT_L8(n) asm volatile("s_waitcnt lgkmcnt(" #n ")" ::: "memory")
; #define BAR8 __builtin_amdgcn_s_barrier()
;     ...
;   { LDB8(B0, 1, 0); LDA8(At, 1, 0); WAIT_V8(2); BAR8; WAIT_L8(0); MMA8(0, 0, At, B0); BAR8;
;     LDB8(B1, 1, 1); WAIT_V8(0); BAR8; WAIT_L8(0); MMA8(0, 1, At, B1); BAR8;
;     LDA8(At, 1, 1); BAR8; WAIT_L8(0); MMA8(1, 0, At, B0); MMA8(1, 1, At, B1); BAR8; }
;   if (wr == 0) BAR8;
;   __syncthreads();
;     ...
;   if (t < 256) {
;     float rs = 1.f;
;     if (e.ss) {
;       const float* sp = e.ss + (size_t)(m0 + t) * e.nss;
;       float s = 0.f;
;       for (int i = 0; i < e.nss; ++i) s += sp[i];
;       rs = rsqrtf(s * e.inv_n + EPS);
;     }
;     ((float*)(smem + SMEM_RSTD))[t] = rs;
	s_waitcnt lgkmcnt(0)
	s_setprio 1
	s_waitcnt lgkmcnt(0)
	v_mfma_f32_16x16x32_bf16 v[4:7], v[8:11], v[196:199], v[128:131]
	v_mfma_f32_16x16x32_bf16 v[104:107], v[12:15], v[226:229], v[4:7]
	v_mfma_f32_16x16x32_bf16 v[4:7], v[8:11], v[230:233], v[124:127]
	v_mfma_f32_16x16x32_bf16 v[116:119], v[12:15], v[238:241], v[4:7]
	v_mfma_f32_16x16x32_bf16 v[4:7], v[16:19], v[196:199], v[120:123]
	v_mfma_f32_16x16x32_bf16 v[100:103], v[24:27], v[226:229], v[4:7]
	v_mfma_f32_16x16x32_bf16 v[4:7], v[16:19], v[230:233], v[132:135]
	v_mfma_f32_16x16x32_bf16 v[108:111], v[24:27], v[238:241], v[4:7]
	v_mfma_f32_16x16x32_bf16 v[4:7], v[28:31], v[196:199], v[112:115]
	v_mfma_f32_16x16x32_bf16 v[92:95], v[32:35], v[226:229], v[4:7]
	v_mfma_f32_16x16x32_bf16 v[4:7], v[28:31], v[230:233], v[206:209]
	v_mfma_f32_16x16x32_bf16 v[96:99], v[32:35], v[238:241], v[4:7]
	v_mfma_f32_16x16x32_bf16 v[4:7], v[242:245], v[196:199], v[210:213]
	v_mfma_f32_16x16x32_bf16 v[84:87], v[246:249], v[226:229], v[4:7]
	v_mfma_f32_16x16x32_bf16 v[4:7], v[242:245], v[230:233], v[214:217]
	v_mfma_f32_16x16x32_bf16 v[88:91], v[246:249], v[238:241], v[4:7]
	s_setprio 0
	s_barrier
	ds_read_b128 v[132:135], v158
	ds_read_b128 v[204:207], v158 offset:1024
	ds_read_b128 v[208:211], v158 offset:2048
	ds_read_b128 v[158:161], v158 offset:3072
	s_waitcnt vmcnt(0)
	s_barrier
	s_waitcnt lgkmcnt(0)
	s_setprio 1
	s_waitcnt lgkmcnt(0)
	v_mfma_f32_16x16x32_bf16 v[4:7], v[8:11], v[132:135], v[218:221]
	v_mfma_f32_16x16x32_bf16 v[8:11], v[8:11], v[208:211], v[172:175]
	v_mfma_f32_16x16x32_bf16 v[4:7], v[12:15], v[204:207], v[4:7]
	v_mfma_f32_16x16x32_bf16 v[20:23], v[12:15], v[158:161], v[8:11]
	v_mfma_f32_16x16x32_bf16 v[8:11], v[16:19], v[132:135], v[176:179]
	v_mfma_f32_16x16x32_bf16 v[12:15], v[16:19], v[208:211], v[180:183]
	v_mfma_f32_16x16x32_bf16 v[8:11], v[24:27], v[204:207], v[8:11]
	v_mfma_f32_16x16x32_bf16 v[24:27], v[24:27], v[158:161], v[12:15]
	v_mfma_f32_16x16x32_bf16 v[12:15], v[28:31], v[132:135], v[80:83]
	v_mfma_f32_16x16x32_bf16 v[16:19], v[28:31], v[208:211], v[76:79]
	v_mfma_f32_16x16x32_bf16 v[12:15], v[32:35], v[204:207], v[12:15]
	v_mfma_f32_16x16x32_bf16 v[28:31], v[32:35], v[158:161], v[16:19]
	v_mfma_f32_16x16x32_bf16 v[16:19], v[242:245], v[132:135], v[72:75]
	v_mfma_f32_16x16x32_bf16 v[32:35], v[242:245], v[208:211], v[68:71]
	v_mfma_f32_16x16x32_bf16 v[16:19], v[246:249], v[204:207], v[16:19]
	v_mfma_f32_16x16x32_bf16 v[32:35], v[246:249], v[158:161], v[32:35]
	s_setprio 0
	s_barrier
	ds_read_b128 v[170:173], v156 offset:49152
	ds_read_b128 v[174:177], v156 offset:50176
	ds_read_b128 v[178:181], v155 offset:49152
	ds_read_b128 v[212:215], v155 offset:50176
	ds_read_b128 v[216:219], v154 offset:49152
	ds_read_b128 v[154:157], v154 offset:50176
	ds_read_b128 v[220:223], v153 offset:49152
	ds_read_b128 v[150:153], v153 offset:50176
	s_barrier
	s_waitcnt lgkmcnt(0)
	s_setprio 1
	s_waitcnt lgkmcnt(0)
	v_mfma_f32_16x16x32_bf16 v[64:67], v[170:173], v[196:199], v[64:67]
	v_mfma_f32_16x16x32_bf16 v[60:63], v[170:173], v[230:233], v[60:63]
	v_mfma_f32_16x16x32_bf16 v[56:59], v[178:181], v[196:199], v[56:59]
	v_mfma_f32_16x16x32_bf16 v[52:55], v[178:181], v[230:233], v[52:55]
	v_mfma_f32_16x16x32_bf16 v[48:51], v[216:219], v[196:199], v[48:51]
	v_mfma_f32_16x16x32_bf16 v[44:47], v[216:219], v[230:233], v[44:47]
	v_mfma_f32_16x16x32_bf16 v[40:43], v[220:223], v[196:199], v[40:43]
	v_mfma_f32_16x16x32_bf16 v[36:39], v[220:223], v[230:233], v[36:39]
	v_mfma_f32_16x16x32_bf16 v[128:131], v[174:177], v[226:229], v[64:67]
	v_mfma_f32_16x16x32_bf16 v[124:127], v[174:177], v[238:241], v[60:63]
	v_mfma_f32_16x16x32_bf16 v[120:123], v[212:215], v[226:229], v[56:59]
	v_mfma_f32_16x16x32_bf16 v[112:115], v[212:215], v[238:241], v[52:55]
	v_mfma_f32_16x16x32_bf16 v[80:83], v[154:157], v[226:229], v[48:51]
	v_mfma_f32_16x16x32_bf16 v[76:79], v[154:157], v[238:241], v[44:47]
	v_mfma_f32_16x16x32_bf16 v[72:75], v[150:153], v[226:229], v[40:43]
	v_mfma_f32_16x16x32_bf16 v[68:71], v[150:153], v[238:241], v[36:39]
	s_setprio 0
	s_setprio 1
	v_mfma_f32_16x16x32_bf16 v[40:43], v[170:173], v[208:211], v[140:143]
	v_mfma_f32_16x16x32_bf16 v[44:47], v[178:181], v[208:211], v[166:169]
	v_mfma_f32_16x16x32_bf16 v[48:51], v[216:219], v[208:211], v[184:187]
	v_mfma_f32_16x16x32_bf16 v[36:39], v[170:173], v[132:135], v[136:139]
	v_mfma_f32_16x16x32_bf16 v[52:55], v[174:177], v[158:161], v[40:43]
	v_mfma_f32_16x16x32_bf16 v[40:43], v[178:181], v[132:135], v[162:165]
	v_mfma_f32_16x16x32_bf16 v[56:59], v[212:215], v[158:161], v[44:47]
	v_mfma_f32_16x16x32_bf16 v[44:47], v[216:219], v[132:135], v[200:203]
	v_mfma_f32_16x16x32_bf16 v[60:63], v[154:157], v[158:161], v[48:51]
	v_mfma_f32_16x16x32_bf16 v[48:51], v[220:223], v[132:135], v[188:191]
	v_mfma_f32_16x16x32_bf16 v[64:67], v[220:223], v[208:211], v[192:195]
	v_mfma_f32_16x16x32_bf16 v[36:39], v[174:177], v[204:207], v[36:39]
	v_mfma_f32_16x16x32_bf16 v[40:43], v[212:215], v[204:207], v[40:43]
	v_mfma_f32_16x16x32_bf16 v[44:47], v[154:157], v[204:207], v[44:47]
	v_mfma_f32_16x16x32_bf16 v[48:51], v[150:153], v[204:207], v[48:51]
	v_mfma_f32_16x16x32_bf16 v[64:67], v[150:153], v[158:161], v[64:67]
	s_setprio 0
	s_movk_i32 s2, 0x100
	v_cmp_gt_u32_e32 vcc, s2, v3
	s_barrier
	s_and_saveexec_b64 s[2:3], vcc
	s_cbranch_execz .LBB0_1155
	s_barrier

; #define LDA8(dst, b, h) _Pragma("unroll") for (int m = 0; m < 4; ++m) _Pragma("unroll") for (int k = 0; k < 2; ++k) \
;     dst[m][k] = *(const bf16x8*)((const char*)SA8(b, h) + lds_byte8(wr * 64 + m * 16 + fr, k * 32 + fq * 8))
; #define LDB8(dst, b, h) _Pragma("unroll") for (int n = 0; n < 2; ++n) _Pragma("unroll") for (int k = 0; k < 2; ++k) \
;     dst[n][k] = *(const bf16x8*)((const char*)SB8(b, h) + lds_byte8(wc * 32 + n * 16 + fr, k * 32 + fq * 8))
; #define WAIT_V8(n) asm volatile("s_waitcnt vmcnt(" #n ")" ::: "memory")
; #define WAIT_L8(n) asm volatile("s_waitcnt lgkmcnt(" #n ")" ::: "memory")
; #define BAR8 __builtin_amdgcn_s_barrier()
; #define SCHED8 __builtin_amdgcn_sched_barrier(0)
;     ...
;   for (int tt = 0; tt < nt - 2; tt += 2) {
;     LDB8(B0, 0, 0); SCHED8; LDA8(At, 0, 0); STAGE8(SA8(1, 1), A, lda, brow + 128, tt + 1);
;     WAIT_L8(8); BAR8; WAIT_L8(0); MMA8(0, 0, At, B0); BAR8; SCHED8;
;     LDB8(B1, 0, 1); STAGE8(SB8(0, 0), Bt, K, bcol, tt + 2);
;     BAR8; WAIT_L8(0); MMA8(0, 1, At, B1); BAR8;
;     LDA8(At, 0, 1); STAGE8(SA8(0, 0), A, lda, brow, tt + 2);
;     BAR8; WAIT_L8(0); MMA8(1, 0, At, B0); BAR8; SCHED8;
;     STAGE8(SB8(0, 1), Bt, K, bcol + 128, tt + 2);
;     WAIT_V8(6); BAR8; MMA8(1, 1, At, B1); BAR8;
.LBB0_1259:
	ds_read_b128 v[174:177], v171
	ds_read_b128 v[178:181], v171 offset:1024
	ds_read_b128 v[182:185], v171 offset:2048
	ds_read_b128 v[186:189], v171 offset:3072
	v_add_u32_e32 v172, 0xc000, v150
	v_lshl_add_u64 v[222:223], v[138:139], 0, s[12:13]
	v_readfirstlane_b32 s14, v172
	v_add_u32_e32 v173, 0xe000, v150
	v_lshl_add_u64 v[226:227], v[222:223], 0, s[34:35]
	s_mov_b32 m0, s14
	v_lshl_add_u64 v[236:237], v[140:141], 0, s[12:13]
	v_readfirstlane_b32 s14, v173
	ds_read_b128 v[190:193], v161
	ds_read_b128 v[194:197], v161 offset:1024
	ds_read_b128 v[198:201], v160
	ds_read_b128 v[202:205], v160 offset:1024
	ds_read_b128 v[206:209], v159
	ds_read_b128 v[210:213], v159 offset:1024
	ds_read_b128 v[214:217], v158
	ds_read_b128 v[218:221], v158 offset:1024
	global_load_lds_dwordx4 v[226:227], off
	v_lshl_add_u64 v[226:227], v[236:237], 0, s[34:35]
	s_mov_b32 m0, s14
	s_nop 0
	global_load_lds_dwordx4 v[226:227], off
	s_waitcnt lgkmcnt(8)
	s_waitcnt vmcnt(10)
	s_barrier
	s_waitcnt lgkmcnt(0)
	s_setprio 1
	s_waitcnt lgkmcnt(0)
	v_mfma_f32_16x16x32_f16 v[128:131], v[190:193], v[174:177], v[128:131]
	v_mfma_f32_16x16x32_f16 v[124:127], v[190:193], v[182:185], v[124:127]
	v_mfma_f32_16x16x32_f16 v[120:123], v[198:201], v[174:177], v[120:123]
	v_mfma_f32_16x16x32_f16 v[116:119], v[198:201], v[182:185], v[116:119]
	v_mfma_f32_16x16x32_f16 v[112:115], v[206:209], v[174:177], v[112:115]
	v_mfma_f32_16x16x32_f16 v[108:111], v[206:209], v[182:185], v[108:111]
	v_mfma_f32_16x16x32_f16 v[104:107], v[214:217], v[174:177], v[104:107]
	v_mfma_f32_16x16x32_f16 v[100:103], v[214:217], v[182:185], v[100:103]
	v_mfma_f32_16x16x32_f16 v[128:131], v[194:197], v[178:181], v[128:131]
	v_mfma_f32_16x16x32_f16 v[124:127], v[194:197], v[186:189], v[124:127]
	v_mfma_f32_16x16x32_f16 v[120:123], v[202:205], v[178:181], v[120:123]
	v_mfma_f32_16x16x32_f16 v[116:119], v[202:205], v[186:189], v[116:119]
	v_mfma_f32_16x16x32_f16 v[112:115], v[210:213], v[178:181], v[112:115]
	v_mfma_f32_16x16x32_f16 v[108:111], v[210:213], v[186:189], v[108:111]
	v_mfma_f32_16x16x32_f16 v[104:107], v[218:221], v[178:181], v[104:107]
	v_mfma_f32_16x16x32_f16 v[100:103], v[218:221], v[186:189], v[100:103]
	s_setprio 0
	s_barrier
	v_lshl_add_u64 v[246:247], v[142:143], 0, s[12:13]
	v_readfirstlane_b32 s14, v151
	v_lshl_add_u64 v[248:249], v[246:247], 0, s[36:37]
	s_mov_b32 m0, s14
	ds_read_b128 v[226:229], v169
	ds_read_b128 v[230:233], v169 offset:1024
	ds_read_b128 v[238:241], v169 offset:2048
	ds_read_b128 v[242:245], v169 offset:3072
	global_load_lds_dwordx4 v[248:249], off
	v_lshl_add_u64 v[248:249], v[144:145], 0, s[12:13]
	v_readfirstlane_b32 s14, v153
	v_lshl_add_u64 v[250:251], v[248:249], 0, s[36:37]
	s_mov_b32 m0, s14
	s_nop 0
	global_load_lds_dwordx4 v[250:251], off
	s_waitcnt vmcnt(10)
	s_barrier
	s_waitcnt lgkmcnt(0)
	s_setprio 1
	s_waitcnt lgkmcnt(0)
	v_mfma_f32_16x16x32_f16 v[96:99], v[190:193], v[226:229], v[96:99]
	v_mfma_f32_16x16x32_f16 v[92:95], v[190:193], v[238:241], v[92:95]
	v_mfma_f32_16x16x32_f16 v[88:91], v[198:201], v[226:229], v[88:91]
	v_mfma_f32_16x16x32_f16 v[84:87], v[198:201], v[238:241], v[84:87]
	v_mfma_f32_16x16x32_f16 v[80:83], v[206:209], v[226:229], v[80:83]
	v_mfma_f32_16x16x32_f16 v[76:79], v[206:209], v[238:241], v[76:79]
	v_mfma_f32_16x16x32_f16 v[72:75], v[214:217], v[226:229], v[72:75]
	v_mfma_f32_16x16x32_f16 v[68:71], v[214:217], v[238:241], v[68:71]
	v_mfma_f32_16x16x32_f16 v[96:99], v[194:197], v[230:233], v[96:99]
	v_mfma_f32_16x16x32_f16 v[92:95], v[194:197], v[242:245], v[92:95]
	v_mfma_f32_16x16x32_f16 v[88:91], v[202:205], v[230:233], v[88:91]
	v_mfma_f32_16x16x32_f16 v[84:87], v[202:205], v[242:245], v[84:87]
	v_mfma_f32_16x16x32_f16 v[80:83], v[210:213], v[230:233], v[80:83]
	v_mfma_f32_16x16x32_f16 v[76:79], v[210:213], v[242:245], v[76:79]
	v_mfma_f32_16x16x32_f16 v[72:75], v[218:221], v[230:233], v[72:75]
	v_mfma_f32_16x16x32_f16 v[68:71], v[218:221], v[242:245], v[68:71]
	s_setprio 0
	v_readfirstlane_b32 s14, v150
	v_lshl_add_u64 v[250:251], v[222:223], 0, s[10:11]
	s_mov_b32 m0, s14
	v_readfirstlane_b32 s14, v152
	s_barrier
	ds_read_b128 v[190:193], v161 offset:16384
	ds_read_b128 v[194:197], v161 offset:17408
	ds_read_b128 v[198:201], v160 offset:16384
	ds_read_b128 v[202:205], v160 offset:17408
	ds_read_b128 v[206:209], v159 offset:16384
	ds_read_b128 v[210:213], v159 offset:17408
	ds_read_b128 v[214:217], v158 offset:16384
	ds_read_b128 v[218:221], v158 offset:17408
	global_load_lds_dwordx4 v[250:251], off
	v_lshl_add_u64 v[250:251], v[236:237], 0, s[10:11]
	s_mov_b32 m0, s14
	s_nop 0
	global_load_lds_dwordx4 v[250:251], off
	s_barrier
	s_waitcnt lgkmcnt(0)
	s_setprio 1
	s_waitcnt lgkmcnt(0)
	v_mfma_f32_16x16x32_f16 v[64:67], v[190:193], v[174:177], v[64:67]
	v_mfma_f32_16x16x32_f16 v[60:63], v[190:193], v[182:185], v[60:63]
	v_mfma_f32_16x16x32_f16 v[56:59], v[198:201], v[174:177], v[56:59]
	v_mfma_f32_16x16x32_f16 v[52:55], v[198:201], v[182:185], v[52:55]
	v_mfma_f32_16x16x32_f16 v[48:51], v[206:209], v[174:177], v[48:51]
	v_mfma_f32_16x16x32_f16 v[44:47], v[206:209], v[182:185], v[44:47]
	v_mfma_f32_16x16x32_f16 v[40:43], v[214:217], v[174:177], v[40:43]
	v_mfma_f32_16x16x32_f16 v[36:39], v[214:217], v[182:185], v[36:39]
	v_mfma_f32_16x16x32_f16 v[64:67], v[194:197], v[178:181], v[64:67]
	v_mfma_f32_16x16x32_f16 v[60:63], v[194:197], v[186:189], v[60:63]
	v_mfma_f32_16x16x32_f16 v[56:59], v[202:205], v[178:181], v[56:59]
	v_mfma_f32_16x16x32_f16 v[52:55], v[202:205], v[186:189], v[52:55]
	v_mfma_f32_16x16x32_f16 v[48:51], v[210:213], v[178:181], v[48:51]
	v_mfma_f32_16x16x32_f16 v[44:47], v[210:213], v[186:189], v[44:47]
	v_mfma_f32_16x16x32_f16 v[40:43], v[218:221], v[178:181], v[40:43]
	v_mfma_f32_16x16x32_f16 v[36:39], v[218:221], v[186:189], v[36:39]
	s_setprio 0
	s_barrier
; #define LDA8(dst, b, h) _Pragma("unroll") for (int m = 0; m < 4; ++m) _Pragma("unroll") for (int k = 0; k < 2; ++k) \
;     dst[m][k] = *(const bf16x8*)((const char*)SA8(b, h) + lds_byte8(wr * 64 + m * 16 + fr, k * 32 + fq * 8))
; #define LDB8(dst, b, h) _Pragma("unroll") for (int n = 0; n < 2; ++n) _Pragma("unroll") for (int k = 0; k < 2; ++k) \
;     dst[n][k] = *(const bf16x8*)((const char*)SB8(b, h) + lds_byte8(wc * 32 + n * 16 + fr, k * 32 + fq * 8))
; #define WAIT_V8(n) asm volatile("s_waitcnt vmcnt(" #n ")" ::: "memory")
; #define WAIT_L8(n) asm volatile("s_waitcnt lgkmcnt(" #n ")" ::: "memory")
; #define BAR8 __builtin_amdgcn_s_barrier()
; #define SCHED8 __builtin_amdgcn_sched_barrier(0)
;     ...
;     WAIT_V8(6); BAR8; MMA8(1, 1, At, B1); BAR8;
;     LDB8(B0, 1, 0); SCHED8; LDA8(At, 1, 0); STAGE8(SA8(0, 1), A, lda, brow + 128, tt + 2);
;     WAIT_L8(8); BAR8; WAIT_L8(0); MMA8(0, 0, At, B0); BAR8; SCHED8;
;     LDB8(B1, 1, 1); STAGE8(SB8(1, 0), Bt, K, bcol, tt + 3);
;     BAR8; WAIT_L8(0); MMA8(0, 1, At, B1); BAR8;
;     LDA8(At, 1, 1); STAGE8(SA8(1, 0), A, lda, brow, tt + 3);
;     BAR8; WAIT_L8(0); MMA8(1, 0, At, B0); BAR8; SCHED8;
	v_readfirstlane_b32 s14, v154
	v_lshl_add_u64 v[174:175], v[246:247], 0, s[40:41]
	s_mov_b32 m0, s14
	v_readfirstlane_b32 s14, v155
	global_load_lds_dwordx4 v[174:175], off
	v_lshl_add_u64 v[174:175], v[248:249], 0, s[40:41]
	s_mov_b32 m0, s14
	s_nop 0
	global_load_lds_dwordx4 v[174:175], off
	s_waitcnt vmcnt(10)
	s_barrier
	s_setprio 1
	v_mfma_f32_16x16x32_f16 v[32:35], v[190:193], v[226:229], v[32:35]
	v_mfma_f32_16x16x32_f16 v[28:31], v[190:193], v[238:241], v[28:31]
	v_mfma_f32_16x16x32_f16 v[24:27], v[198:201], v[226:229], v[24:27]
	v_mfma_f32_16x16x32_f16 v[20:23], v[198:201], v[238:241], v[20:23]
	v_mfma_f32_16x16x32_f16 v[16:19], v[206:209], v[226:229], v[16:19]
	v_mfma_f32_16x16x32_f16 v[12:15], v[206:209], v[238:241], v[12:15]
	v_mfma_f32_16x16x32_f16 v[8:11], v[214:217], v[226:229], v[8:11]
	v_mfma_f32_16x16x32_f16 v[4:7], v[214:217], v[238:241], v[4:7]
	v_mfma_f32_16x16x32_f16 v[32:35], v[194:197], v[230:233], v[32:35]
	v_mfma_f32_16x16x32_f16 v[28:31], v[194:197], v[242:245], v[28:31]
	v_mfma_f32_16x16x32_f16 v[24:27], v[202:205], v[230:233], v[24:27]
	v_mfma_f32_16x16x32_f16 v[20:23], v[202:205], v[242:245], v[20:23]
	v_mfma_f32_16x16x32_f16 v[16:19], v[210:213], v[230:233], v[16:19]
	v_mfma_f32_16x16x32_f16 v[12:15], v[210:213], v[242:245], v[12:15]
	v_mfma_f32_16x16x32_f16 v[8:11], v[218:221], v[230:233], v[8:11]
	v_mfma_f32_16x16x32_f16 v[4:7], v[218:221], v[242:245], v[4:7]
	s_setprio 0
	s_barrier
	ds_read_b128 v[174:177], v163
	ds_read_b128 v[178:181], v163 offset:1024
	ds_read_b128 v[182:185], v163 offset:2048
	ds_read_b128 v[186:189], v163 offset:3072
	v_readfirstlane_b32 s14, v156
	v_lshl_add_u64 v[226:227], v[222:223], 0, s[18:19]
	s_mov_b32 m0, s14
	v_readfirstlane_b32 s14, v157
	ds_read_b128 v[190:193], v161 offset:32768
	ds_read_b128 v[194:197], v161 offset:33792
	ds_read_b128 v[198:201], v160 offset:32768
	ds_read_b128 v[202:205], v160 offset:33792
	ds_read_b128 v[206:209], v159 offset:32768
	ds_read_b128 v[210:213], v159 offset:33792
	ds_read_b128 v[214:217], v158 offset:32768
	ds_read_b128 v[218:221], v158 offset:33792
	global_load_lds_dwordx4 v[226:227], off
	v_lshl_add_u64 v[226:227], v[236:237], 0, s[18:19]
	s_mov_b32 m0, s14
	s_nop 0
	global_load_lds_dwordx4 v[226:227], off
	s_waitcnt lgkmcnt(8)
	s_waitcnt vmcnt(10)
	s_barrier
	s_waitcnt lgkmcnt(0)
	s_setprio 1
	s_waitcnt lgkmcnt(0)
	v_mfma_f32_16x16x32_f16 v[128:131], v[190:193], v[174:177], v[128:131]
	v_mfma_f32_16x16x32_f16 v[124:127], v[190:193], v[182:185], v[124:127]
	v_mfma_f32_16x16x32_f16 v[120:123], v[198:201], v[174:177], v[120:123]
	v_mfma_f32_16x16x32_f16 v[116:119], v[198:201], v[182:185], v[116:119]
	v_mfma_f32_16x16x32_f16 v[112:115], v[206:209], v[174:177], v[112:115]
	v_mfma_f32_16x16x32_f16 v[108:111], v[206:209], v[182:185], v[108:111]
	v_mfma_f32_16x16x32_f16 v[104:107], v[214:217], v[174:177], v[104:107]
	v_mfma_f32_16x16x32_f16 v[100:103], v[214:217], v[182:185], v[100:103]
	v_mfma_f32_16x16x32_f16 v[128:131], v[194:197], v[178:181], v[128:131]
	v_mfma_f32_16x16x32_f16 v[124:127], v[194:197], v[186:189], v[124:127]
	v_mfma_f32_16x16x32_f16 v[120:123], v[202:205], v[178:181], v[120:123]
	v_mfma_f32_16x16x32_f16 v[116:119], v[202:205], v[186:189], v[116:119]
	v_mfma_f32_16x16x32_f16 v[112:115], v[210:213], v[178:181], v[112:115]
	v_mfma_f32_16x16x32_f16 v[108:111], v[210:213], v[186:189], v[108:111]
	v_mfma_f32_16x16x32_f16 v[104:107], v[218:221], v[178:181], v[104:107]
	v_mfma_f32_16x16x32_f16 v[100:103], v[218:221], v[186:189], v[100:103]
	s_setprio 0
	s_barrier
	v_readfirstlane_b32 s14, v164
	v_lshl_add_u64 v[250:251], v[246:247], 0, s[42:43]
	s_mov_b32 m0, s14
	v_readfirstlane_b32 s14, v165
	ds_read_b128 v[226:229], v162
	ds_read_b128 v[230:233], v162 offset:1024
	ds_read_b128 v[238:241], v162 offset:2048
	ds_read_b128 v[242:245], v162 offset:3072
	global_load_lds_dwordx4 v[250:251], off
	v_lshl_add_u64 v[250:251], v[248:249], 0, s[42:43]
	s_mov_b32 m0, s14
	s_nop 0
	global_load_lds_dwordx4 v[250:251], off
	s_waitcnt vmcnt(10)
	s_barrier
	s_waitcnt lgkmcnt(0)
	s_setprio 1
	s_waitcnt lgkmcnt(0)
	v_mfma_f32_16x16x32_f16 v[96:99], v[190:193], v[226:229], v[96:99]
	v_mfma_f32_16x16x32_f16 v[92:95], v[190:193], v[238:241], v[92:95]
	v_mfma_f32_16x16x32_f16 v[88:91], v[198:201], v[226:229], v[88:91]
	v_mfma_f32_16x16x32_f16 v[84:87], v[198:201], v[238:241], v[84:87]
	v_mfma_f32_16x16x32_f16 v[80:83], v[206:209], v[226:229], v[80:83]
	v_mfma_f32_16x16x32_f16 v[76:79], v[206:209], v[238:241], v[76:79]
	v_mfma_f32_16x16x32_f16 v[72:75], v[214:217], v[226:229], v[72:75]
	v_mfma_f32_16x16x32_f16 v[68:71], v[214:217], v[238:241], v[68:71]
	v_mfma_f32_16x16x32_f16 v[96:99], v[194:197], v[230:233], v[96:99]
	v_mfma_f32_16x16x32_f16 v[92:95], v[194:197], v[242:245], v[92:95]
	v_mfma_f32_16x16x32_f16 v[88:91], v[202:205], v[230:233], v[88:91]
	v_mfma_f32_16x16x32_f16 v[84:87], v[202:205], v[242:245], v[84:87]
	v_mfma_f32_16x16x32_f16 v[80:83], v[210:213], v[230:233], v[80:83]
	v_mfma_f32_16x16x32_f16 v[76:79], v[210:213], v[242:245], v[76:79]
	v_mfma_f32_16x16x32_f16 v[72:75], v[218:221], v[230:233], v[72:75]
	v_mfma_f32_16x16x32_f16 v[68:71], v[218:221], v[242:245], v[68:71]
	s_setprio 0
	v_readfirstlane_b32 s14, v166
	v_lshl_add_u64 v[222:223], v[222:223], 0, s[22:23]
	s_mov_b32 m0, s14
	v_readfirstlane_b32 s14, v167
	s_barrier
	ds_read_b128 v[190:193], v161 offset:49152
	ds_read_b128 v[194:197], v161 offset:50176
	ds_read_b128 v[198:201], v160 offset:49152
	ds_read_b128 v[202:205], v160 offset:50176
	ds_read_b128 v[206:209], v159 offset:49152
	ds_read_b128 v[210:213], v159 offset:50176
	ds_read_b128 v[214:217], v158 offset:49152
	ds_read_b128 v[218:221], v158 offset:50176
	global_load_lds_dwordx4 v[222:223], off
	v_lshl_add_u64 v[222:223], v[236:237], 0, s[22:23]
	s_mov_b32 m0, s14
	s_nop 0
	global_load_lds_dwordx4 v[222:223], off
	s_barrier
; #define LDA8(dst, b, h) _Pragma("unroll") for (int m = 0; m < 4; ++m) _Pragma("unroll") for (int k = 0; k < 2; ++k) \
;     dst[m][k] = *(const bf16x8*)((const char*)SA8(b, h) + lds_byte8(wr * 64 + m * 16 + fr, k * 32 + fq * 8))
; #define LDB8(dst, b, h) _Pragma("unroll") for (int n = 0; n < 2; ++n) _Pragma("unroll") for (int k = 0; k < 2; ++k) \
;     dst[n][k] = *(const bf16x8*)((const char*)SB8(b, h) + lds_byte8(wc * 32 + n * 16 + fr, k * 32 + fq * 8))
; #define WAIT_V8(n) asm volatile("s_waitcnt vmcnt(" #n ")" ::: "memory")
; #define WAIT_L8(n) asm volatile("s_waitcnt lgkmcnt(" #n ")" ::: "memory")
; #define BAR8 __builtin_amdgcn_s_barrier()
; #define SCHED8 __builtin_amdgcn_sched_barrier(0)
;     ...
;     BAR8; WAIT_L8(0); MMA8(1, 0, At, B0); BAR8; SCHED8;
;     STAGE8(SB8(1, 1), Bt, K, bcol + 128, tt + 3);
;     WAIT_V8(6); BAR8; MMA8(1, 1, At, B1); BAR8;
;   }
;   { LDB8(B0, 0, 0); LDA8(At, 0, 0); STAGE8(SA8(1, 1), A, lda, brow + 128, nt - 1);
;     BAR8; WAIT_L8(0); MMA8(0, 0, At, B0); BAR8;
;     LDB8(B1, 0, 1); BAR8; WAIT_L8(0); MMA8(0, 1, At, B1); BAR8;
;     LDA8(At, 0, 1); WAIT_V8(4); BAR8; WAIT_L8(0); MMA8(1, 0, At, B0); MMA8(1, 1, At, B1); BAR8; }
	s_waitcnt lgkmcnt(0)
	s_setprio 1
	s_waitcnt lgkmcnt(0)
	v_mfma_f32_16x16x32_f16 v[64:67], v[190:193], v[174:177], v[64:67]
	v_mfma_f32_16x16x32_f16 v[60:63], v[190:193], v[182:185], v[60:63]
	v_mfma_f32_16x16x32_f16 v[56:59], v[198:201], v[174:177], v[56:59]
	v_mfma_f32_16x16x32_f16 v[52:55], v[198:201], v[182:185], v[52:55]
	v_mfma_f32_16x16x32_f16 v[48:51], v[206:209], v[174:177], v[48:51]
	v_mfma_f32_16x16x32_f16 v[44:47], v[206:209], v[182:185], v[44:47]
	v_mfma_f32_16x16x32_f16 v[40:43], v[214:217], v[174:177], v[40:43]
	v_mfma_f32_16x16x32_f16 v[36:39], v[214:217], v[182:185], v[36:39]
	v_mfma_f32_16x16x32_f16 v[64:67], v[194:197], v[178:181], v[64:67]
	v_mfma_f32_16x16x32_f16 v[60:63], v[194:197], v[186:189], v[60:63]
	v_mfma_f32_16x16x32_f16 v[56:59], v[202:205], v[178:181], v[56:59]
	v_mfma_f32_16x16x32_f16 v[52:55], v[202:205], v[186:189], v[52:55]
	v_mfma_f32_16x16x32_f16 v[48:51], v[210:213], v[178:181], v[48:51]
	v_mfma_f32_16x16x32_f16 v[44:47], v[210:213], v[186:189], v[44:47]
	v_mfma_f32_16x16x32_f16 v[40:43], v[218:221], v[178:181], v[40:43]
	v_mfma_f32_16x16x32_f16 v[36:39], v[218:221], v[186:189], v[36:39]
	s_setprio 0
	s_barrier
	v_readfirstlane_b32 s14, v168
	v_lshl_add_u64 v[174:175], v[246:247], 0, s[44:45]
	s_mov_b32 m0, s14
	v_readfirstlane_b32 s14, v170
	global_load_lds_dwordx4 v[174:175], off
	v_lshl_add_u64 v[174:175], v[248:249], 0, s[44:45]
	s_mov_b32 m0, s14
	s_nop 0
	global_load_lds_dwordx4 v[174:175], off
	s_waitcnt vmcnt(10)
	s_barrier
	s_setprio 1
	v_mfma_f32_16x16x32_f16 v[32:35], v[190:193], v[226:229], v[32:35]
	v_mfma_f32_16x16x32_f16 v[28:31], v[190:193], v[238:241], v[28:31]
	v_mfma_f32_16x16x32_f16 v[24:27], v[198:201], v[226:229], v[24:27]
	v_mfma_f32_16x16x32_f16 v[20:23], v[198:201], v[238:241], v[20:23]
	v_mfma_f32_16x16x32_f16 v[16:19], v[206:209], v[226:229], v[16:19]
	v_mfma_f32_16x16x32_f16 v[12:15], v[206:209], v[238:241], v[12:15]
	v_mfma_f32_16x16x32_f16 v[8:11], v[214:217], v[226:229], v[8:11]
	v_mfma_f32_16x16x32_f16 v[4:7], v[214:217], v[238:241], v[4:7]
	v_mfma_f32_16x16x32_f16 v[32:35], v[194:197], v[230:233], v[32:35]
	v_mfma_f32_16x16x32_f16 v[28:31], v[194:197], v[242:245], v[28:31]
	v_mfma_f32_16x16x32_f16 v[24:27], v[202:205], v[230:233], v[24:27]
	v_mfma_f32_16x16x32_f16 v[20:23], v[202:205], v[242:245], v[20:23]
	v_mfma_f32_16x16x32_f16 v[16:19], v[210:213], v[230:233], v[16:19]
	v_mfma_f32_16x16x32_f16 v[12:15], v[210:213], v[242:245], v[12:15]
	v_mfma_f32_16x16x32_f16 v[8:11], v[218:221], v[230:233], v[8:11]
	v_mfma_f32_16x16x32_f16 v[4:7], v[218:221], v[242:245], v[4:7]
	s_setprio 0
	s_add_i32 s1, s1, 2
	s_add_u32 s12, s12, 0x100
	s_addc_u32 s13, s13, 0
	s_cmp_lt_u32 s1, 12
	s_barrier
	s_cbranch_scc1 .LBB0_1259
	s_add_u32 s8, s8, 0x40780
	s_addc_u32 s9, s9, 0
	v_lshl_add_u64 v[132:133], s[8:9], 0, v[132:133]
	v_readfirstlane_b32 s1, v172
	v_lshl_add_u64 v[0:1], v[0:1], 1, v[132:133]
	s_mov_b32 m0, s1
	ds_read_b128 v[138:141], v171
	ds_read_b128 v[142:145], v171 offset:1024
	ds_read_b128 v[150:153], v171 offset:2048
	ds_read_b128 v[154:157], v171 offset:3072
	ds_read_b128 v[164:167], v161
	ds_read_b128 v[174:177], v161 offset:1024
	ds_read_b128 v[178:181], v160
	ds_read_b128 v[182:185], v160 offset:1024
	ds_read_b128 v[186:189], v159
	ds_read_b128 v[190:193], v159 offset:1024
	ds_read_b128 v[194:197], v158
	ds_read_b128 v[198:201], v158 offset:1024
	global_load_lds_dwordx4 v[0:1], off
	v_lshl_add_u64 v[0:1], s[8:9], 0, v[136:137]
	v_readfirstlane_b32 s1, v173
	v_lshl_add_u64 v[0:1], v[134:135], 1, v[0:1]
	s_mov_b32 m0, s1
	s_nop 0
	global_load_lds_dwordx4 v[0:1], off
	s_waitcnt vmcnt(10)
	s_barrier
	s_waitcnt lgkmcnt(0)
	s_setprio 1
	s_waitcnt lgkmcnt(0)
	v_mfma_f32_16x16x32_f16 v[128:131], v[164:167], v[138:141], v[128:131]
	v_mfma_f32_16x16x32_f16 v[124:127], v[164:167], v[150:153], v[124:127]
	v_mfma_f32_16x16x32_f16 v[120:123], v[178:181], v[138:141], v[120:123]
	v_mfma_f32_16x16x32_f16 v[116:119], v[178:181], v[150:153], v[116:119]
	v_mfma_f32_16x16x32_f16 v[104:107], v[194:197], v[138:141], v[104:107]
	v_mfma_f32_16x16x32_f16 v[100:103], v[194:197], v[150:153], v[100:103]
	v_mfma_f32_16x16x32_f16 v[128:131], v[174:177], v[142:145], v[128:131]
	v_mfma_f32_16x16x32_f16 v[124:127], v[174:177], v[154:157], v[124:127]
	v_mfma_f32_16x16x32_f16 v[120:123], v[182:185], v[142:145], v[120:123]
	v_mfma_f32_16x16x32_f16 v[116:119], v[182:185], v[154:157], v[116:119]
	v_mfma_f32_16x16x32_f16 v[112:115], v[186:189], v[138:141], v[112:115]
	v_mfma_f32_16x16x32_f16 v[108:111], v[186:189], v[150:153], v[108:111]
	v_mfma_f32_16x16x32_f16 v[104:107], v[198:201], v[142:145], v[104:107]
	v_mfma_f32_16x16x32_f16 v[100:103], v[198:201], v[154:157], v[100:103]
	v_mfma_f32_16x16x32_f16 v[132:135], v[190:193], v[142:145], v[112:115]
	v_mfma_f32_16x16x32_f16 v[170:173], v[190:193], v[154:157], v[108:111]
	s_setprio 0
	s_barrier
	s_nop 1
	ds_read_b128 v[108:111], v169
	ds_read_b128 v[112:115], v169 offset:1024
	ds_read_b128 v[202:205], v169 offset:2048
	ds_read_b128 v[206:209], v169 offset:3072
	s_waitcnt vmcnt(8)
	s_barrier
; #define LDA8(dst, b, h) _Pragma("unroll") for (int m = 0; m < 4; ++m) _Pragma("unroll") for (int k = 0; k < 2; ++k) \
;     dst[m][k] = *(const bf16x8*)((const char*)SA8(b, h) + lds_byte8(wr * 64 + m * 16 + fr, k * 32 + fq * 8))
; #define LDB8(dst, b, h) _Pragma("unroll") for (int n = 0; n < 2; ++n) _Pragma("unroll") for (int k = 0; k < 2; ++k) \
;     dst[n][k] = *(const bf16x8*)((const char*)SB8(b, h) + lds_byte8(wc * 32 + n * 16 + fr, k * 32 + fq * 8))
; #define WAIT_V8(n) asm volatile("s_waitcnt vmcnt(" #n ")" ::: "memory")
; #define WAIT_L8(n) asm volatile("s_waitcnt lgkmcnt(" #n ")" ::: "memory")
; #define BAR8 __builtin_amdgcn_s_barrier()
;     ...
;     LDB8(B1, 0, 1); BAR8; WAIT_L8(0); MMA8(0, 1, At, B1); BAR8;
;     LDA8(At, 0, 1); WAIT_V8(4); BAR8; WAIT_L8(0); MMA8(1, 0, At, B0); MMA8(1, 1, At, B1); BAR8; }
;   { LDB8(B0, 1, 0); LDA8(At, 1, 0); WAIT_V8(2); BAR8; WAIT_L8(0); MMA8(0, 0, At, B0); BAR8;
	s_waitcnt lgkmcnt(0)
	s_setprio 1
	s_waitcnt lgkmcnt(0)
	v_mfma_f32_16x16x32_f16 v[88:91], v[178:181], v[108:111], v[88:91]
	v_mfma_f32_16x16x32_f16 v[84:87], v[178:181], v[202:205], v[84:87]
	v_mfma_f32_16x16x32_f16 v[72:75], v[194:197], v[108:111], v[72:75]
	v_mfma_f32_16x16x32_f16 v[68:71], v[194:197], v[202:205], v[68:71]
	v_mfma_f32_16x16x32_f16 v[96:99], v[164:167], v[108:111], v[96:99]
	v_mfma_f32_16x16x32_f16 v[92:95], v[164:167], v[202:205], v[92:95]
	v_mfma_f32_16x16x32_f16 v[88:91], v[182:185], v[112:115], v[88:91]
	v_mfma_f32_16x16x32_f16 v[84:87], v[182:185], v[206:209], v[84:87]
	v_mfma_f32_16x16x32_f16 v[80:83], v[186:189], v[108:111], v[80:83]
	v_mfma_f32_16x16x32_f16 v[76:79], v[186:189], v[202:205], v[76:79]
	v_mfma_f32_16x16x32_f16 v[72:75], v[198:201], v[112:115], v[72:75]
	v_mfma_f32_16x16x32_f16 v[68:71], v[198:201], v[206:209], v[68:71]
	v_mfma_f32_16x16x32_f16 v[210:213], v[174:177], v[112:115], v[96:99]
	v_mfma_f32_16x16x32_f16 v[164:167], v[174:177], v[206:209], v[92:95]
	v_mfma_f32_16x16x32_f16 v[174:177], v[190:193], v[112:115], v[80:83]
	v_mfma_f32_16x16x32_f16 v[178:181], v[190:193], v[206:209], v[76:79]
	s_setprio 0
	s_barrier
	s_nop 0
	ds_read_b128 v[76:79], v161 offset:16384
	ds_read_b128 v[80:83], v161 offset:17408
	ds_read_b128 v[92:95], v160 offset:16384
	ds_read_b128 v[96:99], v160 offset:17408
	ds_read_b128 v[182:185], v159 offset:16384
	ds_read_b128 v[186:189], v159 offset:17408
	ds_read_b128 v[190:193], v158 offset:16384
	ds_read_b128 v[194:197], v158 offset:17408
	s_waitcnt vmcnt(4)
	s_barrier
	s_waitcnt lgkmcnt(0)
	s_setprio 1
	s_waitcnt lgkmcnt(0)
	v_mfma_f32_16x16x32_f16 v[64:67], v[76:79], v[138:141], v[64:67]
	v_mfma_f32_16x16x32_f16 v[60:63], v[76:79], v[150:153], v[60:63]
	v_mfma_f32_16x16x32_f16 v[56:59], v[92:95], v[138:141], v[56:59]
	v_mfma_f32_16x16x32_f16 v[52:55], v[92:95], v[150:153], v[52:55]
	v_mfma_f32_16x16x32_f16 v[40:43], v[190:193], v[138:141], v[40:43]
	v_mfma_f32_16x16x32_f16 v[36:39], v[190:193], v[150:153], v[36:39]
	v_mfma_f32_16x16x32_f16 v[64:67], v[80:83], v[142:145], v[64:67]
	v_mfma_f32_16x16x32_f16 v[60:63], v[80:83], v[154:157], v[60:63]
	v_mfma_f32_16x16x32_f16 v[56:59], v[96:99], v[142:145], v[56:59]
	v_mfma_f32_16x16x32_f16 v[52:55], v[96:99], v[154:157], v[52:55]
	v_mfma_f32_16x16x32_f16 v[48:51], v[182:185], v[138:141], v[48:51]
	v_mfma_f32_16x16x32_f16 v[44:47], v[182:185], v[150:153], v[44:47]
	v_mfma_f32_16x16x32_f16 v[40:43], v[194:197], v[142:145], v[40:43]
	v_mfma_f32_16x16x32_f16 v[36:39], v[194:197], v[154:157], v[36:39]
	v_mfma_f32_16x16x32_f16 v[198:201], v[186:189], v[142:145], v[48:51]
	v_mfma_f32_16x16x32_f16 v[214:217], v[186:189], v[154:157], v[44:47]
	s_setprio 0
	s_setprio 1
	v_mfma_f32_16x16x32_f16 v[24:27], v[92:95], v[108:111], v[24:27]
	v_mfma_f32_16x16x32_f16 v[20:23], v[92:95], v[202:205], v[20:23]
	v_mfma_f32_16x16x32_f16 v[8:11], v[190:193], v[108:111], v[8:11]
	v_mfma_f32_16x16x32_f16 v[4:7], v[190:193], v[202:205], v[4:7]
	v_mfma_f32_16x16x32_f16 v[32:35], v[76:79], v[108:111], v[32:35]
	v_mfma_f32_16x16x32_f16 v[28:31], v[76:79], v[202:205], v[28:31]
	v_mfma_f32_16x16x32_f16 v[24:27], v[96:99], v[112:115], v[24:27]
	v_mfma_f32_16x16x32_f16 v[20:23], v[96:99], v[206:209], v[20:23]
	v_mfma_f32_16x16x32_f16 v[16:19], v[182:185], v[108:111], v[16:19]
	v_mfma_f32_16x16x32_f16 v[12:15], v[182:185], v[202:205], v[12:15]
	v_mfma_f32_16x16x32_f16 v[8:11], v[194:197], v[112:115], v[8:11]
	v_mfma_f32_16x16x32_f16 v[4:7], v[194:197], v[206:209], v[4:7]
	v_mfma_f32_16x16x32_f16 v[136:139], v[80:83], v[112:115], v[32:35]
	v_mfma_f32_16x16x32_f16 v[140:143], v[80:83], v[206:209], v[28:31]
	v_mfma_f32_16x16x32_f16 v[150:153], v[186:189], v[112:115], v[16:19]
	v_mfma_f32_16x16x32_f16 v[154:157], v[186:189], v[206:209], v[12:15]
	s_setprio 0
	s_barrier
	s_nop 0
	ds_read_b128 v[12:15], v163
	ds_read_b128 v[16:19], v163 offset:1024
	ds_read_b128 v[182:185], v163 offset:2048
	ds_read_b128 v[186:189], v163 offset:3072
	ds_read_b128 v[28:31], v161 offset:32768
	ds_read_b128 v[32:35], v161 offset:33792
	ds_read_b128 v[44:47], v160 offset:32768
	ds_read_b128 v[48:51], v160 offset:33792
	ds_read_b128 v[190:193], v159 offset:32768
	ds_read_b128 v[194:197], v159 offset:33792
	ds_read_b128 v[202:205], v158 offset:32768
	ds_read_b128 v[206:209], v158 offset:33792
	s_waitcnt vmcnt(2)
	s_barrier
; #define LDA8(dst, b, h) _Pragma("unroll") for (int m = 0; m < 4; ++m) _Pragma("unroll") for (int k = 0; k < 2; ++k) \
;     dst[m][k] = *(const bf16x8*)((const char*)SA8(b, h) + lds_byte8(wr * 64 + m * 16 + fr, k * 32 + fq * 8))
; #define LDB8(dst, b, h) _Pragma("unroll") for (int n = 0; n < 2; ++n) _Pragma("unroll") for (int k = 0; k < 2; ++k) \
;     dst[n][k] = *(const bf16x8*)((const char*)SB8(b, h) + lds_byte8(wc * 32 + n * 16 + fr, k * 32 + fq * 8))
; #define WAIT_V8(n) asm volatile("s_waitcnt vmcnt(" #n ")" ::: "memory")
; #define WAIT_L8(n) asm volatile("s_waitcnt lgkmcnt(" #n ")" ::: "memory")
; #define BAR8 __builtin_amdgcn_s_barrier()
;     ...
;   { LDB8(B0, 1, 0); LDA8(At, 1, 0); WAIT_V8(2); BAR8; WAIT_L8(0); MMA8(0, 0, At, B0); BAR8;
;     LDB8(B1, 1, 1); WAIT_V8(0); BAR8; WAIT_L8(0); MMA8(0, 1, At, B1); BAR8;
;     LDA8(At, 1, 1); BAR8; WAIT_L8(0); MMA8(1, 0, At, B0); MMA8(1, 1, At, B1); BAR8; }
;   if (wr == 0) BAR8;
;   __syncthreads();
;     ...
;   if (t < 256) {
;     float rs = 1.f;
;     if (e.ss) {
	s_waitcnt lgkmcnt(0)
	s_setprio 1
	s_waitcnt lgkmcnt(0)
	v_mfma_f32_16x16x32_f16 v[76:79], v[28:31], v[12:15], v[128:131]
	v_mfma_f32_16x16x32_f16 v[128:131], v[32:35], v[16:19], v[76:79]
	v_mfma_f32_16x16x32_f16 v[76:79], v[28:31], v[182:185], v[124:127]
	v_mfma_f32_16x16x32_f16 v[124:127], v[32:35], v[186:189], v[76:79]
	v_mfma_f32_16x16x32_f16 v[76:79], v[44:47], v[12:15], v[120:123]
	v_mfma_f32_16x16x32_f16 v[112:115], v[48:51], v[16:19], v[76:79]
	v_mfma_f32_16x16x32_f16 v[76:79], v[44:47], v[182:185], v[116:119]
	v_mfma_f32_16x16x32_f16 v[108:111], v[48:51], v[186:189], v[76:79]
	v_mfma_f32_16x16x32_f16 v[76:79], v[190:193], v[12:15], v[132:135]
	v_mfma_f32_16x16x32_f16 v[96:99], v[194:197], v[16:19], v[76:79]
	v_mfma_f32_16x16x32_f16 v[76:79], v[190:193], v[182:185], v[170:173]
	v_mfma_f32_16x16x32_f16 v[92:95], v[194:197], v[186:189], v[76:79]
	v_mfma_f32_16x16x32_f16 v[76:79], v[202:205], v[12:15], v[104:107]
	v_mfma_f32_16x16x32_f16 v[80:83], v[206:209], v[16:19], v[76:79]
	v_mfma_f32_16x16x32_f16 v[76:79], v[202:205], v[182:185], v[100:103]
	v_mfma_f32_16x16x32_f16 v[76:79], v[206:209], v[186:189], v[76:79]
	s_setprio 0
	s_barrier
	ds_read_b128 v[132:135], v162
	ds_read_b128 v[168:171], v162 offset:1024
	ds_read_b128 v[218:221], v162 offset:2048
	ds_read_b128 v[226:229], v162 offset:3072
	s_waitcnt vmcnt(0)
	s_barrier
	s_waitcnt lgkmcnt(0)
	s_setprio 1
	s_waitcnt lgkmcnt(0)
	v_mfma_f32_16x16x32_f16 v[100:103], v[28:31], v[132:135], v[210:213]
	v_mfma_f32_16x16x32_f16 v[28:31], v[28:31], v[218:221], v[164:167]
	v_mfma_f32_16x16x32_f16 v[116:119], v[32:35], v[226:229], v[28:31]
	v_mfma_f32_16x16x32_f16 v[28:31], v[44:47], v[132:135], v[88:91]
	v_mfma_f32_16x16x32_f16 v[104:107], v[48:51], v[168:171], v[28:31]
	v_mfma_f32_16x16x32_f16 v[28:31], v[44:47], v[218:221], v[84:87]
	v_mfma_f32_16x16x32_f16 v[120:123], v[32:35], v[168:171], v[100:103]
	v_mfma_f32_16x16x32_f16 v[100:103], v[48:51], v[226:229], v[28:31]
	v_mfma_f32_16x16x32_f16 v[28:31], v[190:193], v[132:135], v[174:177]
	v_mfma_f32_16x16x32_f16 v[88:91], v[194:197], v[168:171], v[28:31]
	v_mfma_f32_16x16x32_f16 v[28:31], v[190:193], v[218:221], v[178:181]
	v_mfma_f32_16x16x32_f16 v[84:87], v[194:197], v[226:229], v[28:31]
	v_mfma_f32_16x16x32_f16 v[28:31], v[202:205], v[132:135], v[72:75]
	v_mfma_f32_16x16x32_f16 v[72:75], v[206:209], v[168:171], v[28:31]
	v_mfma_f32_16x16x32_f16 v[28:31], v[202:205], v[218:221], v[68:71]
	v_mfma_f32_16x16x32_f16 v[68:71], v[206:209], v[226:229], v[28:31]
	s_setprio 0
	s_barrier
	ds_read_b128 v[162:165], v161 offset:49152
	ds_read_b128 v[172:175], v161 offset:50176
	ds_read_b128 v[176:179], v160 offset:49152
	ds_read_b128 v[190:193], v160 offset:50176
	ds_read_b128 v[194:197], v159 offset:49152
	ds_read_b128 v[202:205], v159 offset:50176
	ds_read_b128 v[206:209], v158 offset:49152
	ds_read_b128 v[158:161], v158 offset:50176
	s_barrier
	s_waitcnt lgkmcnt(0)
	s_setprio 1
	s_waitcnt lgkmcnt(0)
	v_mfma_f32_16x16x32_f16 v[28:31], v[162:165], v[12:15], v[64:67]
	v_mfma_f32_16x16x32_f16 v[64:67], v[172:175], v[16:19], v[28:31]
	v_mfma_f32_16x16x32_f16 v[28:31], v[162:165], v[182:185], v[60:63]
	v_mfma_f32_16x16x32_f16 v[60:63], v[172:175], v[186:189], v[28:31]
	v_mfma_f32_16x16x32_f16 v[28:31], v[176:179], v[12:15], v[56:59]
	v_mfma_f32_16x16x32_f16 v[48:51], v[190:193], v[16:19], v[28:31]
	v_mfma_f32_16x16x32_f16 v[28:31], v[176:179], v[182:185], v[52:55]
	v_mfma_f32_16x16x32_f16 v[44:47], v[190:193], v[186:189], v[28:31]
	v_mfma_f32_16x16x32_f16 v[28:31], v[194:197], v[12:15], v[198:201]
	v_mfma_f32_16x16x32_f16 v[12:15], v[206:209], v[12:15], v[40:43]
	v_mfma_f32_16x16x32_f16 v[32:35], v[202:205], v[16:19], v[28:31]
	v_mfma_f32_16x16x32_f16 v[28:31], v[194:197], v[182:185], v[214:217]
	v_mfma_f32_16x16x32_f16 v[16:19], v[158:161], v[16:19], v[12:15]
	v_mfma_f32_16x16x32_f16 v[12:15], v[206:209], v[182:185], v[36:39]
	v_mfma_f32_16x16x32_f16 v[28:31], v[202:205], v[186:189], v[28:31]
	v_mfma_f32_16x16x32_f16 v[12:15], v[158:161], v[186:189], v[12:15]
	s_setprio 0
	s_setprio 1
	v_mfma_f32_16x16x32_f16 v[36:39], v[162:165], v[132:135], v[136:139]
	v_mfma_f32_16x16x32_f16 v[56:59], v[172:175], v[168:171], v[36:39]
	v_mfma_f32_16x16x32_f16 v[36:39], v[162:165], v[218:221], v[140:143]
	v_mfma_f32_16x16x32_f16 v[20:23], v[176:179], v[218:221], v[20:23]
	v_mfma_f32_16x16x32_f16 v[52:55], v[172:175], v[226:229], v[36:39]
	v_mfma_f32_16x16x32_f16 v[24:27], v[176:179], v[132:135], v[24:27]
	v_mfma_f32_16x16x32_f16 v[36:39], v[190:193], v[226:229], v[20:23]
	v_mfma_f32_16x16x32_f16 v[20:23], v[194:197], v[132:135], v[150:153]
	v_mfma_f32_16x16x32_f16 v[40:43], v[190:193], v[168:171], v[24:27]
	v_mfma_f32_16x16x32_f16 v[24:27], v[202:205], v[168:171], v[20:23]
	v_mfma_f32_16x16x32_f16 v[20:23], v[194:197], v[218:221], v[154:157]
	v_mfma_f32_16x16x32_f16 v[8:11], v[206:209], v[132:135], v[8:11]
	v_mfma_f32_16x16x32_f16 v[4:7], v[206:209], v[218:221], v[4:7]
	v_mfma_f32_16x16x32_f16 v[20:23], v[202:205], v[226:229], v[20:23]
	v_mfma_f32_16x16x32_f16 v[8:11], v[158:161], v[168:171], v[8:11]
	v_mfma_f32_16x16x32_f16 v[4:7], v[158:161], v[226:229], v[4:7]
	s_setprio 0
	s_movk_i32 s1, 0x100
	v_cmp_gt_u32_e32 vcc, s1, v3
	s_barrier
	s_and_saveexec_b64 s[8:9], vcc
	s_cbranch_execz .LBB0_1262
	s_barrier

; #define LDA8(dst, b, h) _Pragma("unroll") for (int m = 0; m < 4; ++m) _Pragma("unroll") for (int k = 0; k < 2; ++k) \
;     dst[m][k] = *(const bf16x8*)((const char*)SA8(b, h) + lds_byte8(wr * 64 + m * 16 + fr, k * 32 + fq * 8))
; #define LDB8(dst, b, h) _Pragma("unroll") for (int n = 0; n < 2; ++n) _Pragma("unroll") for (int k = 0; k < 2; ++k) \
;     dst[n][k] = *(const bf16x8*)((const char*)SB8(b, h) + lds_byte8(wc * 32 + n * 16 + fr, k * 32 + fq * 8))
; #define WAIT_V8(n) asm volatile("s_waitcnt vmcnt(" #n ")" ::: "memory")
; #define WAIT_L8(n) asm volatile("s_waitcnt lgkmcnt(" #n ")" ::: "memory")
; #define BAR8 __builtin_amdgcn_s_barrier()
; #define SCHED8 __builtin_amdgcn_sched_barrier(0)
;     ...
;   for (int tt = 0; tt < nt - 2; tt += 2) {
;     LDB8(B0, 0, 0); SCHED8; LDA8(At, 0, 0); STAGE8(SA8(1, 1), A, lda, brow + 128, tt + 1);
;     WAIT_L8(8); BAR8; WAIT_L8(0); MMA8(0, 0, At, B0); BAR8; SCHED8;
;     LDB8(B1, 0, 1); STAGE8(SB8(0, 0), Bt, K, bcol, tt + 2);
;     BAR8; WAIT_L8(0); MMA8(0, 1, At, B1); BAR8;
;     LDA8(At, 0, 1); STAGE8(SA8(0, 0), A, lda, brow, tt + 2);
;     BAR8; WAIT_L8(0); MMA8(1, 0, At, B0); BAR8; SCHED8;
;     STAGE8(SB8(0, 1), Bt, K, bcol + 128, tt + 2);
;     WAIT_V8(6); BAR8; MMA8(1, 1, At, B1); BAR8;
.LBB0_1325:
	ds_read_b128 v[174:177], v171
	ds_read_b128 v[178:181], v171 offset:1024
	ds_read_b128 v[182:185], v171 offset:2048
	ds_read_b128 v[186:189], v171 offset:3072
	v_add_u32_e32 v172, 0xc000, v150
	v_lshl_add_u64 v[222:223], v[142:143], 0, s[12:13]
	v_readfirstlane_b32 s31, v172
	v_add_u32_e32 v173, 0xe000, v150
	v_lshl_add_u64 v[226:227], v[222:223], 0, s[36:37]
	s_mov_b32 m0, s31
	v_lshl_add_u64 v[236:237], v[144:145], 0, s[12:13]
	v_readfirstlane_b32 s31, v173
	ds_read_b128 v[190:193], v156
	ds_read_b128 v[194:197], v156 offset:1024
	ds_read_b128 v[198:201], v155
	ds_read_b128 v[202:205], v155 offset:1024
	ds_read_b128 v[206:209], v154
	ds_read_b128 v[210:213], v154 offset:1024
	ds_read_b128 v[214:217], v153
	ds_read_b128 v[218:221], v153 offset:1024
	global_load_lds_dwordx4 v[226:227], off
	v_lshl_add_u64 v[226:227], v[236:237], 0, s[36:37]
	s_mov_b32 m0, s31
	s_nop 0
	global_load_lds_dwordx4 v[226:227], off
	s_waitcnt lgkmcnt(8)
	s_waitcnt vmcnt(10)
	s_barrier
	s_waitcnt lgkmcnt(0)
	s_setprio 1
	s_waitcnt lgkmcnt(0)
	v_mfma_f32_16x16x32_bf16 v[128:131], v[190:193], v[174:177], v[128:131]
	v_mfma_f32_16x16x32_bf16 v[124:127], v[190:193], v[182:185], v[124:127]
	v_mfma_f32_16x16x32_bf16 v[120:123], v[198:201], v[174:177], v[120:123]
	v_mfma_f32_16x16x32_bf16 v[116:119], v[198:201], v[182:185], v[116:119]
	v_mfma_f32_16x16x32_bf16 v[112:115], v[206:209], v[174:177], v[112:115]
	v_mfma_f32_16x16x32_bf16 v[108:111], v[206:209], v[182:185], v[108:111]
	v_mfma_f32_16x16x32_bf16 v[104:107], v[214:217], v[174:177], v[104:107]
	v_mfma_f32_16x16x32_bf16 v[100:103], v[214:217], v[182:185], v[100:103]
	v_mfma_f32_16x16x32_bf16 v[128:131], v[194:197], v[178:181], v[128:131]
	v_mfma_f32_16x16x32_bf16 v[124:127], v[194:197], v[186:189], v[124:127]
	v_mfma_f32_16x16x32_bf16 v[120:123], v[202:205], v[178:181], v[120:123]
	v_mfma_f32_16x16x32_bf16 v[116:119], v[202:205], v[186:189], v[116:119]
	v_mfma_f32_16x16x32_bf16 v[112:115], v[210:213], v[178:181], v[112:115]
	v_mfma_f32_16x16x32_bf16 v[108:111], v[210:213], v[186:189], v[108:111]
	v_mfma_f32_16x16x32_bf16 v[104:107], v[218:221], v[178:181], v[104:107]
	v_mfma_f32_16x16x32_bf16 v[100:103], v[218:221], v[186:189], v[100:103]
	s_setprio 0
	s_barrier
	v_lshl_add_u64 v[246:247], v[138:139], 0, s[12:13]
	v_readfirstlane_b32 s31, v151
	v_lshl_add_u64 v[248:249], v[246:247], 0, s[38:39]
	s_mov_b32 m0, s31
	ds_read_b128 v[226:229], v169
	ds_read_b128 v[230:233], v169 offset:1024
	ds_read_b128 v[238:241], v169 offset:2048
	ds_read_b128 v[242:245], v169 offset:3072
	global_load_lds_dwordx4 v[248:249], off
	v_lshl_add_u64 v[248:249], v[140:141], 0, s[12:13]
	v_readfirstlane_b32 s31, v157
	v_lshl_add_u64 v[250:251], v[248:249], 0, s[38:39]
	s_mov_b32 m0, s31
	s_nop 0
	global_load_lds_dwordx4 v[250:251], off
	s_waitcnt vmcnt(10)
	s_barrier
	s_waitcnt lgkmcnt(0)
	s_setprio 1
	s_waitcnt lgkmcnt(0)
	v_mfma_f32_16x16x32_bf16 v[96:99], v[190:193], v[226:229], v[96:99]
	v_mfma_f32_16x16x32_bf16 v[92:95], v[190:193], v[238:241], v[92:95]
	v_mfma_f32_16x16x32_bf16 v[88:91], v[198:201], v[226:229], v[88:91]
	v_mfma_f32_16x16x32_bf16 v[84:87], v[198:201], v[238:241], v[84:87]
	v_mfma_f32_16x16x32_bf16 v[80:83], v[206:209], v[226:229], v[80:83]
	v_mfma_f32_16x16x32_bf16 v[76:79], v[206:209], v[238:241], v[76:79]
	v_mfma_f32_16x16x32_bf16 v[72:75], v[214:217], v[226:229], v[72:75]
	v_mfma_f32_16x16x32_bf16 v[68:71], v[214:217], v[238:241], v[68:71]
	v_mfma_f32_16x16x32_bf16 v[96:99], v[194:197], v[230:233], v[96:99]
	v_mfma_f32_16x16x32_bf16 v[92:95], v[194:197], v[242:245], v[92:95]
	v_mfma_f32_16x16x32_bf16 v[88:91], v[202:205], v[230:233], v[88:91]
	v_mfma_f32_16x16x32_bf16 v[84:87], v[202:205], v[242:245], v[84:87]
	v_mfma_f32_16x16x32_bf16 v[80:83], v[210:213], v[230:233], v[80:83]
	v_mfma_f32_16x16x32_bf16 v[76:79], v[210:213], v[242:245], v[76:79]
	v_mfma_f32_16x16x32_bf16 v[72:75], v[218:221], v[230:233], v[72:75]
	v_mfma_f32_16x16x32_bf16 v[68:71], v[218:221], v[242:245], v[68:71]
	s_setprio 0
	v_readfirstlane_b32 s31, v150
	v_lshl_add_u64 v[250:251], v[222:223], 0, s[40:41]
	s_mov_b32 m0, s31
	v_readfirstlane_b32 s31, v152
	s_barrier
	ds_read_b128 v[190:193], v156 offset:16384
	ds_read_b128 v[194:197], v156 offset:17408
	ds_read_b128 v[198:201], v155 offset:16384
	ds_read_b128 v[202:205], v155 offset:17408
	ds_read_b128 v[206:209], v154 offset:16384
	ds_read_b128 v[210:213], v154 offset:17408
	ds_read_b128 v[214:217], v153 offset:16384
	ds_read_b128 v[218:221], v153 offset:17408
	global_load_lds_dwordx4 v[250:251], off
	v_lshl_add_u64 v[250:251], v[236:237], 0, s[40:41]
	s_mov_b32 m0, s31
	s_nop 0
	global_load_lds_dwordx4 v[250:251], off
	s_barrier
	s_waitcnt lgkmcnt(0)
	s_setprio 1
	s_waitcnt lgkmcnt(0)
	v_mfma_f32_16x16x32_bf16 v[64:67], v[190:193], v[174:177], v[64:67]
	v_mfma_f32_16x16x32_bf16 v[60:63], v[190:193], v[182:185], v[60:63]
	v_mfma_f32_16x16x32_bf16 v[56:59], v[198:201], v[174:177], v[56:59]
	v_mfma_f32_16x16x32_bf16 v[52:55], v[198:201], v[182:185], v[52:55]
	v_mfma_f32_16x16x32_bf16 v[48:51], v[206:209], v[174:177], v[48:51]
	v_mfma_f32_16x16x32_bf16 v[44:47], v[206:209], v[182:185], v[44:47]
	v_mfma_f32_16x16x32_bf16 v[40:43], v[214:217], v[174:177], v[40:43]
	v_mfma_f32_16x16x32_bf16 v[36:39], v[214:217], v[182:185], v[36:39]
	v_mfma_f32_16x16x32_bf16 v[64:67], v[194:197], v[178:181], v[64:67]
	v_mfma_f32_16x16x32_bf16 v[60:63], v[194:197], v[186:189], v[60:63]
	v_mfma_f32_16x16x32_bf16 v[56:59], v[202:205], v[178:181], v[56:59]
	v_mfma_f32_16x16x32_bf16 v[52:55], v[202:205], v[186:189], v[52:55]
	v_mfma_f32_16x16x32_bf16 v[48:51], v[210:213], v[178:181], v[48:51]
	v_mfma_f32_16x16x32_bf16 v[44:47], v[210:213], v[186:189], v[44:47]
	v_mfma_f32_16x16x32_bf16 v[40:43], v[218:221], v[178:181], v[40:43]
	v_mfma_f32_16x16x32_bf16 v[36:39], v[218:221], v[186:189], v[36:39]
	s_setprio 0
	s_barrier
; #define LDA8(dst, b, h) _Pragma("unroll") for (int m = 0; m < 4; ++m) _Pragma("unroll") for (int k = 0; k < 2; ++k) \
;     dst[m][k] = *(const bf16x8*)((const char*)SA8(b, h) + lds_byte8(wr * 64 + m * 16 + fr, k * 32 + fq * 8))
; #define LDB8(dst, b, h) _Pragma("unroll") for (int n = 0; n < 2; ++n) _Pragma("unroll") for (int k = 0; k < 2; ++k) \
;     dst[n][k] = *(const bf16x8*)((const char*)SB8(b, h) + lds_byte8(wc * 32 + n * 16 + fr, k * 32 + fq * 8))
; #define WAIT_V8(n) asm volatile("s_waitcnt vmcnt(" #n ")" ::: "memory")
; #define WAIT_L8(n) asm volatile("s_waitcnt lgkmcnt(" #n ")" ::: "memory")
; #define BAR8 __builtin_amdgcn_s_barrier()
; #define SCHED8 __builtin_amdgcn_sched_barrier(0)
;     ...
;     WAIT_V8(6); BAR8; MMA8(1, 1, At, B1); BAR8;
;     LDB8(B0, 1, 0); SCHED8; LDA8(At, 1, 0); STAGE8(SA8(0, 1), A, lda, brow + 128, tt + 2);
;     WAIT_L8(8); BAR8; WAIT_L8(0); MMA8(0, 0, At, B0); BAR8; SCHED8;
;     LDB8(B1, 1, 1); STAGE8(SB8(1, 0), Bt, K, bcol, tt + 3);
;     BAR8; WAIT_L8(0); MMA8(0, 1, At, B1); BAR8;
;     LDA8(At, 1, 1); STAGE8(SA8(1, 0), A, lda, brow, tt + 3);
;     BAR8; WAIT_L8(0); MMA8(1, 0, At, B0); BAR8; SCHED8;
	v_readfirstlane_b32 s31, v160
	v_lshl_add_u64 v[174:175], v[246:247], 0, s[42:43]
	s_mov_b32 m0, s31
	v_readfirstlane_b32 s31, v161
	global_load_lds_dwordx4 v[174:175], off
	v_lshl_add_u64 v[174:175], v[248:249], 0, s[42:43]
	s_mov_b32 m0, s31
	s_nop 0
	global_load_lds_dwordx4 v[174:175], off
	s_waitcnt vmcnt(10)
	s_barrier
	s_setprio 1
	v_mfma_f32_16x16x32_bf16 v[32:35], v[190:193], v[226:229], v[32:35]
	v_mfma_f32_16x16x32_bf16 v[28:31], v[190:193], v[238:241], v[28:31]
	v_mfma_f32_16x16x32_bf16 v[24:27], v[198:201], v[226:229], v[24:27]
	v_mfma_f32_16x16x32_bf16 v[20:23], v[198:201], v[238:241], v[20:23]
	v_mfma_f32_16x16x32_bf16 v[16:19], v[206:209], v[226:229], v[16:19]
	v_mfma_f32_16x16x32_bf16 v[12:15], v[206:209], v[238:241], v[12:15]
	v_mfma_f32_16x16x32_bf16 v[8:11], v[214:217], v[226:229], v[8:11]
	v_mfma_f32_16x16x32_bf16 v[4:7], v[214:217], v[238:241], v[4:7]
	v_mfma_f32_16x16x32_bf16 v[32:35], v[194:197], v[230:233], v[32:35]
	v_mfma_f32_16x16x32_bf16 v[28:31], v[194:197], v[242:245], v[28:31]
	v_mfma_f32_16x16x32_bf16 v[24:27], v[202:205], v[230:233], v[24:27]
	v_mfma_f32_16x16x32_bf16 v[20:23], v[202:205], v[242:245], v[20:23]
	v_mfma_f32_16x16x32_bf16 v[16:19], v[210:213], v[230:233], v[16:19]
	v_mfma_f32_16x16x32_bf16 v[12:15], v[210:213], v[242:245], v[12:15]
	v_mfma_f32_16x16x32_bf16 v[8:11], v[218:221], v[230:233], v[8:11]
	v_mfma_f32_16x16x32_bf16 v[4:7], v[218:221], v[242:245], v[4:7]
	s_setprio 0
	s_barrier
	ds_read_b128 v[174:177], v159
	ds_read_b128 v[178:181], v159 offset:1024
	ds_read_b128 v[182:185], v159 offset:2048
	ds_read_b128 v[186:189], v159 offset:3072
	v_readfirstlane_b32 s31, v162
	v_lshl_add_u64 v[226:227], v[222:223], 0, s[44:45]
	s_mov_b32 m0, s31
	v_readfirstlane_b32 s31, v163
	ds_read_b128 v[190:193], v156 offset:32768
	ds_read_b128 v[194:197], v156 offset:33792
	ds_read_b128 v[198:201], v155 offset:32768
	ds_read_b128 v[202:205], v155 offset:33792
	ds_read_b128 v[206:209], v154 offset:32768
	ds_read_b128 v[210:213], v154 offset:33792
	ds_read_b128 v[214:217], v153 offset:32768
	ds_read_b128 v[218:221], v153 offset:33792
	global_load_lds_dwordx4 v[226:227], off
	v_lshl_add_u64 v[226:227], v[236:237], 0, s[44:45]
	s_mov_b32 m0, s31
	s_nop 0
	global_load_lds_dwordx4 v[226:227], off
	s_waitcnt lgkmcnt(8)
	s_waitcnt vmcnt(10)
	s_barrier
	s_waitcnt lgkmcnt(0)
	s_setprio 1
	s_waitcnt lgkmcnt(0)
	v_mfma_f32_16x16x32_bf16 v[128:131], v[190:193], v[174:177], v[128:131]
	v_mfma_f32_16x16x32_bf16 v[124:127], v[190:193], v[182:185], v[124:127]
	v_mfma_f32_16x16x32_bf16 v[120:123], v[198:201], v[174:177], v[120:123]
	v_mfma_f32_16x16x32_bf16 v[116:119], v[198:201], v[182:185], v[116:119]
	v_mfma_f32_16x16x32_bf16 v[112:115], v[206:209], v[174:177], v[112:115]
	v_mfma_f32_16x16x32_bf16 v[108:111], v[206:209], v[182:185], v[108:111]
	v_mfma_f32_16x16x32_bf16 v[104:107], v[214:217], v[174:177], v[104:107]
	v_mfma_f32_16x16x32_bf16 v[100:103], v[214:217], v[182:185], v[100:103]
	v_mfma_f32_16x16x32_bf16 v[128:131], v[194:197], v[178:181], v[128:131]
	v_mfma_f32_16x16x32_bf16 v[124:127], v[194:197], v[186:189], v[124:127]
	v_mfma_f32_16x16x32_bf16 v[120:123], v[202:205], v[178:181], v[120:123]
	v_mfma_f32_16x16x32_bf16 v[116:119], v[202:205], v[186:189], v[116:119]
	v_mfma_f32_16x16x32_bf16 v[112:115], v[210:213], v[178:181], v[112:115]
	v_mfma_f32_16x16x32_bf16 v[108:111], v[210:213], v[186:189], v[108:111]
	v_mfma_f32_16x16x32_bf16 v[104:107], v[218:221], v[178:181], v[104:107]
	v_mfma_f32_16x16x32_bf16 v[100:103], v[218:221], v[186:189], v[100:103]
	s_setprio 0
	s_barrier
	v_readfirstlane_b32 s31, v164
	v_lshl_add_u64 v[250:251], v[246:247], 0, s[46:47]
	s_mov_b32 m0, s31
	v_readfirstlane_b32 s31, v165
	ds_read_b128 v[226:229], v158
	ds_read_b128 v[230:233], v158 offset:1024
	ds_read_b128 v[238:241], v158 offset:2048
	ds_read_b128 v[242:245], v158 offset:3072
	global_load_lds_dwordx4 v[250:251], off
	v_lshl_add_u64 v[250:251], v[248:249], 0, s[46:47]
	s_mov_b32 m0, s31
	s_nop 0
	global_load_lds_dwordx4 v[250:251], off
	s_waitcnt vmcnt(10)
	s_barrier
	s_waitcnt lgkmcnt(0)
	s_setprio 1
	s_waitcnt lgkmcnt(0)
	v_mfma_f32_16x16x32_bf16 v[96:99], v[190:193], v[226:229], v[96:99]
	v_mfma_f32_16x16x32_bf16 v[92:95], v[190:193], v[238:241], v[92:95]
	v_mfma_f32_16x16x32_bf16 v[88:91], v[198:201], v[226:229], v[88:91]
	v_mfma_f32_16x16x32_bf16 v[84:87], v[198:201], v[238:241], v[84:87]
	v_mfma_f32_16x16x32_bf16 v[80:83], v[206:209], v[226:229], v[80:83]
	v_mfma_f32_16x16x32_bf16 v[76:79], v[206:209], v[238:241], v[76:79]
	v_mfma_f32_16x16x32_bf16 v[72:75], v[214:217], v[226:229], v[72:75]
	v_mfma_f32_16x16x32_bf16 v[68:71], v[214:217], v[238:241], v[68:71]
	v_mfma_f32_16x16x32_bf16 v[96:99], v[194:197], v[230:233], v[96:99]
	v_mfma_f32_16x16x32_bf16 v[92:95], v[194:197], v[242:245], v[92:95]
	v_mfma_f32_16x16x32_bf16 v[88:91], v[202:205], v[230:233], v[88:91]
	v_mfma_f32_16x16x32_bf16 v[84:87], v[202:205], v[242:245], v[84:87]
	v_mfma_f32_16x16x32_bf16 v[80:83], v[210:213], v[230:233], v[80:83]
	v_mfma_f32_16x16x32_bf16 v[76:79], v[210:213], v[242:245], v[76:79]
	v_mfma_f32_16x16x32_bf16 v[72:75], v[218:221], v[230:233], v[72:75]
	v_mfma_f32_16x16x32_bf16 v[68:71], v[218:221], v[242:245], v[68:71]
	s_setprio 0
	v_readfirstlane_b32 s31, v166
	v_lshl_add_u64 v[222:223], v[222:223], 0, s[48:49]
	s_mov_b32 m0, s31
	v_readfirstlane_b32 s31, v167
	s_barrier
	ds_read_b128 v[190:193], v156 offset:49152
	ds_read_b128 v[194:197], v156 offset:50176
	ds_read_b128 v[198:201], v155 offset:49152
	ds_read_b128 v[202:205], v155 offset:50176
	ds_read_b128 v[206:209], v154 offset:49152
	ds_read_b128 v[210:213], v154 offset:50176
	ds_read_b128 v[214:217], v153 offset:49152
	ds_read_b128 v[218:221], v153 offset:50176
	global_load_lds_dwordx4 v[222:223], off
	v_lshl_add_u64 v[222:223], v[236:237], 0, s[48:49]
	s_mov_b32 m0, s31
	s_nop 0
	global_load_lds_dwordx4 v[222:223], off
	s_barrier
; #define LDA8(dst, b, h) _Pragma("unroll") for (int m = 0; m < 4; ++m) _Pragma("unroll") for (int k = 0; k < 2; ++k) \
;     dst[m][k] = *(const bf16x8*)((const char*)SA8(b, h) + lds_byte8(wr * 64 + m * 16 + fr, k * 32 + fq * 8))
; #define LDB8(dst, b, h) _Pragma("unroll") for (int n = 0; n < 2; ++n) _Pragma("unroll") for (int k = 0; k < 2; ++k) \
;     dst[n][k] = *(const bf16x8*)((const char*)SB8(b, h) + lds_byte8(wc * 32 + n * 16 + fr, k * 32 + fq * 8))
; #define WAIT_V8(n) asm volatile("s_waitcnt vmcnt(" #n ")" ::: "memory")
; #define WAIT_L8(n) asm volatile("s_waitcnt lgkmcnt(" #n ")" ::: "memory")
; #define BAR8 __builtin_amdgcn_s_barrier()
; #define SCHED8 __builtin_amdgcn_sched_barrier(0)
;     ...
;     BAR8; WAIT_L8(0); MMA8(1, 0, At, B0); BAR8; SCHED8;
;     STAGE8(SB8(1, 1), Bt, K, bcol + 128, tt + 3);
;     WAIT_V8(6); BAR8; MMA8(1, 1, At, B1); BAR8;
;   }
;   { LDB8(B0, 0, 0); LDA8(At, 0, 0); STAGE8(SA8(1, 1), A, lda, brow + 128, nt - 1);
;     BAR8; WAIT_L8(0); MMA8(0, 0, At, B0); BAR8;
;     LDB8(B1, 0, 1); BAR8; WAIT_L8(0); MMA8(0, 1, At, B1); BAR8;
;     LDA8(At, 0, 1); WAIT_V8(4); BAR8; WAIT_L8(0); MMA8(1, 0, At, B0); MMA8(1, 1, At, B1); BAR8; }
	s_waitcnt lgkmcnt(0)
	s_setprio 1
	s_waitcnt lgkmcnt(0)
	v_mfma_f32_16x16x32_bf16 v[64:67], v[190:193], v[174:177], v[64:67]
	v_mfma_f32_16x16x32_bf16 v[60:63], v[190:193], v[182:185], v[60:63]
	v_mfma_f32_16x16x32_bf16 v[56:59], v[198:201], v[174:177], v[56:59]
	v_mfma_f32_16x16x32_bf16 v[52:55], v[198:201], v[182:185], v[52:55]
	v_mfma_f32_16x16x32_bf16 v[48:51], v[206:209], v[174:177], v[48:51]
	v_mfma_f32_16x16x32_bf16 v[44:47], v[206:209], v[182:185], v[44:47]
	v_mfma_f32_16x16x32_bf16 v[40:43], v[214:217], v[174:177], v[40:43]
	v_mfma_f32_16x16x32_bf16 v[36:39], v[214:217], v[182:185], v[36:39]
	v_mfma_f32_16x16x32_bf16 v[64:67], v[194:197], v[178:181], v[64:67]
	v_mfma_f32_16x16x32_bf16 v[60:63], v[194:197], v[186:189], v[60:63]
	v_mfma_f32_16x16x32_bf16 v[56:59], v[202:205], v[178:181], v[56:59]
	v_mfma_f32_16x16x32_bf16 v[52:55], v[202:205], v[186:189], v[52:55]
	v_mfma_f32_16x16x32_bf16 v[48:51], v[210:213], v[178:181], v[48:51]
	v_mfma_f32_16x16x32_bf16 v[44:47], v[210:213], v[186:189], v[44:47]
	v_mfma_f32_16x16x32_bf16 v[40:43], v[218:221], v[178:181], v[40:43]
	v_mfma_f32_16x16x32_bf16 v[36:39], v[218:221], v[186:189], v[36:39]
	s_setprio 0
	s_barrier
	v_readfirstlane_b32 s31, v168
	v_lshl_add_u64 v[174:175], v[246:247], 0, s[50:51]
	s_mov_b32 m0, s31
	v_readfirstlane_b32 s31, v170
	global_load_lds_dwordx4 v[174:175], off
	v_lshl_add_u64 v[174:175], v[248:249], 0, s[50:51]
	s_mov_b32 m0, s31
	s_nop 0
	global_load_lds_dwordx4 v[174:175], off
	s_waitcnt vmcnt(10)
	s_barrier
	s_setprio 1
	v_mfma_f32_16x16x32_bf16 v[32:35], v[190:193], v[226:229], v[32:35]
	v_mfma_f32_16x16x32_bf16 v[28:31], v[190:193], v[238:241], v[28:31]
	v_mfma_f32_16x16x32_bf16 v[24:27], v[198:201], v[226:229], v[24:27]
	v_mfma_f32_16x16x32_bf16 v[20:23], v[198:201], v[238:241], v[20:23]
	v_mfma_f32_16x16x32_bf16 v[16:19], v[206:209], v[226:229], v[16:19]
	v_mfma_f32_16x16x32_bf16 v[12:15], v[206:209], v[238:241], v[12:15]
	v_mfma_f32_16x16x32_bf16 v[8:11], v[214:217], v[226:229], v[8:11]
	v_mfma_f32_16x16x32_bf16 v[4:7], v[214:217], v[238:241], v[4:7]
	v_mfma_f32_16x16x32_bf16 v[32:35], v[194:197], v[230:233], v[32:35]
	v_mfma_f32_16x16x32_bf16 v[28:31], v[194:197], v[242:245], v[28:31]
	v_mfma_f32_16x16x32_bf16 v[24:27], v[202:205], v[230:233], v[24:27]
	v_mfma_f32_16x16x32_bf16 v[20:23], v[202:205], v[242:245], v[20:23]
	v_mfma_f32_16x16x32_bf16 v[16:19], v[210:213], v[230:233], v[16:19]
	v_mfma_f32_16x16x32_bf16 v[12:15], v[210:213], v[242:245], v[12:15]
	v_mfma_f32_16x16x32_bf16 v[8:11], v[218:221], v[230:233], v[8:11]
	v_mfma_f32_16x16x32_bf16 v[4:7], v[218:221], v[242:245], v[4:7]
	s_setprio 0
	s_add_i32 s29, s29, 2
	s_add_u32 s12, s12, 0x100
	s_addc_u32 s13, s13, 0
	s_cmp_lt_u32 s29, 40
	s_barrier
	s_cbranch_scc1 .LBB0_1325
	s_add_i32 s27, s27, 0xb0000
	s_add_u32 s2, s2, s27
	s_addc_u32 s3, s3, 0
	s_add_u32 s2, s2, 0x2001580
	s_addc_u32 s3, s3, 0
	v_lshl_add_u64 v[132:133], v[132:133], 1, s[2:3]
	v_readfirstlane_b32 s12, v172
	v_lshl_add_u64 v[0:1], v[0:1], 1, v[132:133]
	s_mov_b32 m0, s12
	ds_read_b128 v[138:141], v171
	ds_read_b128 v[142:145], v171 offset:1024
	ds_read_b128 v[160:163], v171 offset:2048
	ds_read_b128 v[164:167], v171 offset:3072
	ds_read_b128 v[174:177], v156
	ds_read_b128 v[178:181], v156 offset:1024
	ds_read_b128 v[182:185], v155
	ds_read_b128 v[186:189], v155 offset:1024
	ds_read_b128 v[190:193], v154
	ds_read_b128 v[194:197], v154 offset:1024
	ds_read_b128 v[198:201], v153
	ds_read_b128 v[202:205], v153 offset:1024
	global_load_lds_dwordx4 v[0:1], off
	v_lshl_add_u64 v[0:1], v[136:137], 1, s[2:3]
	v_readfirstlane_b32 s2, v173
	v_lshl_add_u64 v[0:1], v[134:135], 1, v[0:1]
	s_mov_b32 m0, s2
	s_nop 0
	global_load_lds_dwordx4 v[0:1], off
	s_waitcnt vmcnt(10)
	s_barrier
	s_waitcnt lgkmcnt(0)
	s_setprio 1
	s_waitcnt lgkmcnt(0)
	v_mfma_f32_16x16x32_bf16 v[128:131], v[174:177], v[138:141], v[128:131]
	v_mfma_f32_16x16x32_bf16 v[124:127], v[174:177], v[160:163], v[124:127]
	v_mfma_f32_16x16x32_bf16 v[120:123], v[182:185], v[138:141], v[120:123]
	v_mfma_f32_16x16x32_bf16 v[112:115], v[190:193], v[138:141], v[112:115]
	v_mfma_f32_16x16x32_bf16 v[128:131], v[178:181], v[142:145], v[128:131]
	v_mfma_f32_16x16x32_bf16 v[124:127], v[178:181], v[164:167], v[124:127]
	v_mfma_f32_16x16x32_bf16 v[120:123], v[186:189], v[142:145], v[120:123]
	v_mfma_f32_16x16x32_bf16 v[116:119], v[182:185], v[160:163], v[116:119]
	v_mfma_f32_16x16x32_bf16 v[112:115], v[194:197], v[142:145], v[112:115]
	v_mfma_f32_16x16x32_bf16 v[108:111], v[190:193], v[160:163], v[108:111]
	v_mfma_f32_16x16x32_bf16 v[104:107], v[198:201], v[138:141], v[104:107]
	v_mfma_f32_16x16x32_bf16 v[100:103], v[198:201], v[160:163], v[100:103]
	v_mfma_f32_16x16x32_bf16 v[132:135], v[186:189], v[164:167], v[116:119]
	v_mfma_f32_16x16x32_bf16 v[170:173], v[194:197], v[164:167], v[108:111]
	v_mfma_f32_16x16x32_bf16 v[206:209], v[202:205], v[142:145], v[104:107]
	v_mfma_f32_16x16x32_bf16 v[210:213], v[202:205], v[164:167], v[100:103]
	s_setprio 0
	s_barrier
	s_nop 1
	ds_read_b128 v[100:103], v169
	ds_read_b128 v[104:107], v169 offset:1024
	ds_read_b128 v[108:111], v169 offset:2048
	ds_read_b128 v[116:119], v169 offset:3072
	s_waitcnt vmcnt(8)
	s_barrier
; #define LDA8(dst, b, h) _Pragma("unroll") for (int m = 0; m < 4; ++m) _Pragma("unroll") for (int k = 0; k < 2; ++k) \
;     dst[m][k] = *(const bf16x8*)((const char*)SA8(b, h) + lds_byte8(wr * 64 + m * 16 + fr, k * 32 + fq * 8))
; #define LDB8(dst, b, h) _Pragma("unroll") for (int n = 0; n < 2; ++n) _Pragma("unroll") for (int k = 0; k < 2; ++k) \
;     dst[n][k] = *(const bf16x8*)((const char*)SB8(b, h) + lds_byte8(wc * 32 + n * 16 + fr, k * 32 + fq * 8))
; #define WAIT_V8(n) asm volatile("s_waitcnt vmcnt(" #n ")" ::: "memory")
; #define WAIT_L8(n) asm volatile("s_waitcnt lgkmcnt(" #n ")" ::: "memory")
; #define BAR8 __builtin_amdgcn_s_barrier()
;     ...
;     LDB8(B1, 0, 1); BAR8; WAIT_L8(0); MMA8(0, 1, At, B1); BAR8;
;     LDA8(At, 0, 1); WAIT_V8(4); BAR8; WAIT_L8(0); MMA8(1, 0, At, B0); MMA8(1, 1, At, B1); BAR8; }
;   { LDB8(B0, 1, 0); LDA8(At, 1, 0); WAIT_V8(2); BAR8; WAIT_L8(0); MMA8(0, 0, At, B0); BAR8;
	s_waitcnt lgkmcnt(0)
	s_setprio 1
	s_waitcnt lgkmcnt(0)
	v_mfma_f32_16x16x32_bf16 v[80:83], v[190:193], v[100:103], v[80:83]
	v_mfma_f32_16x16x32_bf16 v[76:79], v[190:193], v[108:111], v[76:79]
	v_mfma_f32_16x16x32_bf16 v[72:75], v[198:201], v[100:103], v[72:75]
	v_mfma_f32_16x16x32_bf16 v[68:71], v[198:201], v[108:111], v[68:71]
	v_mfma_f32_16x16x32_bf16 v[96:99], v[174:177], v[100:103], v[96:99]
	v_mfma_f32_16x16x32_bf16 v[92:95], v[174:177], v[108:111], v[92:95]
	v_mfma_f32_16x16x32_bf16 v[88:91], v[182:185], v[100:103], v[88:91]
	v_mfma_f32_16x16x32_bf16 v[84:87], v[182:185], v[108:111], v[84:87]
	v_mfma_f32_16x16x32_bf16 v[80:83], v[194:197], v[104:107], v[80:83]
	v_mfma_f32_16x16x32_bf16 v[76:79], v[194:197], v[116:119], v[76:79]
	v_mfma_f32_16x16x32_bf16 v[72:75], v[202:205], v[104:107], v[72:75]
	v_mfma_f32_16x16x32_bf16 v[68:71], v[202:205], v[116:119], v[68:71]
	v_mfma_f32_16x16x32_bf16 v[214:217], v[178:181], v[104:107], v[96:99]
	v_mfma_f32_16x16x32_bf16 v[174:177], v[178:181], v[116:119], v[92:95]
	v_mfma_f32_16x16x32_bf16 v[178:181], v[186:189], v[104:107], v[88:91]
	v_mfma_f32_16x16x32_bf16 v[182:185], v[186:189], v[116:119], v[84:87]
	s_setprio 0
	s_barrier
	s_nop 0
	ds_read_b128 v[84:87], v156 offset:16384
	ds_read_b128 v[88:91], v156 offset:17408
	ds_read_b128 v[92:95], v155 offset:16384
	ds_read_b128 v[96:99], v155 offset:17408
	ds_read_b128 v[186:189], v154 offset:16384
	ds_read_b128 v[190:193], v154 offset:17408
	ds_read_b128 v[194:197], v153 offset:16384
	ds_read_b128 v[198:201], v153 offset:17408
	s_waitcnt vmcnt(4)
	s_barrier
	s_waitcnt lgkmcnt(0)
	s_setprio 1
	s_waitcnt lgkmcnt(0)
	v_mfma_f32_16x16x32_bf16 v[64:67], v[84:87], v[138:141], v[64:67]
	v_mfma_f32_16x16x32_bf16 v[60:63], v[84:87], v[160:163], v[60:63]
	v_mfma_f32_16x16x32_bf16 v[56:59], v[92:95], v[138:141], v[56:59]
	v_mfma_f32_16x16x32_bf16 v[52:55], v[92:95], v[160:163], v[52:55]
	v_mfma_f32_16x16x32_bf16 v[48:51], v[186:189], v[138:141], v[48:51]
	v_mfma_f32_16x16x32_bf16 v[44:47], v[186:189], v[160:163], v[44:47]
	v_mfma_f32_16x16x32_bf16 v[40:43], v[194:197], v[138:141], v[40:43]
	v_mfma_f32_16x16x32_bf16 v[36:39], v[194:197], v[160:163], v[36:39]
	v_mfma_f32_16x16x32_bf16 v[64:67], v[88:91], v[142:145], v[64:67]
	v_mfma_f32_16x16x32_bf16 v[60:63], v[88:91], v[164:167], v[60:63]
	v_mfma_f32_16x16x32_bf16 v[56:59], v[96:99], v[142:145], v[56:59]
	v_mfma_f32_16x16x32_bf16 v[52:55], v[96:99], v[164:167], v[52:55]
	v_mfma_f32_16x16x32_bf16 v[48:51], v[190:193], v[142:145], v[48:51]
	v_mfma_f32_16x16x32_bf16 v[44:47], v[190:193], v[164:167], v[44:47]
	v_mfma_f32_16x16x32_bf16 v[40:43], v[198:201], v[142:145], v[40:43]
	v_mfma_f32_16x16x32_bf16 v[36:39], v[198:201], v[164:167], v[36:39]
	s_setprio 0
	s_setprio 1
	v_mfma_f32_16x16x32_bf16 v[32:35], v[84:87], v[100:103], v[32:35]
	v_mfma_f32_16x16x32_bf16 v[28:31], v[84:87], v[108:111], v[28:31]
	v_mfma_f32_16x16x32_bf16 v[24:27], v[92:95], v[100:103], v[24:27]
	v_mfma_f32_16x16x32_bf16 v[20:23], v[92:95], v[108:111], v[20:23]
	v_mfma_f32_16x16x32_bf16 v[16:19], v[186:189], v[100:103], v[16:19]
	v_mfma_f32_16x16x32_bf16 v[12:15], v[186:189], v[108:111], v[12:15]
	v_mfma_f32_16x16x32_bf16 v[8:11], v[194:197], v[100:103], v[8:11]
	v_mfma_f32_16x16x32_bf16 v[4:7], v[194:197], v[108:111], v[4:7]
	v_mfma_f32_16x16x32_bf16 v[136:139], v[88:91], v[104:107], v[32:35]
	v_mfma_f32_16x16x32_bf16 v[140:143], v[88:91], v[116:119], v[28:31]
	v_mfma_f32_16x16x32_bf16 v[160:163], v[96:99], v[104:107], v[24:27]
	v_mfma_f32_16x16x32_bf16 v[164:167], v[96:99], v[116:119], v[20:23]
	v_mfma_f32_16x16x32_bf16 v[202:205], v[190:193], v[104:107], v[16:19]
	v_mfma_f32_16x16x32_bf16 v[186:189], v[190:193], v[116:119], v[12:15]
	v_mfma_f32_16x16x32_bf16 v[190:193], v[198:201], v[104:107], v[8:11]
	v_mfma_f32_16x16x32_bf16 v[194:197], v[198:201], v[116:119], v[4:7]
	s_setprio 0
	s_barrier
	ds_read_b128 v[198:201], v159
	ds_read_b128 v[218:221], v159 offset:1024
	ds_read_b128 v[226:229], v159 offset:2048
	ds_read_b128 v[230:233], v159 offset:3072
	ds_read_b128 v[8:11], v156 offset:32768
	ds_read_b128 v[12:15], v156 offset:33792
	ds_read_b128 v[16:19], v155 offset:32768
	ds_read_b128 v[24:27], v155 offset:33792
	ds_read_b128 v[28:31], v154 offset:32768
	ds_read_b128 v[32:35], v154 offset:33792
	ds_read_b128 v[238:241], v153 offset:32768
	ds_read_b128 v[242:245], v153 offset:33792
	s_waitcnt vmcnt(2)
	s_barrier
; #define LDA8(dst, b, h) _Pragma("unroll") for (int m = 0; m < 4; ++m) _Pragma("unroll") for (int k = 0; k < 2; ++k) \
;     dst[m][k] = *(const bf16x8*)((const char*)SA8(b, h) + lds_byte8(wr * 64 + m * 16 + fr, k * 32 + fq * 8))
; #define LDB8(dst, b, h) _Pragma("unroll") for (int n = 0; n < 2; ++n) _Pragma("unroll") for (int k = 0; k < 2; ++k) \
;     dst[n][k] = *(const bf16x8*)((const char*)SB8(b, h) + lds_byte8(wc * 32 + n * 16 + fr, k * 32 + fq * 8))
; #define WAIT_V8(n) asm volatile("s_waitcnt vmcnt(" #n ")" ::: "memory")
; #define WAIT_L8(n) asm volatile("s_waitcnt lgkmcnt(" #n ")" ::: "memory")
; #define BAR8 __builtin_amdgcn_s_barrier()
;     ...
;   { LDB8(B0, 1, 0); LDA8(At, 1, 0); WAIT_V8(2); BAR8; WAIT_L8(0); MMA8(0, 0, At, B0); BAR8;
;     LDB8(B1, 1, 1); WAIT_V8(0); BAR8; WAIT_L8(0); MMA8(0, 1, At, B1); BAR8;
;     LDA8(At, 1, 1); BAR8; WAIT_L8(0); MMA8(1, 0, At, B0); MMA8(1, 1, At, B1); BAR8; }
;   if (wr == 0) BAR8;
;   __syncthreads();
;     ...
;   if (t < 256) {
;     float rs = 1.f;
;     if (e.ss) {
;       const float* sp = e.ss + (size_t)(m0 + t) * e.nss;
;       float s = 0.f;
;       for (int i = 0; i < e.nss; ++i) s += sp[i];
;       rs = rsqrtf(s * e.inv_n + EPS);
;     }
;     ((float*)(smem + SMEM_RSTD))[t] = rs;
	s_waitcnt lgkmcnt(0)
	s_setprio 1
	s_waitcnt lgkmcnt(0)
	v_mfma_f32_16x16x32_bf16 v[4:7], v[8:11], v[198:201], v[128:131]
	v_mfma_f32_16x16x32_bf16 v[104:107], v[12:15], v[218:221], v[4:7]
	v_mfma_f32_16x16x32_bf16 v[4:7], v[8:11], v[226:229], v[124:127]
	v_mfma_f32_16x16x32_bf16 v[116:119], v[12:15], v[230:233], v[4:7]
	v_mfma_f32_16x16x32_bf16 v[4:7], v[16:19], v[198:201], v[120:123]
	v_mfma_f32_16x16x32_bf16 v[100:103], v[24:27], v[218:221], v[4:7]
	v_mfma_f32_16x16x32_bf16 v[4:7], v[16:19], v[226:229], v[132:135]
	v_mfma_f32_16x16x32_bf16 v[108:111], v[24:27], v[230:233], v[4:7]
	v_mfma_f32_16x16x32_bf16 v[4:7], v[28:31], v[198:201], v[112:115]
	v_mfma_f32_16x16x32_bf16 v[92:95], v[32:35], v[218:221], v[4:7]
	v_mfma_f32_16x16x32_bf16 v[4:7], v[28:31], v[226:229], v[170:173]
	v_mfma_f32_16x16x32_bf16 v[96:99], v[32:35], v[230:233], v[4:7]
	v_mfma_f32_16x16x32_bf16 v[4:7], v[238:241], v[198:201], v[206:209]
	v_mfma_f32_16x16x32_bf16 v[84:87], v[242:245], v[218:221], v[4:7]
	v_mfma_f32_16x16x32_bf16 v[4:7], v[238:241], v[226:229], v[210:213]
	v_mfma_f32_16x16x32_bf16 v[88:91], v[242:245], v[230:233], v[4:7]
	s_setprio 0
	s_barrier
	ds_read_b128 v[132:135], v158
	ds_read_b128 v[168:171], v158 offset:1024
	ds_read_b128 v[206:209], v158 offset:2048
	ds_read_b128 v[210:213], v158 offset:3072
	s_waitcnt vmcnt(0)
	s_barrier
	s_waitcnt lgkmcnt(0)
	s_setprio 1
	s_waitcnt lgkmcnt(0)
	v_mfma_f32_16x16x32_bf16 v[4:7], v[8:11], v[132:135], v[214:217]
	v_mfma_f32_16x16x32_bf16 v[8:11], v[8:11], v[206:209], v[174:177]
	v_mfma_f32_16x16x32_bf16 v[4:7], v[12:15], v[168:171], v[4:7]
	v_mfma_f32_16x16x32_bf16 v[20:23], v[12:15], v[210:213], v[8:11]
	v_mfma_f32_16x16x32_bf16 v[8:11], v[16:19], v[132:135], v[178:181]
	v_mfma_f32_16x16x32_bf16 v[12:15], v[16:19], v[206:209], v[182:185]
	v_mfma_f32_16x16x32_bf16 v[8:11], v[24:27], v[168:171], v[8:11]
	v_mfma_f32_16x16x32_bf16 v[24:27], v[24:27], v[210:213], v[12:15]
	v_mfma_f32_16x16x32_bf16 v[12:15], v[28:31], v[132:135], v[80:83]
	v_mfma_f32_16x16x32_bf16 v[16:19], v[28:31], v[206:209], v[76:79]
	v_mfma_f32_16x16x32_bf16 v[12:15], v[32:35], v[168:171], v[12:15]
	v_mfma_f32_16x16x32_bf16 v[28:31], v[32:35], v[210:213], v[16:19]
	v_mfma_f32_16x16x32_bf16 v[16:19], v[238:241], v[132:135], v[72:75]
	v_mfma_f32_16x16x32_bf16 v[32:35], v[238:241], v[206:209], v[68:71]
	v_mfma_f32_16x16x32_bf16 v[16:19], v[242:245], v[168:171], v[16:19]
	v_mfma_f32_16x16x32_bf16 v[32:35], v[242:245], v[210:213], v[32:35]
	s_setprio 0
	s_barrier
	ds_read_b128 v[172:175], v156 offset:49152
	ds_read_b128 v[156:159], v156 offset:50176
	ds_read_b128 v[176:179], v155 offset:49152
	ds_read_b128 v[180:183], v155 offset:50176
	ds_read_b128 v[214:217], v154 offset:49152
	ds_read_b128 v[238:241], v154 offset:50176
	ds_read_b128 v[242:245], v153 offset:49152
	ds_read_b128 v[150:153], v153 offset:50176
	s_barrier
	s_waitcnt lgkmcnt(0)
	s_setprio 1
	s_waitcnt lgkmcnt(0)
	v_mfma_f32_16x16x32_bf16 v[64:67], v[172:175], v[198:201], v[64:67]
	v_mfma_f32_16x16x32_bf16 v[60:63], v[172:175], v[226:229], v[60:63]
	v_mfma_f32_16x16x32_bf16 v[56:59], v[176:179], v[198:201], v[56:59]
	v_mfma_f32_16x16x32_bf16 v[52:55], v[176:179], v[226:229], v[52:55]
	v_mfma_f32_16x16x32_bf16 v[48:51], v[214:217], v[198:201], v[48:51]
	v_mfma_f32_16x16x32_bf16 v[44:47], v[214:217], v[226:229], v[44:47]
	v_mfma_f32_16x16x32_bf16 v[40:43], v[242:245], v[198:201], v[40:43]
	v_mfma_f32_16x16x32_bf16 v[36:39], v[242:245], v[226:229], v[36:39]
	v_mfma_f32_16x16x32_bf16 v[128:131], v[156:159], v[218:221], v[64:67]
	v_mfma_f32_16x16x32_bf16 v[124:127], v[156:159], v[230:233], v[60:63]
	v_mfma_f32_16x16x32_bf16 v[120:123], v[180:183], v[218:221], v[56:59]
	v_mfma_f32_16x16x32_bf16 v[112:115], v[180:183], v[230:233], v[52:55]
	v_mfma_f32_16x16x32_bf16 v[80:83], v[238:241], v[218:221], v[48:51]
	v_mfma_f32_16x16x32_bf16 v[76:79], v[238:241], v[230:233], v[44:47]
	v_mfma_f32_16x16x32_bf16 v[72:75], v[150:153], v[218:221], v[40:43]
	v_mfma_f32_16x16x32_bf16 v[68:71], v[150:153], v[230:233], v[36:39]
	s_setprio 0
	s_setprio 1
	v_mfma_f32_16x16x32_bf16 v[40:43], v[172:175], v[206:209], v[140:143]
	v_mfma_f32_16x16x32_bf16 v[44:47], v[176:179], v[206:209], v[164:167]
	v_mfma_f32_16x16x32_bf16 v[48:51], v[214:217], v[206:209], v[186:189]
	v_mfma_f32_16x16x32_bf16 v[36:39], v[172:175], v[132:135], v[136:139]
	v_mfma_f32_16x16x32_bf16 v[52:55], v[156:159], v[210:213], v[40:43]
	v_mfma_f32_16x16x32_bf16 v[40:43], v[176:179], v[132:135], v[160:163]
	v_mfma_f32_16x16x32_bf16 v[56:59], v[180:183], v[210:213], v[44:47]
	v_mfma_f32_16x16x32_bf16 v[44:47], v[214:217], v[132:135], v[202:205]
	v_mfma_f32_16x16x32_bf16 v[60:63], v[238:241], v[210:213], v[48:51]
	v_mfma_f32_16x16x32_bf16 v[48:51], v[242:245], v[132:135], v[190:193]
	v_mfma_f32_16x16x32_bf16 v[64:67], v[242:245], v[206:209], v[194:197]
	v_mfma_f32_16x16x32_bf16 v[36:39], v[156:159], v[168:171], v[36:39]
	v_mfma_f32_16x16x32_bf16 v[40:43], v[180:183], v[168:171], v[40:43]
	v_mfma_f32_16x16x32_bf16 v[44:47], v[238:241], v[168:171], v[44:47]
	v_mfma_f32_16x16x32_bf16 v[48:51], v[150:153], v[168:171], v[48:51]
	v_mfma_f32_16x16x32_bf16 v[64:67], v[150:153], v[210:213], v[64:67]
	s_setprio 0
	s_movk_i32 s2, 0x100
	v_cmp_gt_u32_e32 vcc, s2, v3
	s_barrier
	s_and_saveexec_b64 s[2:3], vcc
	s_cbranch_execz .LBB0_1328
	s_barrier
